# non-temporal hint extended to mixer outputs and the final f32 output stores
# baseline (speedup 1.0000x reference)
.LBB0_925:
	s_or_b64 exec, exec, s[10:11]
	ds_read_b128 v[56:59], v196
	ds_read_b128 v[60:63], v196 offset:16
	ds_read_b128 v[64:67], v205
	v_mov_b32_e32 v68, s5
	v_add_f32_e32 v101, s4, v68
	v_subrev_u32_e32 v72, 48, v92
	s_waitcnt lgkmcnt(2)
	v_add_f32_e32 v68, v56, v57
	v_add_f32_e32 v70, v58, v59
	s_waitcnt lgkmcnt(1)
	v_add_f32_e32 v60, v60, v61
	v_add_f32_e32 v62, v62, v63
	s_waitcnt lgkmcnt(0)
	v_mov_b32_e32 v69, v64
	v_mov_b32_e32 v71, v65
	v_mov_b32_e32 v61, v66
	v_mov_b32_e32 v63, v67
	ds_read_b128 v[56:59], v197
	ds_read_b32 v66, v186
	v_pk_add_f32 v[64:65], v[68:69], v[70:71]
	v_pk_add_f32 v[60:61], v[60:61], v[62:63]
	v_and_b32_e32 v62, 0xffff0000, v98
	v_pk_add_f32 v[60:61], v[64:65], v[60:61]
	v_mul_f32_e32 v62, 0xbfb8aa3b, v62
	v_add_f32_e32 v60, v60, v61
	v_lshlrev_b32_e32 v61, 16, v98
	v_mul_f32_e32 v61, 0xbfb8aa3b, v61
	v_exp_f32_e32 v61, v61
	s_waitcnt lgkmcnt(0)
	v_mul_f32_e32 v66, 0xbfb8aa3b, v66
	v_exp_f32_e32 v63, v62
	v_exp_f32_e32 v66, v66
	v_add_f32_e32 v61, 1.0, v61
	v_lshlrev_b32_e32 v64, 16, v99
	v_rcp_f32_e32 v62, v61
	v_add_f32_e32 v61, 1.0, v63
	v_max_f32_e64 v60, |v60|, v66
	v_and_b32_e32 v65, 0xffff0000, v99
	v_rcp_f32_e32 v63, v61
	v_mul_f32_e32 v61, 0xbfb8aa3b, v64
	v_rcp_f32_e32 v60, v60
	v_exp_f32_e32 v61, v61
	v_mul_f32_e32 v64, 0xbfb8aa3b, v65
	v_exp_f32_e32 v65, v64
	ds_read_b32 v67, v188
	ds_read_b32 v68, v190
	ds_read_b32 v69, v192
	v_pk_mul_f32 v[52:53], v[52:53], v[60:61] op_sel_hi:[1,0]
	v_add_f32_e32 v61, 1.0, v61
	v_rcp_f32_e32 v64, v61
	v_add_f32_e32 v61, 1.0, v65
	v_rcp_f32_e32 v65, v61
	v_pk_mul_f32 v[52:53], v[62:63], v[52:53]
	v_add_f32_e32 v56, v56, v57
	v_cvt_pk_bf16_f32 v62, v52, v53
	v_pk_mul_f32 v[52:53], v[54:55], v[60:61] op_sel_hi:[1,0]
	v_add_f32_e32 v58, v58, v59
	v_pk_mul_f32 v[52:53], v[64:65], v[52:53]
	v_mov_b32_e32 v93, v73
	v_cvt_pk_bf16_f32 v63, v52, v53
	v_lshlrev_b64 v[52:53], 7, v[72:73]
	v_lshl_add_u64 v[60:61], v[76:77], 0, v[52:53]
	ds_read_b128 v[52:55], v197 offset:16
	global_store_dwordx2 v[60:61], v[62:63], off nt
	ds_read_b128 v[60:63], v206
	v_subrev_u32_e32 v72, 32, v92
	s_add_i32 s3, s3, 2
	s_waitcnt lgkmcnt(1)
	v_add_f32_e32 v52, v52, v53
	v_add_f32_e32 v54, v54, v55
	s_waitcnt lgkmcnt(0)
	v_mov_b32_e32 v57, v60
	v_mov_b32_e32 v59, v61
	v_mov_b32_e32 v53, v62
	v_mov_b32_e32 v55, v63
	v_pk_add_f32 v[56:57], v[56:57], v[58:59]
	v_pk_add_f32 v[52:53], v[52:53], v[54:55]
	v_and_b32_e32 v54, 0xffff0000, v96
	v_pk_add_f32 v[52:53], v[56:57], v[52:53]
	v_mul_f32_e32 v54, 0xbfb8aa3b, v54
	v_add_f32_e32 v52, v52, v53
	v_lshlrev_b32_e32 v53, 16, v96
	v_mul_f32_e32 v53, 0xbfb8aa3b, v53
	v_exp_f32_e32 v53, v53
	v_mul_f32_e32 v58, 0xbfb8aa3b, v67
	v_exp_f32_e32 v55, v54
	v_exp_f32_e32 v58, v58
	v_add_f32_e32 v53, 1.0, v53
	v_lshlrev_b32_e32 v56, 16, v97
	v_rcp_f32_e32 v54, v53
	v_add_f32_e32 v53, 1.0, v55
	v_max_f32_e64 v52, |v52|, v58
	v_and_b32_e32 v57, 0xffff0000, v97
	v_rcp_f32_e32 v55, v53
	v_mul_f32_e32 v53, 0xbfb8aa3b, v56
	v_rcp_f32_e32 v52, v52
	v_exp_f32_e32 v53, v53
	v_mul_f32_e32 v56, 0xbfb8aa3b, v57
	v_exp_f32_e32 v57, v56
	v_lshl_add_u64 v[78:79], v[78:79], 0, s[44:45]
	v_pk_mul_f32 v[48:49], v[48:49], v[52:53] op_sel_hi:[1,0]
	v_add_f32_e32 v53, 1.0, v53
	v_rcp_f32_e32 v56, v53
	v_add_f32_e32 v53, 1.0, v57
	v_rcp_f32_e32 v57, v53
	v_pk_mul_f32 v[48:49], v[54:55], v[48:49]
	v_lshl_add_u64 v[82:83], v[82:83], 0, s[44:45]
	v_cvt_pk_bf16_f32 v58, v48, v49
	v_pk_mul_f32 v[48:49], v[50:51], v[52:53] op_sel_hi:[1,0]
	v_lshlrev_b64 v[52:53], 7, v[72:73]
	v_pk_mul_f32 v[48:49], v[56:57], v[48:49]
	v_lshl_add_u64 v[56:57], v[76:77], 0, v[52:53]
	v_cvt_pk_bf16_f32 v59, v48, v49
	ds_read_b128 v[48:51], v198
	ds_read_b128 v[52:55], v198 offset:16
	global_store_dwordx2 v[56:57], v[58:59], off nt
	ds_read_b128 v[56:59], v207
	v_add_u32_e32 v72, -16, v92
	s_waitcnt lgkmcnt(2)
	v_add_f32_e32 v60, v48, v49
	v_add_f32_e32 v62, v50, v51
	s_waitcnt lgkmcnt(1)
	v_add_f32_e32 v52, v52, v53
	v_add_f32_e32 v54, v54, v55
	s_waitcnt lgkmcnt(0)
	v_mov_b32_e32 v61, v56
	v_mov_b32_e32 v63, v57
	v_mov_b32_e32 v53, v58
	v_mov_b32_e32 v55, v59
	v_pk_add_f32 v[56:57], v[60:61], v[62:63]
	v_pk_add_f32 v[52:53], v[52:53], v[54:55]
	v_and_b32_e32 v54, 0xffff0000, v80
	v_pk_add_f32 v[52:53], v[56:57], v[52:53]
	v_mul_f32_e32 v54, 0xbfb8aa3b, v54
	v_add_f32_e32 v52, v52, v53
	v_lshlrev_b32_e32 v53, 16, v80
	v_mul_f32_e32 v53, 0xbfb8aa3b, v53
	v_exp_f32_e32 v53, v53
	v_mul_f32_e32 v58, 0xbfb8aa3b, v68
	v_exp_f32_e32 v55, v54
	v_exp_f32_e32 v58, v58
	v_add_f32_e32 v53, 1.0, v53
	v_lshlrev_b32_e32 v56, 16, v81
	v_rcp_f32_e32 v54, v53
	v_add_f32_e32 v53, 1.0, v55
	v_max_f32_e64 v52, |v52|, v58
	v_and_b32_e32 v57, 0xffff0000, v81
	v_rcp_f32_e32 v55, v53
	v_mul_f32_e32 v53, 0xbfb8aa3b, v56
	v_rcp_f32_e32 v52, v52
	v_exp_f32_e32 v53, v53
	v_mul_f32_e32 v56, 0xbfb8aa3b, v57
	v_exp_f32_e32 v57, v56
	ds_read_b128 v[48:51], v199
	v_pk_mul_f32 v[44:45], v[44:45], v[52:53] op_sel_hi:[1,0]
	v_add_f32_e32 v53, 1.0, v53
	v_rcp_f32_e32 v56, v53
	v_add_f32_e32 v53, 1.0, v57
	v_rcp_f32_e32 v57, v53
	v_pk_mul_f32 v[44:45], v[54:55], v[44:45]
	v_lshl_add_u64 v[84:85], v[84:85], 0, s[44:45]
	v_cvt_pk_bf16_f32 v54, v44, v45
	v_pk_mul_f32 v[44:45], v[46:47], v[52:53] op_sel_hi:[1,0]
	v_lshl_add_u64 v[86:87], v[86:87], 0, s[46:47]
	v_pk_mul_f32 v[44:45], v[56:57], v[44:45]
	v_lshl_add_u64 v[88:89], v[88:89], 0, s[46:47]
	v_cvt_pk_bf16_f32 v55, v44, v45
	v_lshlrev_b64 v[44:45], 7, v[72:73]
	v_lshl_add_u64 v[52:53], v[76:77], 0, v[44:45]
	ds_read_b128 v[44:47], v199 offset:16
	global_store_dwordx2 v[52:53], v[54:55], off nt
	ds_read_b128 v[52:55], v208
	s_waitcnt lgkmcnt(2)
	v_add_f32_e32 v48, v48, v49
	v_add_f32_e32 v50, v50, v51
	s_waitcnt lgkmcnt(1)
	v_add_f32_e32 v44, v44, v45
	v_add_f32_e32 v46, v46, v47
	s_waitcnt lgkmcnt(0)
	v_mov_b32_e32 v49, v52
	v_mov_b32_e32 v51, v53
	v_mov_b32_e32 v45, v54
	v_mov_b32_e32 v47, v55
	v_pk_add_f32 v[48:49], v[48:49], v[50:51]
	v_pk_add_f32 v[44:45], v[44:45], v[46:47]
	v_and_b32_e32 v46, 0xffff0000, v74
	v_pk_add_f32 v[44:45], v[48:49], v[44:45]
	v_mul_f32_e32 v46, 0xbfb8aa3b, v46
	v_add_f32_e32 v44, v44, v45
	v_lshlrev_b32_e32 v45, 16, v74
	v_mul_f32_e32 v45, 0xbfb8aa3b, v45
	v_exp_f32_e32 v45, v45
	v_mul_f32_e32 v50, 0xbfb8aa3b, v69
	v_exp_f32_e32 v47, v46
	v_exp_f32_e32 v50, v50
	v_add_f32_e32 v45, 1.0, v45
	v_lshlrev_b32_e32 v48, 16, v75
	v_rcp_f32_e32 v46, v45
	v_add_f32_e32 v45, 1.0, v47
	v_max_f32_e64 v44, |v44|, v50
	v_and_b32_e32 v49, 0xffff0000, v75
	v_rcp_f32_e32 v47, v45
	v_mul_f32_e32 v45, 0xbfb8aa3b, v48
	v_rcp_f32_e32 v44, v44
	v_exp_f32_e32 v45, v45
	v_mul_f32_e32 v48, 0xbfb8aa3b, v49
	v_exp_f32_e32 v49, v48
	v_lshl_add_u64 v[90:91], v[90:91], 0, s[46:47]
	v_pk_mul_f32 v[40:41], v[40:41], v[44:45] op_sel_hi:[1,0]
	v_add_f32_e32 v45, 1.0, v45
	v_rcp_f32_e32 v48, v45
	v_add_f32_e32 v45, 1.0, v49
	v_rcp_f32_e32 v49, v45
	v_pk_mul_f32 v[42:43], v[42:43], v[44:45] op_sel_hi:[1,0]
	v_pk_mul_f32 v[40:41], v[46:47], v[40:41]
	v_lshl_add_u64 v[94:95], v[94:95], 0, s[46:47]
	v_pk_mul_f32 v[42:43], v[48:49], v[42:43]
	v_cvt_pk_bf16_f32 v40, v40, v41
	v_cvt_pk_bf16_f32 v41, v42, v43
	v_lshlrev_b64 v[42:43], 7, v[92:93]
	v_lshl_add_u64 v[42:43], v[76:77], 0, v[42:43]
	global_store_dwordx2 v[42:43], v[40:41], off nt
	s_waitcnt lgkmcnt(0)
	s_barrier
	v_add_u32_e32 v92, 0x80, v92
	s_andn2_b64 vcc, exec, s[72:73]
	s_waitcnt vmcnt(10)
	v_mov_b32_e32 v100, v110
	v_mov_b64_e32 v[110:111], v[108:109]
	s_waitcnt vmcnt(7)
	v_mov_b64_e32 v[98:99], v[112:113]
	s_waitcnt vmcnt(6)
	v_mov_b64_e32 v[96:97], v[154:155]
	s_waitcnt vmcnt(5)
	v_mov_b64_e32 v[80:81], v[114:115]
	s_waitcnt vmcnt(4)
	v_mov_b64_e32 v[74:75], v[116:117]
	v_mov_b64_e32 v[112:113], v[106:107]
	v_mov_b32_e32 v154, v203
	v_mov_b64_e32 v[114:115], v[104:105]
	v_mov_b64_e32 v[116:117], v[102:103]
	s_cbranch_vccz .LBB0_954

.LBB0_940:
	s_or_b64 exec, exec, s[18:19]
	v_mov_b32_e32 v56, s5
	v_add_f32_e32 v209, s4, v56
	s_add_i32 s4, 0, 0x12900
	v_add_u32_e32 v205, s4, v185
	ds_read_b128 v[56:59], v196
	ds_read_b128 v[60:63], v196 offset:16
	ds_read_b128 v[64:67], v205
	v_add_u32_e32 v72, 0xffffff90, v92
	v_add_u32_e32 v206, s4, v187
	s_waitcnt lgkmcnt(2)
	v_add_f32_e32 v68, v56, v57
	v_add_f32_e32 v70, v58, v59
	s_waitcnt lgkmcnt(1)
	v_add_f32_e32 v60, v60, v61
	v_add_f32_e32 v62, v62, v63
	s_waitcnt lgkmcnt(0)
	v_mov_b32_e32 v69, v64
	v_mov_b32_e32 v71, v65
	v_mov_b32_e32 v61, v66
	v_mov_b32_e32 v63, v67
	ds_read_b128 v[56:59], v197
	ds_read_b32 v66, v186
	v_pk_add_f32 v[64:65], v[68:69], v[70:71]
	v_pk_add_f32 v[60:61], v[60:61], v[62:63]
	v_and_b32_e32 v62, 0xffff0000, v116
	v_pk_add_f32 v[60:61], v[64:65], v[60:61]
	v_mul_f32_e32 v62, 0xbfb8aa3b, v62
	v_add_f32_e32 v60, v60, v61
	v_lshlrev_b32_e32 v61, 16, v116
	v_mul_f32_e32 v61, 0xbfb8aa3b, v61
	v_exp_f32_e32 v61, v61
	s_waitcnt lgkmcnt(0)
	v_mul_f32_e32 v66, 0xbfb8aa3b, v66
	v_exp_f32_e32 v63, v62
	v_exp_f32_e32 v66, v66
	v_add_f32_e32 v61, 1.0, v61
	v_lshlrev_b32_e32 v64, 16, v117
	v_rcp_f32_e32 v62, v61
	v_add_f32_e32 v61, 1.0, v63
	v_max_f32_e64 v60, |v60|, v66
	v_and_b32_e32 v65, 0xffff0000, v117
	v_rcp_f32_e32 v63, v61
	v_mul_f32_e32 v61, 0xbfb8aa3b, v64
	v_rcp_f32_e32 v60, v60
	v_exp_f32_e32 v61, v61
	v_mul_f32_e32 v64, 0xbfb8aa3b, v65
	v_exp_f32_e32 v65, v64
	ds_read_b32 v67, v188
	ds_read_b32 v68, v190
	ds_read_b32 v69, v192
	v_pk_mul_f32 v[52:53], v[52:53], v[60:61] op_sel_hi:[1,0]
	v_add_f32_e32 v61, 1.0, v61
	v_rcp_f32_e32 v64, v61
	v_add_f32_e32 v61, 1.0, v65
	v_rcp_f32_e32 v65, v61
	v_pk_mul_f32 v[54:55], v[54:55], v[60:61] op_sel_hi:[1,0]
	v_pk_mul_f32 v[52:53], v[62:63], v[52:53]
	ds_read_b128 v[60:63], v206
	v_pk_mul_f32 v[54:55], v[64:65], v[54:55]
	v_cvt_pk_bf16_f32 v52, v52, v53
	v_cvt_pk_bf16_f32 v53, v54, v55
	v_lshlrev_b64 v[54:55], 7, v[72:73]
	v_lshl_add_u64 v[54:55], v[76:77], 0, v[54:55]
	global_store_dwordx2 v[54:55], v[52:53], off nt
	ds_read_b128 v[52:55], v197 offset:16
	v_add_f32_e32 v56, v56, v57
	v_add_f32_e32 v58, v58, v59
	s_waitcnt lgkmcnt(1)
	v_mov_b32_e32 v57, v60
	v_mov_b32_e32 v59, v61
	s_waitcnt lgkmcnt(0)
	v_add_f32_e32 v52, v52, v53
	v_add_f32_e32 v54, v54, v55
	v_mov_b32_e32 v53, v62
	v_mov_b32_e32 v55, v63
	v_pk_add_f32 v[56:57], v[56:57], v[58:59]
	v_pk_add_f32 v[52:53], v[52:53], v[54:55]
	v_and_b32_e32 v54, 0xffff0000, v114
	v_pk_add_f32 v[52:53], v[56:57], v[52:53]
	v_mul_f32_e32 v54, 0xbfb8aa3b, v54
	v_add_f32_e32 v52, v52, v53
	v_lshlrev_b32_e32 v53, 16, v114
	v_mul_f32_e32 v53, 0xbfb8aa3b, v53
	v_exp_f32_e32 v53, v53
	v_mul_f32_e32 v58, 0xbfb8aa3b, v67
	v_exp_f32_e32 v55, v54
	v_exp_f32_e32 v58, v58
	v_add_f32_e32 v53, 1.0, v53
	v_lshlrev_b32_e32 v56, 16, v115
	v_rcp_f32_e32 v54, v53
	v_add_f32_e32 v53, 1.0, v55
	v_max_f32_e64 v52, |v52|, v58
	v_and_b32_e32 v57, 0xffff0000, v115
	v_rcp_f32_e32 v55, v53
	v_mul_f32_e32 v53, 0xbfb8aa3b, v56
	v_rcp_f32_e32 v52, v52
	v_exp_f32_e32 v53, v53
	v_mul_f32_e32 v56, 0xbfb8aa3b, v57
	v_exp_f32_e32 v57, v56
	v_add_u32_e32 v72, 0xffffffa0, v92
	v_pk_mul_f32 v[48:49], v[48:49], v[52:53] op_sel_hi:[1,0]
	v_add_f32_e32 v53, 1.0, v53
	v_rcp_f32_e32 v56, v53
	v_add_f32_e32 v53, 1.0, v57
	v_rcp_f32_e32 v57, v53
	v_pk_mul_f32 v[48:49], v[54:55], v[48:49]
	v_add_u32_e32 v207, s4, v189
	v_cvt_pk_bf16_f32 v54, v48, v49
	v_pk_mul_f32 v[48:49], v[50:51], v[52:53] op_sel_hi:[1,0]
	v_add_u32_e32 v208, s4, v191
	v_pk_mul_f32 v[48:49], v[56:57], v[48:49]
	ds_read_b128 v[56:59], v207
	v_cvt_pk_bf16_f32 v55, v48, v49
	v_lshlrev_b64 v[48:49], 7, v[72:73]
	v_lshl_add_u64 v[52:53], v[76:77], 0, v[48:49]
	ds_read_b128 v[48:51], v198
	global_store_dwordx2 v[52:53], v[54:55], off nt
	ds_read_b128 v[52:55], v198 offset:16
	s_waitcnt lgkmcnt(2)
	v_mov_b32_e32 v61, v56
	v_mov_b32_e32 v63, v57
	s_waitcnt lgkmcnt(1)
	v_add_f32_e32 v60, v48, v49
	v_add_f32_e32 v62, v50, v51
	s_waitcnt lgkmcnt(0)
	v_add_f32_e32 v52, v52, v53
	v_add_f32_e32 v54, v54, v55
	v_mov_b32_e32 v53, v58
	v_mov_b32_e32 v55, v59
	v_pk_add_f32 v[56:57], v[60:61], v[62:63]
	v_pk_add_f32 v[52:53], v[52:53], v[54:55]
	v_and_b32_e32 v54, 0xffff0000, v112
	v_pk_add_f32 v[52:53], v[56:57], v[52:53]
	v_mul_f32_e32 v54, 0xbfb8aa3b, v54
	v_add_f32_e32 v52, v52, v53
	v_lshlrev_b32_e32 v53, 16, v112
	v_mul_f32_e32 v53, 0xbfb8aa3b, v53
	v_exp_f32_e32 v53, v53
	v_mul_f32_e32 v58, 0xbfb8aa3b, v68
	v_exp_f32_e32 v55, v54
	v_exp_f32_e32 v58, v58
	v_add_f32_e32 v53, 1.0, v53
	v_lshlrev_b32_e32 v56, 16, v113
	v_rcp_f32_e32 v54, v53
	v_add_f32_e32 v53, 1.0, v55
	v_max_f32_e64 v52, |v52|, v58
	v_and_b32_e32 v57, 0xffff0000, v113
	v_rcp_f32_e32 v55, v53
	v_mul_f32_e32 v53, 0xbfb8aa3b, v56
	v_rcp_f32_e32 v52, v52
	v_exp_f32_e32 v53, v53
	v_mul_f32_e32 v56, 0xbfb8aa3b, v57
	v_exp_f32_e32 v57, v56
	v_add_u32_e32 v72, 0xffffffb0, v92
	v_pk_mul_f32 v[44:45], v[44:45], v[52:53] op_sel_hi:[1,0]
	v_add_f32_e32 v53, 1.0, v53
	v_rcp_f32_e32 v56, v53
	v_add_f32_e32 v53, 1.0, v57
	v_rcp_f32_e32 v57, v53
	v_pk_mul_f32 v[46:47], v[46:47], v[52:53] op_sel_hi:[1,0]
	v_pk_mul_f32 v[44:45], v[54:55], v[44:45]
	ds_read_b128 v[48:51], v199
	v_pk_mul_f32 v[46:47], v[56:57], v[46:47]
	v_cvt_pk_bf16_f32 v44, v44, v45
	v_cvt_pk_bf16_f32 v45, v46, v47
	v_lshlrev_b64 v[46:47], 7, v[72:73]
	v_lshl_add_u64 v[46:47], v[76:77], 0, v[46:47]
	global_store_dwordx2 v[46:47], v[44:45], off nt
	ds_read_b128 v[44:47], v199 offset:16
	ds_read_b128 v[52:55], v208
	s_waitcnt lgkmcnt(2)
	v_add_f32_e32 v48, v48, v49
	v_add_f32_e32 v50, v50, v51
	v_subrev_u32_e32 v72, 64, v92
	s_waitcnt lgkmcnt(1)
	v_add_f32_e32 v44, v44, v45
	v_add_f32_e32 v46, v46, v47
	s_waitcnt lgkmcnt(0)
	v_mov_b32_e32 v49, v52
	v_mov_b32_e32 v51, v53
	v_mov_b32_e32 v45, v54
	v_mov_b32_e32 v47, v55
	v_pk_add_f32 v[48:49], v[48:49], v[50:51]
	v_pk_add_f32 v[44:45], v[44:45], v[46:47]
	v_and_b32_e32 v46, 0xffff0000, v110
	v_pk_add_f32 v[44:45], v[48:49], v[44:45]
	v_mul_f32_e32 v46, 0xbfb8aa3b, v46
	v_add_f32_e32 v44, v44, v45
	v_lshlrev_b32_e32 v45, 16, v110
	v_mul_f32_e32 v45, 0xbfb8aa3b, v45
	v_exp_f32_e32 v45, v45
	v_mul_f32_e32 v50, 0xbfb8aa3b, v69
	v_exp_f32_e32 v47, v46
	v_exp_f32_e32 v50, v50
	v_add_f32_e32 v45, 1.0, v45
	v_lshlrev_b32_e32 v48, 16, v111
	v_rcp_f32_e32 v46, v45
	v_add_f32_e32 v45, 1.0, v47
	v_max_f32_e64 v44, |v44|, v50
	v_and_b32_e32 v49, 0xffff0000, v111
	v_rcp_f32_e32 v47, v45
	v_mul_f32_e32 v45, 0xbfb8aa3b, v48
	v_rcp_f32_e32 v44, v44
	v_exp_f32_e32 v45, v45
	v_mul_f32_e32 v48, 0xbfb8aa3b, v49
	v_exp_f32_e32 v49, v48
	v_readlane_b32 s33, v158, 63
	v_pk_mul_f32 v[40:41], v[40:41], v[44:45] op_sel_hi:[1,0]
	v_add_f32_e32 v45, 1.0, v45
	v_rcp_f32_e32 v48, v45
	v_add_f32_e32 v45, 1.0, v49
	v_rcp_f32_e32 v49, v45
	v_pk_mul_f32 v[42:43], v[42:43], v[44:45] op_sel_hi:[1,0]
	v_pk_mul_f32 v[40:41], v[46:47], v[40:41]
	s_and_b64 vcc, exec, s[14:15]
	v_pk_mul_f32 v[42:43], v[48:49], v[42:43]
	v_cvt_pk_bf16_f32 v40, v40, v41
	v_cvt_pk_bf16_f32 v41, v42, v43
	v_lshlrev_b64 v[42:43], 7, v[72:73]
	v_lshl_add_u64 v[42:43], v[76:77], 0, v[42:43]
	global_store_dwordx2 v[42:43], v[40:41], off nt
	s_waitcnt lgkmcnt(0)
	s_barrier
	v_max_f32_e32 v40, v158, v158
	v_max_f32_e32 v40, v209, v40
	v_readlane_b32 s5, v159, 63
	v_readlane_b32 s4, v40, 63
	s_cbranch_vccnz .LBB0_942
	v_sub_f32_e32 v42, v209, v40
	v_mul_f32_e32 v42, 0x3fb8aa3b, v42
	v_exp_f32_e32 v42, v42
	v_add_f32_e32 v41, v159, v40
	ds_write_b32 v161, v157
	ds_write_b32 v162, v40
	ds_write_b32 v163, v41
	ds_write_b32 v164, v42

.LBB0_964:
	s_or_b64 exec, exec, s[22:23]
	s_waitcnt lgkmcnt(0)
	s_barrier
	ds_read_b128 v[132:135], v216
	ds_read_b128 v[136:139], v216 offset:16
	v_subrev_u32_e32 v154, 48, v170
	v_mov_b32_e32 v171, v155
	s_add_i32 s2, s2, 2
	s_waitcnt lgkmcnt(1)
	v_mov_b32_e32 v140, v132
	s_waitcnt lgkmcnt(0)
	v_mov_b32_e32 v141, v136
	v_mov_b32_e32 v136, v133
	v_pk_add_f32 v[132:133], v[140:141], v[136:137]
	v_mov_b32_e32 v136, v134
	v_mov_b32_e32 v137, v138
	v_mov_b32_e32 v138, v135
	v_pk_add_f32 v[134:135], v[136:137], v[138:139]
	v_lshl_add_u64 v[160:161], v[160:161], 0, s[36:37]
	v_pk_add_f32 v[132:133], v[132:133], v[134:135]
	v_lshlrev_b32_e32 v134, 16, v177
	v_add_f32_e32 v132, v132, v133
	v_fmamk_f32 v132, v132, 0x3c000000, v151
	v_rsq_f32_e32 v132, v132
	v_and_b32_e32 v135, 0xffff0000, v177
	v_mul_f32_e32 v138, 0xbfb8aa3b, v134
	v_mul_f32_e32 v139, 0xbfb8aa3b, v135
	v_pk_mul_f32 v[130:131], v[130:131], v[132:133] op_sel_hi:[1,0]
	v_pk_mul_f32 v[128:129], v[128:129], v[132:133] op_sel_hi:[1,0]
	v_pk_mul_f32 v[136:137], v[2:3], v[130:131]
	v_lshlrev_b32_e32 v130, 16, v176
	v_and_b32_e32 v131, 0xffff0000, v176
	v_mul_f32_e32 v132, 0xbfb8aa3b, v130
	v_mul_f32_e32 v133, 0xbfb8aa3b, v131
	v_exp_f32_e32 v132, v132
	v_exp_f32_e32 v133, v133
	v_exp_f32_e32 v138, v138
	v_exp_f32_e32 v139, v139
	v_add_f32_e32 v132, 1.0, v132
	v_add_f32_e32 v133, 1.0, v133
	v_rcp_f32_e32 v132, v132
	v_rcp_f32_e32 v133, v133
	v_add_f32_e32 v138, 1.0, v138
	v_add_f32_e32 v139, 1.0, v139
	v_rcp_f32_e32 v138, v138
	v_rcp_f32_e32 v139, v139
	v_pk_mul_f32 v[128:129], v[0:1], v[128:129]
	v_pk_mul_f32 v[130:131], v[132:133], v[130:131]
	v_lshl_add_u64 v[162:163], v[162:163], 0, s[36:37]
	v_pk_mul_f32 v[128:129], v[130:131], v[128:129]
	v_pk_mul_f32 v[138:139], v[138:139], v[134:135]
	v_cvt_pk_bf16_f32 v140, v128, v129
	ds_read_b128 v[128:131], v216 offset:512
	ds_read_b128 v[132:135], v216 offset:528
	v_pk_mul_f32 v[136:137], v[138:139], v[136:137]
	v_lshl_add_u64 v[164:165], v[164:165], 0, s[36:37]
	v_cvt_pk_bf16_f32 v141, v136, v137
	s_waitcnt lgkmcnt(1)
	v_mov_b32_e32 v136, v128
	s_waitcnt lgkmcnt(0)
	v_mov_b32_e32 v137, v132
	v_mov_b32_e32 v132, v129
	v_pk_add_f32 v[128:129], v[136:137], v[132:133]
	v_mov_b32_e32 v132, v130
	v_mov_b32_e32 v133, v134
	v_mov_b32_e32 v134, v131
	v_pk_add_f32 v[130:131], v[132:133], v[134:135]
	v_lshl_add_u64 v[166:167], v[166:167], 0, s[38:39]
	v_pk_add_f32 v[128:129], v[128:129], v[130:131]
	v_lshlrev_b64 v[130:131], 7, v[154:155]
	v_add_f32_e32 v128, v128, v129
	v_fmamk_f32 v128, v128, 0x3c000000, v151
	v_rsq_f32_e32 v128, v128
	v_lshl_add_u64 v[130:131], v[158:159], 0, v[130:131]
	global_store_dwordx2 v[130:131], v[140:141], off nt
	v_lshlrev_b32_e32 v130, 16, v175
	v_pk_mul_f32 v[126:127], v[126:127], v[128:129] op_sel_hi:[1,0]
	v_pk_mul_f32 v[124:125], v[124:125], v[128:129] op_sel_hi:[1,0]
	v_pk_mul_f32 v[132:133], v[2:3], v[126:127]
	v_lshlrev_b32_e32 v126, 16, v174
	v_and_b32_e32 v127, 0xffff0000, v174
	v_mul_f32_e32 v128, 0xbfb8aa3b, v126
	v_mul_f32_e32 v129, 0xbfb8aa3b, v127
	v_exp_f32_e32 v128, v128
	v_exp_f32_e32 v129, v129
	v_and_b32_e32 v131, 0xffff0000, v175
	v_mul_f32_e32 v134, 0xbfb8aa3b, v130
	v_mul_f32_e32 v135, 0xbfb8aa3b, v131
	v_exp_f32_e32 v134, v134
	v_exp_f32_e32 v135, v135
	v_add_f32_e32 v128, 1.0, v128
	v_add_f32_e32 v129, 1.0, v129
	v_rcp_f32_e32 v128, v128
	v_rcp_f32_e32 v129, v129
	v_add_f32_e32 v134, 1.0, v134
	v_add_f32_e32 v135, 1.0, v135
	v_rcp_f32_e32 v134, v134
	v_rcp_f32_e32 v135, v135
	v_pk_mul_f32 v[124:125], v[0:1], v[124:125]
	v_pk_mul_f32 v[126:127], v[128:129], v[126:127]
	v_subrev_u32_e32 v154, 32, v170
	v_pk_mul_f32 v[124:125], v[126:127], v[124:125]
	v_pk_mul_f32 v[134:135], v[134:135], v[130:131]
	v_cvt_pk_bf16_f32 v136, v124, v125
	ds_read_b128 v[124:127], v216 offset:1024
	ds_read_b128 v[128:131], v216 offset:1040
	v_pk_mul_f32 v[132:133], v[134:135], v[132:133]
	v_lshl_add_u64 v[168:169], v[168:169], 0, s[38:39]
	v_cvt_pk_bf16_f32 v137, v132, v133
	s_waitcnt lgkmcnt(1)
	v_mov_b32_e32 v132, v124
	s_waitcnt lgkmcnt(0)
	v_mov_b32_e32 v133, v128
	v_mov_b32_e32 v128, v125
	v_pk_add_f32 v[124:125], v[132:133], v[128:129]
	v_mov_b32_e32 v128, v126
	v_mov_b32_e32 v129, v130
	v_mov_b32_e32 v130, v127
	v_pk_add_f32 v[126:127], v[128:129], v[130:131]
	s_andn2_b64 vcc, exec, s[40:41]
	v_pk_add_f32 v[124:125], v[124:125], v[126:127]
	v_lshlrev_b64 v[126:127], 7, v[154:155]
	v_add_f32_e32 v124, v124, v125
	v_fmamk_f32 v124, v124, 0x3c000000, v151
	v_rsq_f32_e32 v124, v124
	v_lshl_add_u64 v[126:127], v[158:159], 0, v[126:127]
	global_store_dwordx2 v[126:127], v[136:137], off nt
	v_lshlrev_b32_e32 v126, 16, v173
	v_pk_mul_f32 v[122:123], v[122:123], v[124:125] op_sel_hi:[1,0]
	v_pk_mul_f32 v[120:121], v[120:121], v[124:125] op_sel_hi:[1,0]
	v_pk_mul_f32 v[128:129], v[2:3], v[122:123]
	v_lshlrev_b32_e32 v122, 16, v172
	v_and_b32_e32 v123, 0xffff0000, v172
	v_mul_f32_e32 v124, 0xbfb8aa3b, v122
	v_mul_f32_e32 v125, 0xbfb8aa3b, v123
	v_exp_f32_e32 v124, v124
	v_exp_f32_e32 v125, v125
	v_and_b32_e32 v127, 0xffff0000, v173
	v_mul_f32_e32 v130, 0xbfb8aa3b, v126
	v_mul_f32_e32 v131, 0xbfb8aa3b, v127
	v_exp_f32_e32 v130, v130
	v_exp_f32_e32 v131, v131
	v_add_f32_e32 v124, 1.0, v124
	v_add_f32_e32 v125, 1.0, v125
	v_rcp_f32_e32 v124, v124
	v_rcp_f32_e32 v125, v125
	v_add_f32_e32 v130, 1.0, v130
	v_add_f32_e32 v131, 1.0, v131
	v_rcp_f32_e32 v130, v130
	v_rcp_f32_e32 v131, v131
	v_pk_mul_f32 v[120:121], v[0:1], v[120:121]
	v_pk_mul_f32 v[122:123], v[124:125], v[122:123]
	v_add_u32_e32 v154, -16, v170
	v_pk_mul_f32 v[120:121], v[122:123], v[120:121]
	v_pk_mul_f32 v[130:131], v[130:131], v[126:127]
	v_cvt_pk_bf16_f32 v132, v120, v121
	ds_read_b128 v[120:123], v216 offset:1536
	ds_read_b128 v[124:127], v216 offset:1552
	v_pk_mul_f32 v[128:129], v[130:131], v[128:129]
	v_mov_b64_e32 v[188:189], v[186:187]
	v_cvt_pk_bf16_f32 v133, v128, v129
	s_waitcnt lgkmcnt(1)
	v_mov_b32_e32 v128, v120
	s_waitcnt lgkmcnt(0)
	v_mov_b32_e32 v129, v124
	v_mov_b32_e32 v124, v121
	v_pk_add_f32 v[120:121], v[128:129], v[124:125]
	v_mov_b32_e32 v124, v122
	v_mov_b32_e32 v125, v126
	v_mov_b32_e32 v126, v123
	v_pk_add_f32 v[122:123], v[124:125], v[126:127]
	v_lshlrev_b32_e32 v124, 16, v157
	v_pk_add_f32 v[120:121], v[120:121], v[122:123]
	v_lshlrev_b64 v[122:123], 7, v[154:155]
	v_add_f32_e32 v120, v120, v121
	v_fmamk_f32 v120, v120, 0x3c000000, v151
	v_rsq_f32_e32 v120, v120
	v_lshl_add_u64 v[122:123], v[158:159], 0, v[122:123]
	global_store_dwordx2 v[122:123], v[132:133], off nt
	v_and_b32_e32 v125, 0xffff0000, v157
	v_pk_mul_f32 v[116:117], v[116:117], v[120:121] op_sel_hi:[1,0]
	v_pk_mul_f32 v[118:119], v[118:119], v[120:121] op_sel_hi:[1,0]
	v_lshlrev_b32_e32 v120, 16, v156
	v_and_b32_e32 v121, 0xffff0000, v156
	v_mul_f32_e32 v122, 0xbfb8aa3b, v120
	v_mul_f32_e32 v123, 0xbfb8aa3b, v121
	v_exp_f32_e32 v122, v122
	v_exp_f32_e32 v123, v123
	v_mul_f32_e32 v126, 0xbfb8aa3b, v124
	v_mul_f32_e32 v127, 0xbfb8aa3b, v125
	v_exp_f32_e32 v126, v126
	v_exp_f32_e32 v127, v127
	v_add_f32_e32 v122, 1.0, v122
	v_add_f32_e32 v123, 1.0, v123
	v_rcp_f32_e32 v122, v122
	v_rcp_f32_e32 v123, v123
	v_add_f32_e32 v126, 1.0, v126
	v_add_f32_e32 v127, 1.0, v127
	v_rcp_f32_e32 v126, v126
	v_rcp_f32_e32 v127, v127
	v_pk_mul_f32 v[116:117], v[0:1], v[116:117]
	v_pk_mul_f32 v[120:121], v[122:123], v[120:121]
	v_pk_mul_f32 v[118:119], v[2:3], v[118:119]
	v_pk_mul_f32 v[116:117], v[120:121], v[116:117]
	v_pk_mul_f32 v[120:121], v[126:127], v[124:125]
	v_cvt_pk_bf16_f32 v116, v116, v117
	v_pk_mul_f32 v[118:119], v[120:121], v[118:119]
	s_waitcnt vmcnt(6)
	v_mov_b64_e32 v[176:177], v[190:191]
	v_cvt_pk_bf16_f32 v117, v118, v119
	v_lshlrev_b64 v[118:119], 7, v[170:171]
	v_lshl_add_u64 v[118:119], v[158:159], 0, v[118:119]
	v_add_u32_e32 v170, 0x80, v170
	s_waitcnt vmcnt(5)
	v_mov_b64_e32 v[174:175], v[192:193]
	s_waitcnt vmcnt(4)
	v_mov_b64_e32 v[172:173], v[194:195]
	s_waitcnt vmcnt(3)
	v_mov_b64_e32 v[156:157], v[198:199]
	v_mov_b64_e32 v[190:191], v[184:185]
	v_mov_b64_e32 v[192:193], v[182:183]
	v_mov_b64_e32 v[194:195], v[178:179]
	global_store_dwordx2 v[118:119], v[116:117], off nt
	s_cbranch_vccz .LBB0_1017

.LBB0_983:
	v_mov_b32_e32 v140, s28
	s_nop 5
	v_cndmask_b32_e64 v140, v136, v140, s[12:13]
	v_cndmask_b32_e64 v140, v140, v136, s[14:15]
	v_cndmask_b32_e64 v140, v136, v140, s[8:9]
	v_mov_b32_e32 v136, s28
	v_cndmask_b32_e64 v141, 0, v137, s[14:15]
	v_cndmask_b32_e64 v142, v138, 0, s[16:17]
	v_cndmask_b32_e64 v143, v139, 0, s[18:19]
	v_cndmask_b32_e64 v136, v132, v136, s[12:13]
	v_cndmask_b32_e64 v137, v137, v141, s[8:9]
	v_cndmask_b32_e64 v139, v139, v143, s[8:9]
	v_cndmask_b32_e64 v138, v138, v142, s[8:9]
	v_cndmask_b32_e64 v141, 0, v133, s[14:15]
	v_cndmask_b32_e64 v136, v136, v132, s[14:15]
	v_cndmask_b32_e64 v142, v134, 0, s[16:17]
	v_cndmask_b32_e64 v143, v135, 0, s[18:19]
	v_cndmask_b32_e64 v141, v133, v141, s[10:11]
	v_cndmask_b32_e64 v135, v135, v143, s[10:11]
	v_cndmask_b32_e64 v142, v134, v142, s[10:11]
	v_cndmask_b32_e64 v134, v132, v136, s[10:11]
	v_cvt_pk_bf16_f32 v132, v140, v137
	v_cvt_pk_bf16_f32 v133, v138, v139
	v_cvt_pk_bf16_f32 v134, v134, v141
	v_cvt_pk_bf16_f32 v135, v142, v135
	ds_write2_b64 v222, v[132:133], v[134:135] offset1:4
	v_add_u32_e32 v132, 0, v213
	s_waitcnt lgkmcnt(0)
	s_barrier
	v_add_u32_e32 v171, 0x20000, v132
	ds_read_b128 v[132:135], v171
	ds_read_b128 v[136:139], v171 offset:64
	ds_read_b64_tr_b16 v[140:141], v214
	ds_read_b64_tr_b16 v[142:143], v214 offset:1088
	s_waitcnt lgkmcnt(3)
	v_pk_mul_f32 v[112:113], v[112:113], v[132:133]
	v_pk_mul_f32 v[114:115], v[114:115], v[134:135]
	ds_read_b128 v[132:135], v223
	ds_read_b128 v[144:147], v171 offset:128
	ds_read_b128 v[224:227], v223 offset:2304
	ds_read_b64_tr_b16 v[228:229], v214 offset:8704
	ds_read_b64_tr_b16 v[230:231], v214 offset:9792
	s_waitcnt lgkmcnt(7)
	v_pk_mul_f32 v[92:93], v[92:93], v[136:137]
	s_waitcnt lgkmcnt(4)
	v_mfma_f32_16x16x32_bf16 v[128:131], v[140:143], v[132:135], v[128:131]
	v_mul_f32_e64 v94, v94, v138
	v_mul_f32_e64 v95, v95, v139
	ds_read_b128 v[132:135], v171 offset:192
	ds_read_b128 v[136:139], v223 offset:4608
	s_waitcnt lgkmcnt(5)
	v_pk_mul_f32 v[84:85], v[84:85], v[144:145]
	s_waitcnt lgkmcnt(4)
	v_mfma_f32_16x16x32_bf16 v[124:127], v[140:143], v[224:227], v[124:127]
	ds_read_b128 v[224:227], v223 offset:6912
	ds_read_b128 v[232:235], v223 offset:4672
	v_pk_mul_f32 v[86:87], v[86:87], v[146:147]
	s_waitcnt lgkmcnt(3)
	v_pk_mul_f32 v[88:89], v[88:89], v[132:133]
	s_waitcnt lgkmcnt(2)
	v_mfma_f32_16x16x32_bf16 v[120:123], v[140:143], v[136:139], v[120:123]
	ds_read_b64_tr_b16 v[138:139], v215 offset:53312
	ds_read_b64_tr_b16 v[136:137], v215 offset:52224
	ds_read_b128 v[236:239], v223 offset:6976
	v_pk_mul_f32 v[90:91], v[90:91], v[134:135]
	s_waitcnt lgkmcnt(4)
	v_mfma_f32_16x16x32_bf16 v[116:119], v[140:143], v[224:227], v[116:119]
	ds_read_b64_tr_b16 v[226:227], v215 offset:53344
	ds_read_b64_tr_b16 v[224:225], v215 offset:52256
	ds_read_b64_tr_b16 v[240:241], v215 offset:52288
	ds_read_b64_tr_b16 v[244:245], v215 offset:52320
	ds_read_b64_tr_b16 v[242:243], v215 offset:53376
	ds_read_b64_tr_b16 v[246:247], v215 offset:53408
	ds_read_b128 v[132:135], v171 offset:320
	s_waitcnt lgkmcnt(0)
	v_pk_mul_f32 v[96:97], v[96:97], v[132:133]
	v_mfma_f32_16x16x32_bf16 v[112:115], v[136:139], v[140:143], v[112:115]
	ds_read_b128 v[136:139], v171 offset:256
	ds_read_b64_tr_b16 v[144:145], v215 offset:52352
	ds_read_b64_tr_b16 v[146:147], v215 offset:53440
	v_pk_mul_f32 v[98:99], v[98:99], v[134:135]
	v_mfma_f32_16x16x32_bf16 v[92:95], v[224:227], v[140:143], v[92:95]
	s_waitcnt lgkmcnt(2)
	v_pk_mul_f32 v[104:105], v[104:105], v[136:137]
	v_pk_mul_f32 v[106:107], v[106:107], v[138:139]
	v_mfma_f32_16x16x32_bf16 v[84:87], v[240:243], v[140:143], v[84:87]
	ds_read_b64_tr_b16 v[138:139], v215 offset:53472
	ds_read_b64_tr_b16 v[136:137], v215 offset:52384
	ds_read_b64_tr_b16 v[224:225], v215 offset:52416
	ds_read_b64_tr_b16 v[240:241], v215 offset:52448
	ds_read_b64_tr_b16 v[226:227], v215 offset:53504
	ds_read_b64_tr_b16 v[242:243], v215 offset:53536
	ds_read_b128 v[132:135], v171 offset:448
	s_waitcnt lgkmcnt(7)
	v_mfma_f32_16x16x32_bf16 v[104:107], v[144:147], v[140:143], v[104:107]
	ds_read_b128 v[144:147], v171 offset:384
	s_waitcnt lgkmcnt(0)
	v_pk_mul_f32 v[100:101], v[100:101], v[144:145]
	v_pk_mul_f32 v[102:103], v[102:103], v[146:147]
	v_mfma_f32_16x16x32_bf16 v[96:99], v[136:139], v[140:143], v[96:99]
	s_nop 0
	v_mfma_f32_16x16x32_bf16 v[136:139], v[224:227], v[140:143], v[100:103]
	v_add_u32_e32 v224, v211, v209
	s_nop 1
	v_pk_mul_f32 v[100:101], v[108:109], v[132:133]
	v_pk_mul_f32 v[102:103], v[110:111], v[134:135]
	v_mfma_f32_16x16x32_bf16 v[88:91], v[244:247], v[140:143], v[88:91]
	s_nop 0
	v_mfma_f32_16x16x32_bf16 v[132:135], v[240:243], v[140:143], v[100:103]
	s_nop 2
	ds_read_b64_tr_b16 v[100:101], v215 offset:60928
	ds_read_b64_tr_b16 v[102:103], v215 offset:62016
	ds_read_b64_tr_b16 v[110:111], v215 offset:62048
	ds_read_b64_tr_b16 v[108:109], v215 offset:60960
	ds_read_b64_tr_b16 v[140:141], v215 offset:60992
	ds_read_b64_tr_b16 v[144:145], v215 offset:61024
	ds_read_b64_tr_b16 v[142:143], v215 offset:62080
	ds_read_b64_tr_b16 v[146:147], v215 offset:62112
	s_waitcnt lgkmcnt(4)
	v_mfma_f32_16x16x32_bf16 v[108:111], v[108:111], v[228:231], v[92:95]
	s_nop 2
	ds_read_b64_tr_b16 v[92:93], v215 offset:61056
	ds_read_b64_tr_b16 v[94:95], v215 offset:62144
	v_mfma_f32_16x16x32_bf16 v[112:115], v[100:103], v[228:231], v[112:115]
	s_waitcnt lgkmcnt(3)
	v_mfma_f32_16x16x32_bf16 v[84:87], v[140:143], v[228:231], v[84:87]
	s_waitcnt lgkmcnt(2)
	v_mfma_f32_16x16x32_bf16 v[88:91], v[144:147], v[228:231], v[88:91]
	ds_read_b64_tr_b16 v[102:103], v215 offset:62176
	ds_read_b64_tr_b16 v[100:101], v215 offset:61088
	ds_read_b64_tr_b16 v[140:141], v215 offset:61120
	ds_read_b64_tr_b16 v[144:145], v215 offset:61152
	ds_read_b64_tr_b16 v[142:143], v215 offset:62208
	ds_read_b64_tr_b16 v[146:147], v215 offset:62240
	s_waitcnt lgkmcnt(6)
	v_mfma_f32_16x16x32_bf16 v[104:107], v[92:95], v[228:231], v[104:107]
	s_waitcnt lgkmcnt(4)
	v_mfma_f32_16x16x32_bf16 v[100:103], v[100:103], v[228:231], v[96:99]
	s_waitcnt lgkmcnt(1)
	v_mfma_f32_16x16x32_bf16 v[92:95], v[140:143], v[228:231], v[136:139]
	s_waitcnt lgkmcnt(0)
	v_mfma_f32_16x16x32_bf16 v[96:99], v[144:147], v[228:231], v[132:135]
	s_nop 2
	v_cvt_pk_bf16_f32 v132, v112, v113
	v_cvt_pk_bf16_f32 v133, v114, v115
	v_cvt_pk_bf16_f32 v134, v108, v109
	v_cvt_pk_bf16_f32 v135, v110, v111
	ds_write2_b64 v224, v[132:133], v[134:135] offset1:4
	v_cvt_pk_bf16_f32 v132, v84, v85
	v_cvt_pk_bf16_f32 v133, v86, v87
	v_cvt_pk_bf16_f32 v134, v88, v89
	v_cvt_pk_bf16_f32 v135, v90, v91
	ds_write2_b64 v224, v[132:133], v[134:135] offset0:8 offset1:12
	v_cvt_pk_bf16_f32 v132, v104, v105
	v_cvt_pk_bf16_f32 v133, v106, v107
	v_cvt_pk_bf16_f32 v134, v100, v101
	v_cvt_pk_bf16_f32 v135, v102, v103
	ds_write2_b64 v224, v[132:133], v[134:135] offset0:16 offset1:20
	v_cvt_pk_bf16_f32 v132, v92, v93
	v_cvt_pk_bf16_f32 v133, v94, v95
	v_cvt_pk_bf16_f32 v134, v96, v97
	v_cvt_pk_bf16_f32 v135, v98, v99
	ds_write2_b64 v224, v[132:133], v[134:135] offset0:24 offset1:28
	v_mul_f32_e32 v132, v129, v129
	v_mul_f32_e32 v133, v131, v131
	v_fmac_f32_e32 v132, v128, v128
	v_fmac_f32_e32 v133, v130, v130
	v_add_f32_e32 v132, v132, v133
	v_mov_b32_e32 v133, v132
	v_mfma_f32_16x16x32_bf16 v[120:123], v[228:231], v[232:235], v[120:123]
	s_nop 0
	v_permlane16_swap_b32_e32 v132, v133
	v_add_f32_e32 v132, v132, v133
	v_mfma_f32_16x16x32_bf16 v[116:119], v[228:231], v[236:239], v[116:119]
	v_mov_b32_e32 v133, v132
	s_nop 1
	v_permlane32_swap_b32_e32 v132, v133
	s_and_saveexec_b64 s[30:31], s[20:21]
	v_add_f32_e32 v132, v132, v133
	ds_write_b32 v217, v132
	s_or_b64 exec, exec, s[30:31]
	v_mul_f32_e32 v132, v125, v125
	v_mul_f32_e32 v133, v127, v127
	v_fmac_f32_e32 v132, v124, v124
	v_fmac_f32_e32 v133, v126, v126
	v_add_f32_e32 v132, v132, v133
	v_mov_b32_e32 v133, v132
	s_nop 1
	v_permlane16_swap_b32_e32 v132, v133
	v_add_f32_e32 v132, v132, v133
	v_mov_b32_e32 v133, v132
	s_nop 1
	v_permlane32_swap_b32_e32 v132, v133
	s_and_saveexec_b64 s[30:31], s[20:21]
	v_add_f32_e32 v132, v132, v133
	ds_write_b32 v217, v132 offset:512
	s_or_b64 exec, exec, s[30:31]
	v_mul_f32_e32 v132, v121, v121
	v_mul_f32_e32 v133, v123, v123
	v_fmac_f32_e32 v132, v120, v120
	v_fmac_f32_e32 v133, v122, v122
	v_add_f32_e32 v132, v132, v133
	v_mov_b32_e32 v133, v132
	s_nop 1
	v_permlane16_swap_b32_e32 v132, v133
	v_add_f32_e32 v132, v132, v133
	v_mov_b32_e32 v133, v132
	s_nop 1
	v_permlane32_swap_b32_e32 v132, v133
	s_and_saveexec_b64 s[30:31], s[20:21]
	v_add_f32_e32 v132, v132, v133
	ds_write_b32 v217, v132 offset:1024
	s_or_b64 exec, exec, s[30:31]
	v_mul_f32_e32 v132, v117, v117
	v_mul_f32_e32 v133, v119, v119
	v_fmac_f32_e32 v132, v116, v116
	v_fmac_f32_e32 v133, v118, v118
	v_add_f32_e32 v132, v132, v133
	v_mov_b32_e32 v133, v132
	s_nop 1
	v_permlane16_swap_b32_e32 v132, v133
	v_add_f32_e32 v132, v132, v133
	v_mov_b32_e32 v133, v132
	s_nop 1
	v_permlane32_swap_b32_e32 v132, v133
	s_and_saveexec_b64 s[30:31], s[20:21]
	v_add_f32_e32 v132, v132, v133
	ds_write_b32 v217, v132 offset:1536
	s_or_b64 exec, exec, s[30:31]
	s_waitcnt lgkmcnt(0)
	s_barrier
	ds_read_b128 v[132:135], v216
	ds_read_b128 v[136:139], v216 offset:16
	v_add_u32_e32 v154, 0xffffff90, v170
	s_waitcnt lgkmcnt(1)
	v_mov_b32_e32 v140, v132
	s_waitcnt lgkmcnt(0)
	v_mov_b32_e32 v141, v136
	v_mov_b32_e32 v136, v133
	v_pk_add_f32 v[132:133], v[140:141], v[136:137]
	v_mov_b32_e32 v136, v134
	v_mov_b32_e32 v137, v138
	v_mov_b32_e32 v138, v135
	v_pk_add_f32 v[134:135], v[136:137], v[138:139]
	s_nop 0
	v_pk_add_f32 v[132:133], v[132:133], v[134:135]
	v_lshlrev_b32_e32 v134, 16, v195
	v_add_f32_e32 v132, v132, v133
	v_fmamk_f32 v132, v132, 0x3c000000, v151
	v_rsq_f32_e32 v132, v132
	v_and_b32_e32 v135, 0xffff0000, v195
	v_mul_f32_e32 v138, 0xbfb8aa3b, v134
	v_mul_f32_e32 v139, 0xbfb8aa3b, v135
	v_pk_mul_f32 v[130:131], v[130:131], v[132:133] op_sel_hi:[1,0]
	v_pk_mul_f32 v[128:129], v[128:129], v[132:133] op_sel_hi:[1,0]
	v_pk_mul_f32 v[136:137], v[2:3], v[130:131]
	v_lshlrev_b32_e32 v130, 16, v194
	v_and_b32_e32 v131, 0xffff0000, v194
	v_mul_f32_e32 v132, 0xbfb8aa3b, v130
	v_mul_f32_e32 v133, 0xbfb8aa3b, v131
	v_exp_f32_e32 v132, v132
	v_exp_f32_e32 v133, v133
	v_exp_f32_e32 v138, v138
	v_exp_f32_e32 v139, v139
	v_add_f32_e32 v132, 1.0, v132
	v_add_f32_e32 v133, 1.0, v133
	v_rcp_f32_e32 v132, v132
	v_rcp_f32_e32 v133, v133
	v_add_f32_e32 v138, 1.0, v138
	v_add_f32_e32 v139, 1.0, v139
	v_rcp_f32_e32 v138, v138
	v_rcp_f32_e32 v139, v139
	v_pk_mul_f32 v[128:129], v[0:1], v[128:129]
	v_pk_mul_f32 v[130:131], v[132:133], v[130:131]
	v_pk_mul_f32 v[138:139], v[138:139], v[134:135]
	v_pk_mul_f32 v[128:129], v[130:131], v[128:129]
	v_pk_mul_f32 v[136:137], v[138:139], v[136:137]
	v_cvt_pk_bf16_f32 v140, v128, v129
	ds_read_b128 v[128:131], v216 offset:512
	ds_read_b128 v[132:135], v216 offset:528
	v_cvt_pk_bf16_f32 v141, v136, v137
	s_waitcnt lgkmcnt(1)
	v_mov_b32_e32 v136, v128
	s_waitcnt lgkmcnt(0)
	v_mov_b32_e32 v137, v132
	v_mov_b32_e32 v132, v129
	v_pk_add_f32 v[128:129], v[136:137], v[132:133]
	v_mov_b32_e32 v132, v130
	v_mov_b32_e32 v133, v134
	v_mov_b32_e32 v134, v131
	v_pk_add_f32 v[130:131], v[132:133], v[134:135]
	s_nop 0
	v_pk_add_f32 v[128:129], v[128:129], v[130:131]
	v_lshlrev_b64 v[130:131], 7, v[154:155]
	v_add_f32_e32 v128, v128, v129
	v_fmamk_f32 v128, v128, 0x3c000000, v151
	v_rsq_f32_e32 v128, v128
	v_lshl_add_u64 v[130:131], v[158:159], 0, v[130:131]
	global_store_dwordx2 v[130:131], v[140:141], off nt
	v_lshlrev_b32_e32 v130, 16, v193
	v_pk_mul_f32 v[126:127], v[126:127], v[128:129] op_sel_hi:[1,0]
	v_pk_mul_f32 v[124:125], v[124:125], v[128:129] op_sel_hi:[1,0]
	v_pk_mul_f32 v[132:133], v[2:3], v[126:127]
	v_lshlrev_b32_e32 v126, 16, v192
	v_and_b32_e32 v127, 0xffff0000, v192
	v_mul_f32_e32 v128, 0xbfb8aa3b, v126
	v_mul_f32_e32 v129, 0xbfb8aa3b, v127
	v_exp_f32_e32 v128, v128
	v_exp_f32_e32 v129, v129
	v_and_b32_e32 v131, 0xffff0000, v193
	v_mul_f32_e32 v134, 0xbfb8aa3b, v130
	v_mul_f32_e32 v135, 0xbfb8aa3b, v131
	v_exp_f32_e32 v134, v134
	v_exp_f32_e32 v135, v135
	v_add_f32_e32 v128, 1.0, v128
	v_add_f32_e32 v129, 1.0, v129
	v_rcp_f32_e32 v128, v128
	v_rcp_f32_e32 v129, v129
	v_add_f32_e32 v134, 1.0, v134
	v_add_f32_e32 v135, 1.0, v135
	v_rcp_f32_e32 v134, v134
	v_rcp_f32_e32 v135, v135
	v_pk_mul_f32 v[124:125], v[0:1], v[124:125]
	v_pk_mul_f32 v[126:127], v[128:129], v[126:127]
	v_add_u32_e32 v154, 0xffffffa0, v170
	v_pk_mul_f32 v[124:125], v[126:127], v[124:125]
	v_pk_mul_f32 v[134:135], v[134:135], v[130:131]
	v_cvt_pk_bf16_f32 v136, v124, v125
	ds_read_b128 v[124:127], v216 offset:1024
	ds_read_b128 v[128:131], v216 offset:1040
	v_pk_mul_f32 v[132:133], v[134:135], v[132:133]
	s_nop 0
	v_cvt_pk_bf16_f32 v137, v132, v133
	s_waitcnt lgkmcnt(1)
	v_mov_b32_e32 v132, v124
	s_waitcnt lgkmcnt(0)
	v_mov_b32_e32 v133, v128
	v_mov_b32_e32 v128, v125
	v_pk_add_f32 v[124:125], v[132:133], v[128:129]
	v_mov_b32_e32 v128, v126
	v_mov_b32_e32 v129, v130
	v_mov_b32_e32 v130, v127
	v_pk_add_f32 v[126:127], v[128:129], v[130:131]
	s_nop 0
	v_pk_add_f32 v[124:125], v[124:125], v[126:127]
	v_lshlrev_b64 v[126:127], 7, v[154:155]
	v_add_f32_e32 v124, v124, v125
	v_fmamk_f32 v124, v124, 0x3c000000, v151
	v_rsq_f32_e32 v124, v124
	v_lshl_add_u64 v[126:127], v[158:159], 0, v[126:127]
	global_store_dwordx2 v[126:127], v[136:137], off nt
	v_lshlrev_b32_e32 v126, 16, v191
	v_pk_mul_f32 v[122:123], v[122:123], v[124:125] op_sel_hi:[1,0]
	v_pk_mul_f32 v[120:121], v[120:121], v[124:125] op_sel_hi:[1,0]
	v_pk_mul_f32 v[128:129], v[2:3], v[122:123]
	v_lshlrev_b32_e32 v122, 16, v190
	v_and_b32_e32 v123, 0xffff0000, v190
	v_mul_f32_e32 v124, 0xbfb8aa3b, v122
	v_mul_f32_e32 v125, 0xbfb8aa3b, v123
	v_exp_f32_e32 v124, v124
	v_exp_f32_e32 v125, v125
	v_and_b32_e32 v127, 0xffff0000, v191
	v_mul_f32_e32 v130, 0xbfb8aa3b, v126
	v_mul_f32_e32 v131, 0xbfb8aa3b, v127
	v_exp_f32_e32 v130, v130
	v_exp_f32_e32 v131, v131
	v_add_f32_e32 v124, 1.0, v124
	v_add_f32_e32 v125, 1.0, v125
	v_rcp_f32_e32 v124, v124
	v_rcp_f32_e32 v125, v125
	v_add_f32_e32 v130, 1.0, v130
	v_add_f32_e32 v131, 1.0, v131
	v_rcp_f32_e32 v130, v130
	v_rcp_f32_e32 v131, v131
	v_pk_mul_f32 v[120:121], v[0:1], v[120:121]
	v_pk_mul_f32 v[122:123], v[124:125], v[122:123]
	v_add_u32_e32 v154, 0xffffffb0, v170
	v_pk_mul_f32 v[120:121], v[122:123], v[120:121]
	v_pk_mul_f32 v[130:131], v[130:131], v[126:127]
	v_cvt_pk_bf16_f32 v132, v120, v121
	ds_read_b128 v[120:123], v216 offset:1536
	ds_read_b128 v[124:127], v216 offset:1552
	v_pk_mul_f32 v[128:129], v[130:131], v[128:129]
	s_nop 0
	v_cvt_pk_bf16_f32 v133, v128, v129
	s_waitcnt lgkmcnt(1)
	v_mov_b32_e32 v128, v120
	s_waitcnt lgkmcnt(0)
	v_mov_b32_e32 v129, v124
	v_mov_b32_e32 v124, v121
	v_pk_add_f32 v[120:121], v[128:129], v[124:125]
	v_mov_b32_e32 v124, v122
	v_mov_b32_e32 v125, v126
	v_mov_b32_e32 v126, v123
	v_pk_add_f32 v[122:123], v[124:125], v[126:127]
	v_lshlrev_b32_e32 v124, 16, v189
	v_pk_add_f32 v[120:121], v[120:121], v[122:123]
	v_lshlrev_b64 v[122:123], 7, v[154:155]
	v_add_f32_e32 v120, v120, v121
	v_fmamk_f32 v120, v120, 0x3c000000, v151
	v_rsq_f32_e32 v120, v120
	v_lshl_add_u64 v[122:123], v[158:159], 0, v[122:123]
	global_store_dwordx2 v[122:123], v[132:133], off nt
	v_and_b32_e32 v125, 0xffff0000, v189
	v_pk_mul_f32 v[116:117], v[116:117], v[120:121] op_sel_hi:[1,0]
	v_pk_mul_f32 v[118:119], v[118:119], v[120:121] op_sel_hi:[1,0]
	v_lshlrev_b32_e32 v120, 16, v188
	v_and_b32_e32 v121, 0xffff0000, v188
	v_mul_f32_e32 v122, 0xbfb8aa3b, v120
	v_mul_f32_e32 v123, 0xbfb8aa3b, v121
	v_exp_f32_e32 v122, v122
	v_exp_f32_e32 v123, v123
	v_mul_f32_e32 v126, 0xbfb8aa3b, v124
	v_mul_f32_e32 v127, 0xbfb8aa3b, v125
	v_exp_f32_e32 v126, v126
	v_exp_f32_e32 v127, v127
	v_add_f32_e32 v122, 1.0, v122
	v_add_f32_e32 v123, 1.0, v123
	v_rcp_f32_e32 v122, v122
	v_rcp_f32_e32 v123, v123
	v_add_f32_e32 v126, 1.0, v126
	v_add_f32_e32 v127, 1.0, v127
	v_rcp_f32_e32 v126, v126
	v_rcp_f32_e32 v127, v127
	v_pk_mul_f32 v[116:117], v[0:1], v[116:117]
	v_pk_mul_f32 v[120:121], v[122:123], v[120:121]
	v_pk_mul_f32 v[118:119], v[2:3], v[118:119]
	v_pk_mul_f32 v[116:117], v[120:121], v[116:117]
	v_pk_mul_f32 v[120:121], v[126:127], v[124:125]
	v_subrev_u32_e32 v154, 64, v170
	v_pk_mul_f32 v[118:119], v[120:121], v[118:119]
	v_cvt_pk_bf16_f32 v116, v116, v117
	v_cvt_pk_bf16_f32 v117, v118, v119
	v_lshlrev_b64 v[118:119], 7, v[154:155]
	v_lshl_add_u64 v[118:119], v[158:159], 0, v[118:119]
	global_store_dwordx2 v[118:119], v[116:117], off nt
	s_waitcnt vmcnt(17)
	ds_write_b128 v204, v[36:39]
	s_waitcnt vmcnt(15)
	ds_write_b128 v204, v[44:47] offset:34816
	s_waitcnt vmcnt(14)
	ds_write_b128 v204, v[56:59] offset:52224
	ds_write_b128 v218, v[40:43]
	s_waitcnt vmcnt(13)
	ds_write_b128 v205, v[60:63]
	s_waitcnt vmcnt(11)
	ds_write_b128 v205, v[68:71] offset:34816
	s_waitcnt vmcnt(10)
	ds_write_b128 v205, v[72:75] offset:52224
	ds_write_b128 v219, v[64:67]
	s_and_saveexec_b64 s[30:31], s[6:7]
	ds_write_b32 v206, v203
	s_or_b64 exec, exec, s[30:31]
	s_andn2_b64 vcc, exec, s[42:43]
	s_waitcnt vmcnt(7)
	v_mov_b64_e32 v[190:191], v[176:177]
	s_waitcnt vmcnt(6)
	v_mov_b64_e32 v[192:193], v[174:175]
	s_waitcnt vmcnt(5)
	v_mov_b64_e32 v[194:195], v[172:173]
	s_waitcnt vmcnt(4)
	v_mov_b64_e32 v[198:199], v[156:157]
	ds_write_b128 v207, v[76:79]
	ds_write_b128 v208, v[80:83]
	s_cbranch_vccnz .LBB0_997
	v_add_co_u32_e32 v36, vcc, 0x49ab0000, v196
	v_mov_b32_e32 v203, 0
	s_nop 0
	v_addc_co_u32_e32 v37, vcc, 0, v197, vcc
	v_add_co_u32_e32 v40, vcc, 0x49ab4000, v196
	s_nop 1
	v_addc_co_u32_e32 v41, vcc, 0, v197, vcc
	v_add_co_u32_e32 v44, vcc, 0x49ab8000, v196
	global_load_dwordx4 v[36:39], v[36:37], off offset:1536
	s_nop 0
	global_load_dwordx4 v[40:43], v[40:41], off offset:1536
	v_addc_co_u32_e32 v45, vcc, 0, v197, vcc
	v_add_co_u32_e32 v56, vcc, 0x49abc000, v196
	s_nop 1
	v_addc_co_u32_e32 v57, vcc, 0, v197, vcc
	v_add_co_u32_e32 v60, vcc, 0x49ab2000, v196
	global_load_dwordx4 v[44:47], v[44:45], off offset:1536
	s_nop 0
	global_load_dwordx4 v[56:59], v[56:57], off offset:1536
	v_addc_co_u32_e32 v61, vcc, 0, v197, vcc
	v_add_co_u32_e32 v64, vcc, 0x49ab6000, v196
	s_nop 1
	v_addc_co_u32_e32 v65, vcc, 0, v197, vcc
	v_add_co_u32_e32 v68, vcc, 0x49aba000, v196
	global_load_dwordx4 v[60:63], v[60:61], off offset:1536
	s_nop 0
	global_load_dwordx4 v[64:67], v[64:65], off offset:1536
	v_addc_co_u32_e32 v69, vcc, 0, v197, vcc
	v_add_co_u32_e32 v72, vcc, 0x49abe000, v196
	s_nop 1
	v_addc_co_u32_e32 v73, vcc, 0, v197, vcc
	global_load_dwordx4 v[68:71], v[68:69], off offset:1536
	s_nop 0
	global_load_dwordx4 v[72:75], v[72:73], off offset:1536
	s_and_saveexec_b64 s[30:31], s[6:7]
	s_cbranch_execz .LBB0_996
	v_lshl_add_u64 v[76:77], s[48:49], 0, v[168:169]
	v_add_co_u32_e32 v76, vcc, 0x49ac0000, v76
	s_nop 1
	v_addc_co_u32_e32 v77, vcc, 0, v77, vcc
	global_load_dword v203, v[76:77], off offset:1536

.LBB0_1027:
	s_or_b64 exec, exec, s[22:23]
	s_waitcnt lgkmcnt(0)
	s_barrier
	ds_read_b128 v[84:87], v158
	ds_read_b128 v[88:91], v158 offset:16
	s_add_i32 s33, s33, 2
	v_lshl_add_u64 v[102:103], v[102:103], 0, s[36:37]
	v_lshl_add_u64 v[104:105], v[104:105], 0, s[36:37]
	s_waitcnt lgkmcnt(1)
	v_mov_b32_e32 v92, v84
	s_waitcnt lgkmcnt(0)
	v_mov_b32_e32 v93, v88
	v_mov_b32_e32 v88, v85
	v_pk_add_f32 v[84:85], v[92:93], v[88:89]
	v_mov_b32_e32 v88, v86
	v_mov_b32_e32 v89, v90
	v_mov_b32_e32 v90, v87
	v_pk_add_f32 v[86:87], v[88:89], v[90:91]
	v_lshlrev_b32_e32 v88, 16, v119
	v_pk_add_f32 v[84:85], v[84:85], v[86:87]
	v_and_b32_e32 v89, 0xffff0000, v119
	v_add_f32_e32 v84, v84, v85
	v_fmamk_f32 v84, v84, 0x3c000000, v151
	v_rsq_f32_e32 v84, v84
	v_mul_f32_e32 v90, 0xbfb8aa3b, v88
	v_mul_f32_e32 v91, 0xbfb8aa3b, v89
	v_exp_f32_e32 v90, v90
	v_pk_mul_f32 v[80:81], v[80:81], v[84:85] op_sel_hi:[1,0]
	v_pk_mul_f32 v[82:83], v[82:83], v[84:85] op_sel_hi:[1,0]
	v_lshlrev_b32_e32 v84, 16, v118
	v_and_b32_e32 v85, 0xffff0000, v118
	v_mul_f32_e32 v86, 0xbfb8aa3b, v84
	v_mul_f32_e32 v87, 0xbfb8aa3b, v85
	v_exp_f32_e32 v86, v86
	v_exp_f32_e32 v87, v87
	v_exp_f32_e32 v91, v91
	v_add_f32_e32 v90, 1.0, v90
	v_add_f32_e32 v86, 1.0, v86
	v_add_f32_e32 v87, 1.0, v87
	v_rcp_f32_e32 v86, v86
	v_rcp_f32_e32 v87, v87
	v_add_f32_e32 v91, 1.0, v91
	v_rcp_f32_e32 v90, v90
	v_rcp_f32_e32 v91, v91
	v_pk_mul_f32 v[80:81], v[0:1], v[80:81]
	v_pk_mul_f32 v[84:85], v[86:87], v[84:85]
	v_pk_mul_f32 v[82:83], v[2:3], v[82:83]
	v_pk_mul_f32 v[80:81], v[84:85], v[80:81]
	v_lshl_add_u64 v[106:107], v[106:107], 0, s[36:37]
	v_cvt_pk_bf16_f32 v92, v80, v81
	v_pk_mul_f32 v[80:81], v[90:91], v[88:89]
	v_add_co_u32_e32 v88, vcc, s4, v134
	v_pk_mul_f32 v[80:81], v[80:81], v[82:83]
	s_nop 0
	v_addc_co_u32_e32 v89, vcc, 0, v135, vcc
	v_cvt_pk_bf16_f32 v93, v80, v81
	ds_read_b128 v[80:83], v158 offset:512
	ds_read_b128 v[84:87], v158 offset:528
	v_lshl_add_u64 v[108:109], v[108:109], 0, s[38:39]
	v_lshl_add_u64 v[110:111], v[110:111], 0, s[38:39]
	v_lshl_add_u64 v[112:113], v[112:113], 0, s[40:41]
	s_waitcnt lgkmcnt(1)
	v_mov_b32_e32 v90, v80
	s_waitcnt lgkmcnt(0)
	v_mov_b32_e32 v91, v84
	v_mov_b32_e32 v84, v81
	v_pk_add_f32 v[80:81], v[90:91], v[84:85]
	v_mov_b32_e32 v84, v82
	v_mov_b32_e32 v85, v86
	v_mov_b32_e32 v86, v83
	v_pk_add_f32 v[82:83], v[84:85], v[86:87]
	v_add_co_u32_e32 v84, vcc, s5, v134
	v_pk_add_f32 v[80:81], v[80:81], v[82:83]
	s_nop 0
	v_addc_co_u32_e32 v85, vcc, 0, v135, vcc
	v_add_f32_e32 v80, v80, v81
	v_fmamk_f32 v80, v80, 0x3c000000, v151
	v_rsq_f32_e32 v80, v80
	global_store_dwordx2 v[84:85], v[92:93], off offset:-4096 nt
	v_lshlrev_b32_e32 v92, 16, v117
	v_and_b32_e32 v93, 0xffff0000, v117
	v_pk_mul_f32 v[78:79], v[78:79], v[80:81] op_sel_hi:[1,0]
	v_pk_mul_f32 v[76:77], v[76:77], v[80:81] op_sel_hi:[1,0]
	v_pk_mul_f32 v[86:87], v[2:3], v[78:79]
	v_lshlrev_b32_e32 v78, 16, v116
	v_and_b32_e32 v79, 0xffff0000, v116
	v_mul_f32_e32 v80, 0xbfb8aa3b, v78
	v_mul_f32_e32 v81, 0xbfb8aa3b, v79
	v_exp_f32_e32 v80, v80
	v_exp_f32_e32 v81, v81
	v_pk_mul_f32 v[90:91], v[0:1], v[76:77]
	s_andn2_b64 vcc, exec, s[42:43]
	v_add_f32_e32 v76, 1.0, v80
	v_add_f32_e32 v77, 1.0, v81
	v_mul_f32_e32 v80, 0xbfb8aa3b, v92
	v_rcp_f32_e32 v76, v76
	v_rcp_f32_e32 v77, v77
	v_exp_f32_e32 v80, v80
	v_mul_f32_e32 v81, 0xbfb8aa3b, v93
	v_exp_f32_e32 v81, v81
	v_pk_mul_f32 v[94:95], v[76:77], v[78:79]
	v_add_f32_e32 v76, 1.0, v80
	v_rcp_f32_e32 v96, v76
	v_add_f32_e32 v76, 1.0, v81
	v_rcp_f32_e32 v97, v76
	ds_read_b128 v[76:79], v158 offset:1024
	ds_read_b128 v[80:83], v158 offset:1040
	v_pk_mul_f32 v[90:91], v[94:95], v[90:91]
	v_mov_b64_e32 v[128:129], v[126:127]
	v_pk_mul_f32 v[92:93], v[96:97], v[92:93]
	s_waitcnt lgkmcnt(1)
	v_mov_b32_e32 v94, v76
	s_waitcnt lgkmcnt(0)
	v_mov_b32_e32 v95, v80
	v_mov_b32_e32 v80, v77
	v_pk_add_f32 v[76:77], v[94:95], v[80:81]
	v_mov_b32_e32 v80, v78
	v_mov_b32_e32 v81, v82
	v_mov_b32_e32 v82, v79
	v_pk_add_f32 v[78:79], v[80:81], v[82:83]
	v_cvt_pk_bf16_f32 v90, v90, v91
	v_pk_add_f32 v[76:77], v[76:77], v[78:79]
	v_pk_mul_f32 v[78:79], v[92:93], v[86:87]
	v_add_f32_e32 v76, v76, v77
	v_fmamk_f32 v76, v76, 0x3c000000, v151
	v_rsq_f32_e32 v76, v76
	v_lshlrev_b32_e32 v86, 16, v115
	v_and_b32_e32 v87, 0xffff0000, v115
	v_cvt_pk_bf16_f32 v91, v78, v79
	v_pk_mul_f32 v[74:75], v[74:75], v[76:77] op_sel_hi:[1,0]
	v_pk_mul_f32 v[72:73], v[72:73], v[76:77] op_sel_hi:[1,0]
	v_pk_mul_f32 v[80:81], v[2:3], v[74:75]
	v_lshlrev_b32_e32 v74, 16, v114
	v_and_b32_e32 v75, 0xffff0000, v114
	v_mul_f32_e32 v76, 0xbfb8aa3b, v74
	v_mul_f32_e32 v77, 0xbfb8aa3b, v75
	v_exp_f32_e32 v76, v76
	v_exp_f32_e32 v77, v77
	v_pk_mul_f32 v[82:83], v[0:1], v[72:73]
	global_store_dwordx2 v[88:89], v[90:91], off offset:2048 nt
	v_add_f32_e32 v72, 1.0, v76
	v_add_f32_e32 v73, 1.0, v77
	v_mul_f32_e32 v76, 0xbfb8aa3b, v86
	v_rcp_f32_e32 v72, v72
	v_rcp_f32_e32 v73, v73
	v_exp_f32_e32 v76, v76
	v_mul_f32_e32 v77, 0xbfb8aa3b, v87
	v_exp_f32_e32 v77, v77
	v_pk_mul_f32 v[88:89], v[72:73], v[74:75]
	v_add_f32_e32 v72, 1.0, v76
	v_rcp_f32_e32 v90, v72
	v_add_f32_e32 v72, 1.0, v77
	v_rcp_f32_e32 v91, v72
	ds_read_b128 v[72:75], v158 offset:1536
	ds_read_b128 v[76:79], v158 offset:1552
	v_pk_mul_f32 v[82:83], v[88:89], v[82:83]
	s_waitcnt vmcnt(5)
	v_mov_b64_e32 v[118:119], v[130:131]
	v_pk_mul_f32 v[86:87], v[90:91], v[86:87]
	s_waitcnt lgkmcnt(1)
	v_mov_b32_e32 v88, v72
	s_waitcnt lgkmcnt(0)
	v_mov_b32_e32 v89, v76
	v_mov_b32_e32 v76, v73
	v_pk_add_f32 v[72:73], v[88:89], v[76:77]
	v_mov_b32_e32 v76, v74
	v_mov_b32_e32 v77, v78
	v_mov_b32_e32 v78, v75
	v_pk_add_f32 v[74:75], v[76:77], v[78:79]
	v_cvt_pk_bf16_f32 v82, v82, v83
	v_pk_add_f32 v[72:73], v[72:73], v[74:75]
	v_pk_mul_f32 v[74:75], v[86:87], v[80:81]
	v_add_f32_e32 v72, v72, v73
	v_fmamk_f32 v72, v72, 0x3c000000, v151
	v_rsq_f32_e32 v72, v72
	v_cvt_pk_bf16_f32 v83, v74, v75
	v_lshlrev_b32_e32 v76, 16, v101
	v_and_b32_e32 v77, 0xffff0000, v101
	v_pk_mul_f32 v[68:69], v[68:69], v[72:73] op_sel_hi:[1,0]
	v_pk_mul_f32 v[70:71], v[70:71], v[72:73] op_sel_hi:[1,0]
	v_lshlrev_b32_e32 v72, 16, v100
	v_and_b32_e32 v73, 0xffff0000, v100
	v_mul_f32_e32 v74, 0xbfb8aa3b, v72
	v_mul_f32_e32 v75, 0xbfb8aa3b, v73
	v_exp_f32_e32 v74, v74
	v_exp_f32_e32 v75, v75
	v_mul_f32_e32 v78, 0xbfb8aa3b, v76
	v_mul_f32_e32 v79, 0xbfb8aa3b, v77
	v_exp_f32_e32 v78, v78
	v_exp_f32_e32 v79, v79
	v_add_f32_e32 v74, 1.0, v74
	v_add_f32_e32 v75, 1.0, v75
	v_rcp_f32_e32 v74, v74
	v_rcp_f32_e32 v75, v75
	v_add_f32_e32 v78, 1.0, v78
	v_add_f32_e32 v79, 1.0, v79
	v_rcp_f32_e32 v78, v78
	v_rcp_f32_e32 v79, v79
	v_pk_mul_f32 v[68:69], v[0:1], v[68:69]
	v_pk_mul_f32 v[72:73], v[74:75], v[72:73]
	v_pk_mul_f32 v[70:71], v[2:3], v[70:71]
	v_pk_mul_f32 v[68:69], v[72:73], v[68:69]
	v_pk_mul_f32 v[72:73], v[78:79], v[76:77]
	v_cvt_pk_bf16_f32 v68, v68, v69
	v_pk_mul_f32 v[70:71], v[72:73], v[70:71]
	s_waitcnt vmcnt(4)
	v_mov_b64_e32 v[116:117], v[132:133]
	v_cvt_pk_bf16_f32 v69, v70, v71
	s_waitcnt vmcnt(3)
	v_mov_b64_e32 v[114:115], v[138:139]
	s_waitcnt vmcnt(2)
	v_mov_b64_e32 v[100:101], v[140:141]
	v_mov_b64_e32 v[130:131], v[124:125]
	v_mov_b64_e32 v[132:133], v[122:123]
	v_mov_b64_e32 v[134:135], v[120:121]
	global_store_dwordx2 v[84:85], v[82:83], off nt
	global_store_dwordx2 v[84:85], v[68:69], off offset:2048 nt
	s_cbranch_vccz .LBB0_1068

.LBB0_1040:
	v_mov_b32_e32 v92, s28
	s_nop 5
	v_cndmask_b32_e64 v92, v88, v92, s[12:13]
	v_cndmask_b32_e64 v92, v92, v88, s[14:15]
	v_cndmask_b32_e64 v92, v88, v92, s[8:9]
	v_mov_b32_e32 v88, s28
	v_cndmask_b32_e64 v93, 0, v89, s[14:15]
	v_cndmask_b32_e64 v94, v90, 0, s[16:17]
	v_cndmask_b32_e64 v95, v91, 0, s[18:19]
	v_cndmask_b32_e64 v88, v84, v88, s[12:13]
	v_cndmask_b32_e64 v89, v89, v93, s[8:9]
	v_cndmask_b32_e64 v91, v91, v95, s[8:9]
	v_cndmask_b32_e64 v90, v90, v94, s[8:9]
	v_cndmask_b32_e64 v93, 0, v85, s[14:15]
	v_cndmask_b32_e64 v88, v88, v84, s[14:15]
	v_cndmask_b32_e64 v94, v86, 0, s[16:17]
	v_cndmask_b32_e64 v95, v87, 0, s[18:19]
	v_cndmask_b32_e64 v93, v85, v93, s[10:11]
	v_cndmask_b32_e64 v87, v87, v95, s[10:11]
	v_cndmask_b32_e64 v94, v86, v94, s[10:11]
	v_cndmask_b32_e64 v86, v84, v88, s[10:11]
	v_cvt_pk_bf16_f32 v84, v92, v89
	v_cvt_pk_bf16_f32 v85, v90, v91
	v_cvt_pk_bf16_f32 v86, v86, v93
	v_cvt_pk_bf16_f32 v87, v94, v87
	ds_write2_b64 v163, v[84:85], v[86:87] offset1:4
	s_waitcnt lgkmcnt(0)
	s_barrier
	ds_read_b64_tr_b16 v[84:85], v164 offset:36864
	ds_read_b64_tr_b16 v[86:87], v164 offset:37952
	v_add_u32_e32 v88, 0, v157
	v_add_u32_e32 v167, 0x14000, v88
	ds_read_b128 v[88:91], v165
	ds_read_b128 v[92:95], v167
	ds_read_b128 v[96:99], v165 offset:2304
	ds_read_b64_tr_b16 v[138:139], v164 offset:45568
	ds_read_b64_tr_b16 v[140:141], v164 offset:46656
	s_waitcnt lgkmcnt(4)
	v_mfma_f32_16x16x32_bf16 v[80:83], v[84:87], v[88:91], v[80:83]
	ds_read_b128 v[88:91], v167 offset:64
	ds_read_b128 v[168:171], v165 offset:4608
	s_waitcnt lgkmcnt(5)
	v_pk_mul_f32 v[52:53], v[52:53], v[92:93]
	s_waitcnt lgkmcnt(4)
	v_mfma_f32_16x16x32_bf16 v[76:79], v[84:87], v[96:99], v[76:79]
	v_mul_f32_e64 v54, v54, v94
	v_mul_f32_e64 v55, v55, v95
	ds_read_b128 v[92:95], v165 offset:6912
	ds_read_b128 v[96:99], v165 offset:4672
	s_waitcnt lgkmcnt(3)
	v_pk_mul_f32 v[56:57], v[56:57], v[88:89]
	s_waitcnt lgkmcnt(2)
	v_mfma_f32_16x16x32_bf16 v[72:75], v[84:87], v[168:171], v[72:75]
	ds_read_b64_tr_b16 v[170:171], v166 offset:28224
	ds_read_b64_tr_b16 v[168:169], v166 offset:27648
	ds_read_b128 v[172:175], v165 offset:6976
	v_pk_mul_f32 v[58:59], v[58:59], v[90:91]
	s_waitcnt lgkmcnt(4)
	v_mfma_f32_16x16x32_bf16 v[68:71], v[84:87], v[92:95], v[68:71]
	ds_read_b64_tr_b16 v[94:95], v166 offset:28256
	ds_read_b64_tr_b16 v[92:93], v166 offset:27680
	ds_read_b64_tr_b16 v[176:177], v166 offset:27712
	ds_read_b64_tr_b16 v[182:183], v166 offset:27744
	ds_read_b64_tr_b16 v[178:179], v166 offset:28288
	ds_read_b64_tr_b16 v[184:185], v166 offset:28320
	ds_read_b128 v[88:91], v167 offset:192
	s_waitcnt lgkmcnt(8)
	v_mfma_f32_16x16x32_bf16 v[52:55], v[168:171], v[84:87], v[52:55]
	ds_read_b128 v[168:171], v167 offset:128
	s_waitcnt lgkmcnt(0)
	v_pk_mul_f32 v[60:61], v[60:61], v[168:169]
	v_pk_mul_f32 v[62:63], v[62:63], v[170:171]
	v_mfma_f32_16x16x32_bf16 v[56:59], v[92:95], v[84:87], v[56:59]
	s_nop 0
	v_mfma_f32_16x16x32_bf16 v[92:95], v[176:179], v[84:87], v[60:63]
	s_nop 2
	v_mul_f32_e64 v60, v64, v88
	v_mul_f32_e64 v61, v65, v89
	v_pk_mul_f32 v[62:63], v[66:67], v[90:91]
	v_mfma_f32_16x16x32_bf16 v[72:75], v[138:141], v[96:99], v[72:75]
	s_nop 0
	v_mfma_f32_16x16x32_bf16 v[84:87], v[182:185], v[84:87], v[60:63]
	s_nop 2
	ds_read_b64_tr_b16 v[60:61], v166 offset:32256
	ds_read_b64_tr_b16 v[62:63], v166 offset:32832
	ds_read_b64_tr_b16 v[90:91], v166 offset:32864
	ds_read_b64_tr_b16 v[88:89], v166 offset:32288
	ds_read_b64_tr_b16 v[96:97], v166 offset:32320
	ds_read_b64_tr_b16 v[168:169], v166 offset:32352
	ds_read_b64_tr_b16 v[98:99], v166 offset:32896
	ds_read_b64_tr_b16 v[170:171], v166 offset:32928
	s_waitcnt lgkmcnt(6)
	v_mfma_f32_16x16x32_bf16 v[64:67], v[60:63], v[138:141], v[52:55]
	s_waitcnt lgkmcnt(4)
	v_mfma_f32_16x16x32_bf16 v[60:63], v[88:91], v[138:141], v[56:59]
	v_add_u32_e32 v88, v155, v149
	s_waitcnt lgkmcnt(1)
	v_mfma_f32_16x16x32_bf16 v[52:55], v[96:99], v[138:141], v[92:95]
	s_waitcnt lgkmcnt(0)
	v_mfma_f32_16x16x32_bf16 v[56:59], v[168:171], v[138:141], v[84:87]
	v_add_u32_e32 v168, 0xd000, v88
	s_nop 1
	v_cvt_pk_bf16_f32 v84, v64, v65
	v_cvt_pk_bf16_f32 v85, v66, v67
	v_cvt_pk_bf16_f32 v86, v60, v61
	v_cvt_pk_bf16_f32 v87, v62, v63
	ds_write2_b64 v168, v[84:85], v[86:87] offset0:128 offset1:132
	v_cvt_pk_bf16_f32 v84, v52, v53
	v_cvt_pk_bf16_f32 v85, v54, v55
	v_cvt_pk_bf16_f32 v86, v56, v57
	v_cvt_pk_bf16_f32 v87, v58, v59
	ds_write2_b64 v168, v[84:85], v[86:87] offset0:136 offset1:140
	v_mul_f32_e32 v84, v81, v81
	v_mul_f32_e32 v85, v83, v83
	v_fmac_f32_e32 v84, v80, v80
	v_fmac_f32_e32 v85, v82, v82
	v_add_f32_e32 v84, v84, v85
	v_mov_b32_e32 v85, v84
	v_mfma_f32_16x16x32_bf16 v[68:71], v[138:141], v[172:175], v[68:71]
	s_nop 0
	v_permlane16_swap_b32_e32 v84, v85
	v_add_f32_e32 v84, v84, v85
	v_mov_b32_e32 v85, v84
	s_nop 1
	v_permlane32_swap_b32_e32 v84, v85
	s_and_saveexec_b64 s[30:31], s[20:21]
	v_add_f32_e32 v84, v84, v85
	ds_write_b32 v159, v84
	s_or_b64 exec, exec, s[30:31]
	v_mul_f32_e32 v84, v77, v77
	v_mul_f32_e32 v85, v79, v79
	v_fmac_f32_e32 v84, v76, v76
	v_fmac_f32_e32 v85, v78, v78
	v_add_f32_e32 v84, v84, v85
	v_mov_b32_e32 v85, v84
	s_nop 1
	v_permlane16_swap_b32_e32 v84, v85
	v_add_f32_e32 v84, v84, v85
	v_mov_b32_e32 v85, v84
	s_nop 1
	v_permlane32_swap_b32_e32 v84, v85
	s_and_saveexec_b64 s[30:31], s[20:21]
	v_add_f32_e32 v84, v84, v85
	ds_write_b32 v159, v84 offset:512
	s_or_b64 exec, exec, s[30:31]
	v_mul_f32_e32 v84, v73, v73
	v_mul_f32_e32 v85, v75, v75
	v_fmac_f32_e32 v84, v72, v72
	v_fmac_f32_e32 v85, v74, v74
	v_add_f32_e32 v84, v84, v85
	v_mov_b32_e32 v85, v84
	s_nop 1
	v_permlane16_swap_b32_e32 v84, v85
	v_add_f32_e32 v84, v84, v85
	v_mov_b32_e32 v85, v84
	s_nop 1
	v_permlane32_swap_b32_e32 v84, v85
	s_and_saveexec_b64 s[30:31], s[20:21]
	v_add_f32_e32 v84, v84, v85
	ds_write_b32 v159, v84 offset:1024
	s_or_b64 exec, exec, s[30:31]
	v_mul_f32_e32 v84, v69, v69
	v_mul_f32_e32 v85, v71, v71
	v_fmac_f32_e32 v84, v68, v68
	v_fmac_f32_e32 v85, v70, v70
	v_add_f32_e32 v84, v84, v85
	v_mov_b32_e32 v85, v84
	s_nop 1
	v_permlane16_swap_b32_e32 v84, v85
	v_add_f32_e32 v84, v84, v85
	v_mov_b32_e32 v85, v84
	s_nop 1
	v_permlane32_swap_b32_e32 v84, v85
	s_and_saveexec_b64 s[30:31], s[20:21]
	v_add_f32_e32 v84, v84, v85
	ds_write_b32 v159, v84 offset:1536
	s_or_b64 exec, exec, s[30:31]
	s_waitcnt lgkmcnt(0)
	s_barrier
	ds_read_b128 v[84:87], v158
	ds_read_b128 v[88:91], v158 offset:16
	s_waitcnt lgkmcnt(1)
	v_mov_b32_e32 v92, v84
	s_waitcnt lgkmcnt(0)
	v_mov_b32_e32 v93, v88
	v_mov_b32_e32 v88, v85
	v_pk_add_f32 v[84:85], v[92:93], v[88:89]
	v_mov_b32_e32 v88, v86
	v_mov_b32_e32 v89, v90
	v_mov_b32_e32 v90, v87
	v_pk_add_f32 v[86:87], v[88:89], v[90:91]
	v_lshlrev_b32_e32 v88, 16, v135
	v_pk_add_f32 v[84:85], v[84:85], v[86:87]
	v_and_b32_e32 v89, 0xffff0000, v135
	v_add_f32_e32 v84, v84, v85
	v_fmamk_f32 v84, v84, 0x3c000000, v151
	v_rsq_f32_e32 v84, v84
	v_mul_f32_e32 v90, 0xbfb8aa3b, v88
	v_mul_f32_e32 v91, 0xbfb8aa3b, v89
	v_exp_f32_e32 v90, v90
	v_pk_mul_f32 v[80:81], v[80:81], v[84:85] op_sel_hi:[1,0]
	v_pk_mul_f32 v[82:83], v[82:83], v[84:85] op_sel_hi:[1,0]
	v_lshlrev_b32_e32 v84, 16, v134
	v_and_b32_e32 v85, 0xffff0000, v134
	v_mul_f32_e32 v86, 0xbfb8aa3b, v84
	v_mul_f32_e32 v87, 0xbfb8aa3b, v85
	v_exp_f32_e32 v86, v86
	v_exp_f32_e32 v87, v87
	v_exp_f32_e32 v91, v91
	v_add_f32_e32 v90, 1.0, v90
	v_add_f32_e32 v86, 1.0, v86
	v_add_f32_e32 v87, 1.0, v87
	v_rcp_f32_e32 v86, v86
	v_rcp_f32_e32 v87, v87
	v_add_f32_e32 v91, 1.0, v91
	v_rcp_f32_e32 v90, v90
	v_rcp_f32_e32 v91, v91
	v_pk_mul_f32 v[80:81], v[0:1], v[80:81]
	v_pk_mul_f32 v[84:85], v[86:87], v[84:85]
	v_pk_mul_f32 v[82:83], v[2:3], v[82:83]
	v_pk_mul_f32 v[80:81], v[84:85], v[80:81]
	v_lshl_add_u64 v[134:135], s[48:49], 0, v[112:113]
	v_cvt_pk_bf16_f32 v92, v80, v81
	v_pk_mul_f32 v[80:81], v[90:91], v[88:89]
	v_add_co_u32_e32 v88, vcc, s2, v134
	v_pk_mul_f32 v[80:81], v[80:81], v[82:83]
	s_nop 0
	v_addc_co_u32_e32 v89, vcc, 0, v135, vcc
	v_cvt_pk_bf16_f32 v93, v80, v81
	ds_read_b128 v[80:83], v158 offset:512
	ds_read_b128 v[84:87], v158 offset:528
	s_waitcnt lgkmcnt(1)
	v_mov_b32_e32 v90, v80
	s_waitcnt lgkmcnt(0)
	v_mov_b32_e32 v91, v84
	v_mov_b32_e32 v84, v81
	v_pk_add_f32 v[80:81], v[90:91], v[84:85]
	v_mov_b32_e32 v84, v82
	v_mov_b32_e32 v85, v86
	v_mov_b32_e32 v86, v83
	v_pk_add_f32 v[82:83], v[84:85], v[86:87]
	v_add_co_u32_e32 v84, vcc, s3, v134
	v_pk_add_f32 v[80:81], v[80:81], v[82:83]
	s_nop 0
	v_addc_co_u32_e32 v85, vcc, 0, v135, vcc
	v_add_f32_e32 v80, v80, v81
	v_fmamk_f32 v80, v80, 0x3c000000, v151
	v_rsq_f32_e32 v80, v80
	global_store_dwordx2 v[84:85], v[92:93], off offset:-4096 nt
	v_lshlrev_b32_e32 v92, 16, v133
	v_and_b32_e32 v93, 0xffff0000, v133
	v_pk_mul_f32 v[78:79], v[78:79], v[80:81] op_sel_hi:[1,0]
	v_pk_mul_f32 v[76:77], v[76:77], v[80:81] op_sel_hi:[1,0]
	v_pk_mul_f32 v[86:87], v[2:3], v[78:79]
	v_lshlrev_b32_e32 v78, 16, v132
	v_and_b32_e32 v79, 0xffff0000, v132
	v_mul_f32_e32 v80, 0xbfb8aa3b, v78
	v_mul_f32_e32 v81, 0xbfb8aa3b, v79
	v_exp_f32_e32 v80, v80
	v_exp_f32_e32 v81, v81
	v_pk_mul_f32 v[90:91], v[0:1], v[76:77]
	v_add_f32_e32 v76, 1.0, v80
	v_add_f32_e32 v77, 1.0, v81
	v_mul_f32_e32 v80, 0xbfb8aa3b, v92
	v_rcp_f32_e32 v76, v76
	v_rcp_f32_e32 v77, v77
	v_exp_f32_e32 v80, v80
	v_mul_f32_e32 v81, 0xbfb8aa3b, v93
	v_exp_f32_e32 v81, v81
	v_pk_mul_f32 v[94:95], v[76:77], v[78:79]
	v_add_f32_e32 v76, 1.0, v80
	v_rcp_f32_e32 v96, v76
	v_add_f32_e32 v76, 1.0, v81
	v_rcp_f32_e32 v97, v76
	ds_read_b128 v[76:79], v158 offset:1024
	ds_read_b128 v[80:83], v158 offset:1040
	v_pk_mul_f32 v[90:91], v[94:95], v[90:91]
	v_pk_mul_f32 v[92:93], v[96:97], v[92:93]
	s_waitcnt lgkmcnt(1)
	v_mov_b32_e32 v94, v76
	s_waitcnt lgkmcnt(0)
	v_mov_b32_e32 v95, v80
	v_mov_b32_e32 v80, v77
	v_pk_add_f32 v[76:77], v[94:95], v[80:81]
	v_mov_b32_e32 v80, v78
	v_mov_b32_e32 v81, v82
	v_mov_b32_e32 v82, v79
	v_pk_add_f32 v[78:79], v[80:81], v[82:83]
	v_cvt_pk_bf16_f32 v90, v90, v91
	v_pk_add_f32 v[76:77], v[76:77], v[78:79]
	v_pk_mul_f32 v[78:79], v[92:93], v[86:87]
	v_add_f32_e32 v76, v76, v77
	v_fmamk_f32 v76, v76, 0x3c000000, v151
	v_rsq_f32_e32 v76, v76
	v_lshlrev_b32_e32 v86, 16, v131
	v_and_b32_e32 v87, 0xffff0000, v131
	v_cvt_pk_bf16_f32 v91, v78, v79
	v_pk_mul_f32 v[74:75], v[74:75], v[76:77] op_sel_hi:[1,0]
	v_pk_mul_f32 v[72:73], v[72:73], v[76:77] op_sel_hi:[1,0]
	v_pk_mul_f32 v[80:81], v[2:3], v[74:75]
	v_lshlrev_b32_e32 v74, 16, v130
	v_and_b32_e32 v75, 0xffff0000, v130
	v_mul_f32_e32 v76, 0xbfb8aa3b, v74
	v_mul_f32_e32 v77, 0xbfb8aa3b, v75
	v_exp_f32_e32 v76, v76
	v_exp_f32_e32 v77, v77
	v_pk_mul_f32 v[82:83], v[0:1], v[72:73]
	global_store_dwordx2 v[88:89], v[90:91], off offset:2048 nt
	v_add_f32_e32 v72, 1.0, v76
	v_add_f32_e32 v73, 1.0, v77
	v_mul_f32_e32 v76, 0xbfb8aa3b, v86
	v_rcp_f32_e32 v72, v72
	v_rcp_f32_e32 v73, v73
	v_exp_f32_e32 v76, v76
	v_mul_f32_e32 v77, 0xbfb8aa3b, v87
	v_exp_f32_e32 v77, v77
	v_pk_mul_f32 v[88:89], v[72:73], v[74:75]
	v_add_f32_e32 v72, 1.0, v76
	v_rcp_f32_e32 v90, v72
	v_add_f32_e32 v72, 1.0, v77
	v_rcp_f32_e32 v91, v72
	ds_read_b128 v[72:75], v158 offset:1536
	ds_read_b128 v[76:79], v158 offset:1552
	v_pk_mul_f32 v[82:83], v[88:89], v[82:83]
	v_pk_mul_f32 v[86:87], v[90:91], v[86:87]
	s_waitcnt lgkmcnt(1)
	v_mov_b32_e32 v88, v72
	s_waitcnt lgkmcnt(0)
	v_mov_b32_e32 v89, v76
	v_mov_b32_e32 v76, v73
	v_pk_add_f32 v[72:73], v[88:89], v[76:77]
	v_mov_b32_e32 v76, v74
	v_mov_b32_e32 v77, v78
	v_mov_b32_e32 v78, v75
	v_pk_add_f32 v[74:75], v[76:77], v[78:79]
	v_cvt_pk_bf16_f32 v82, v82, v83
	v_pk_add_f32 v[72:73], v[72:73], v[74:75]
	v_pk_mul_f32 v[74:75], v[86:87], v[80:81]
	v_add_f32_e32 v72, v72, v73
	v_fmamk_f32 v72, v72, 0x3c000000, v151
	v_rsq_f32_e32 v72, v72
	v_cvt_pk_bf16_f32 v83, v74, v75
	v_lshlrev_b32_e32 v76, 16, v129
	v_and_b32_e32 v77, 0xffff0000, v129
	v_pk_mul_f32 v[68:69], v[68:69], v[72:73] op_sel_hi:[1,0]
	v_pk_mul_f32 v[70:71], v[70:71], v[72:73] op_sel_hi:[1,0]
	v_lshlrev_b32_e32 v72, 16, v128
	v_and_b32_e32 v73, 0xffff0000, v128
	v_mul_f32_e32 v74, 0xbfb8aa3b, v72
	v_mul_f32_e32 v75, 0xbfb8aa3b, v73
	v_exp_f32_e32 v74, v74
	v_exp_f32_e32 v75, v75
	v_mul_f32_e32 v78, 0xbfb8aa3b, v76
	v_mul_f32_e32 v79, 0xbfb8aa3b, v77
	v_exp_f32_e32 v78, v78
	v_exp_f32_e32 v79, v79
	v_add_f32_e32 v74, 1.0, v74
	v_add_f32_e32 v75, 1.0, v75
	v_rcp_f32_e32 v74, v74
	v_rcp_f32_e32 v75, v75
	v_add_f32_e32 v78, 1.0, v78
	v_add_f32_e32 v79, 1.0, v79
	v_rcp_f32_e32 v78, v78
	v_rcp_f32_e32 v79, v79
	v_pk_mul_f32 v[68:69], v[0:1], v[68:69]
	v_pk_mul_f32 v[72:73], v[74:75], v[72:73]
	v_pk_mul_f32 v[70:71], v[2:3], v[70:71]
	v_pk_mul_f32 v[68:69], v[72:73], v[68:69]
	v_pk_mul_f32 v[72:73], v[78:79], v[76:77]
	v_cvt_pk_bf16_f32 v68, v68, v69
	v_pk_mul_f32 v[70:71], v[72:73], v[70:71]
	global_store_dwordx2 v[84:85], v[82:83], off nt
	v_cvt_pk_bf16_f32 v69, v70, v71
	global_store_dwordx2 v[84:85], v[68:69], off offset:2048 nt
	s_waitcnt vmcnt(13)
	ds_write_b128 v144, v[24:27]
	s_waitcnt vmcnt(11)
	ds_write_b128 v144, v[36:39] offset:18432
	s_waitcnt vmcnt(10)
	ds_write_b128 v144, v[40:43] offset:27648
	ds_write_b128 v160, v[32:35]
	s_and_saveexec_b64 s[30:31], s[6:7]
	ds_write_b32 v145, v143
	s_or_b64 exec, exec, s[30:31]
	s_andn2_b64 vcc, exec, s[44:45]
	s_waitcnt vmcnt(7)
	v_mov_b64_e32 v[130:131], v[118:119]
	s_waitcnt vmcnt(6)
	v_mov_b64_e32 v[132:133], v[116:117]
	s_waitcnt vmcnt(5)
	v_mov_b64_e32 v[138:139], v[114:115]
	s_waitcnt vmcnt(4)
	v_mov_b64_e32 v[140:141], v[100:101]
	ds_write_b128 v146, v[44:47] offset:36864
	ds_write_b128 v147, v[48:51] offset:36864
	s_cbranch_vccnz .LBB0_1054
	v_add_co_u32_e32 v24, vcc, 0x45a18000, v136
	v_mov_b32_e32 v143, 0
	s_nop 0
	v_addc_co_u32_e32 v25, vcc, 0, v137, vcc
	v_add_co_u32_e32 v32, vcc, 0x45a1a000, v136
	s_nop 1
	v_addc_co_u32_e32 v33, vcc, 0, v137, vcc
	v_add_co_u32_e32 v36, vcc, 0x45a1c000, v136
	global_load_dwordx4 v[24:27], v[24:25], off offset:768
	s_nop 0
	global_load_dwordx4 v[32:35], v[32:33], off offset:768
	v_addc_co_u32_e32 v37, vcc, 0, v137, vcc
	v_add_co_u32_e32 v40, vcc, 0x45a1e000, v136
	s_nop 1
	v_addc_co_u32_e32 v41, vcc, 0, v137, vcc
	global_load_dwordx4 v[36:39], v[36:37], off offset:768
	s_nop 0
	global_load_dwordx4 v[40:43], v[40:41], off offset:768
	s_and_saveexec_b64 s[30:31], s[6:7]
	s_cbranch_execz .LBB0_1053
	v_lshl_add_u64 v[44:45], s[48:49], 0, v[110:111]
	v_add_co_u32_e32 v44, vcc, 0x45a20000, v44
	s_nop 1
	v_addc_co_u32_e32 v45, vcc, 0, v45, vcc
	global_load_dword v143, v[44:45], off offset:768

.LBB0_1226:
	s_waitcnt lgkmcnt(0)
	s_barrier
	s_andn2_b64 vcc, exec, s[22:23]
	s_cbranch_vccnz .LBB0_1070
	ds_read2st64_b32 v[74:75], v238 offset1:1
	ds_read2st64_b32 v[98:99], v238 offset0:2 offset1:3
	ds_read2st64_b32 v[100:101], v238 offset0:4 offset1:5
	ds_read2st64_b32 v[102:103], v238 offset0:6 offset1:7
	ds_read2st64_b32 v[104:105], v238 offset0:8 offset1:9
	ds_read2st64_b32 v[106:107], v238 offset0:10 offset1:11
	ds_read2st64_b32 v[108:109], v238 offset0:12 offset1:13
	ds_read2st64_b32 v[110:111], v238 offset0:14 offset1:15
	ds_read2st64_b32 v[112:113], v238 offset0:16 offset1:17
	ds_read2st64_b32 v[114:115], v238 offset0:18 offset1:19
	ds_read2st64_b32 v[116:117], v238 offset0:20 offset1:21
	ds_read2st64_b32 v[118:119], v238 offset0:22 offset1:23
	ds_read2st64_b32 v[120:121], v238 offset0:24 offset1:25
	ds_read2st64_b32 v[122:123], v238 offset0:26 offset1:27
	ds_read2st64_b32 v[124:125], v238 offset0:28 offset1:29
	ds_read2st64_b32 v[126:127], v238 offset0:30 offset1:31
	ds_read2st64_b32 v[128:129], v238 offset0:32 offset1:33
	ds_read2st64_b32 v[130:131], v238 offset0:34 offset1:35
	ds_read2st64_b32 v[132:133], v238 offset0:36 offset1:37
	ds_read2st64_b32 v[134:135], v238 offset0:38 offset1:39
	ds_read2st64_b32 v[92:93], v238 offset0:40 offset1:41
	ds_read2st64_b32 v[96:97], v238 offset0:42 offset1:43
	ds_read2st64_b32 v[86:87], v238 offset0:44 offset1:45
	ds_read2st64_b32 v[88:89], v238 offset0:46 offset1:47
	ds_read2st64_b32 v[78:79], v238 offset0:56 offset1:57
	ds_read2st64_b32 v[80:81], v238 offset0:58 offset1:59
	ds_read2st64_b32 v[76:77], v238 offset0:60 offset1:61
	ds_read2st64_b32 v[66:67], v238 offset0:62 offset1:63
	ds_read2st64_b32 v[90:91], v238 offset0:48 offset1:49
	ds_read2st64_b32 v[94:95], v238 offset0:50 offset1:51
	ds_read2st64_b32 v[82:83], v238 offset0:52 offset1:53
	ds_read2st64_b32 v[84:85], v238 offset0:54 offset1:55
	s_waitcnt lgkmcnt(14)
	v_pk_mul_f32 v[74:75], v[188:189], v[74:75]
	v_pk_mul_f32 v[98:99], v[188:189], v[98:99]
	v_pk_fma_f32 v[74:75], v[50:51], v[0:1], v[74:75] op_sel_hi:[1,0,1] neg_lo:[0,0,1] neg_hi:[0,0,1]
	v_pk_fma_f32 v[52:53], v[52:53], v[0:1], v[98:99] op_sel_hi:[1,0,1] neg_lo:[0,0,1] neg_hi:[0,0,1]
	v_mul_f32_e32 v50, v75, v75
	v_pk_fma_f32 v[50:51], v[74:75], v[74:75], v[50:51] op_sel_hi:[1,1,0]
	v_mul_f32_e32 v98, v53, v53
	v_pk_fma_f32 v[50:51], v[52:53], v[52:53], v[50:51]
	v_or_b32_e32 v72, s45, v228
	v_pk_add_f32 v[98:99], v[50:51], v[98:99] op_sel_hi:[1,0]
	v_pk_mul_f32 v[50:51], v[188:189], v[102:103]
	s_waitcnt lgkmcnt(4)
	v_pk_mul_f32 v[66:67], v[188:189], v[66:67]
	v_pk_fma_f32 v[50:51], v[56:57], v[0:1], v[50:51] op_sel_hi:[1,0,1] neg_lo:[0,0,1] neg_hi:[0,0,1]
	v_pk_mul_f32 v[56:57], v[188:189], v[100:101]
	v_lshl_add_u64 v[70:71], v[184:185], 2, s[10:11]
	v_pk_fma_f32 v[56:57], v[54:55], v[0:1], v[56:57] op_sel_hi:[1,0,1] neg_lo:[0,0,1] neg_hi:[0,0,1]
	v_pk_fma_f32 v[16:17], v[16:17], v[0:1], v[66:67] op_sel_hi:[1,0,1] neg_lo:[0,0,1] neg_hi:[0,0,1]
	v_pk_fma_f32 v[54:55], v[56:57], v[56:57], v[98:99]
	v_mul_f32_e32 v98, v57, v57
	v_pk_add_f32 v[54:55], v[54:55], v[98:99] op_sel_hi:[1,0]
	v_mul_f32_e32 v98, v51, v51
	v_pk_fma_f32 v[54:55], v[50:51], v[50:51], v[54:55]
	global_load_dwordx4 v[66:69], v[70:71], off
	v_pk_add_f32 v[98:99], v[54:55], v[98:99] op_sel_hi:[1,0]
	v_pk_mul_f32 v[54:55], v[188:189], v[106:107]
	v_ashrrev_i32_e32 v73, 31, v72
	v_pk_fma_f32 v[54:55], v[60:61], v[0:1], v[54:55] op_sel_hi:[1,0,1] neg_lo:[0,0,1] neg_hi:[0,0,1]
	v_pk_mul_f32 v[60:61], v[188:189], v[104:105]
	s_lshl_b32 s12, s44, 1
	v_pk_fma_f32 v[60:61], v[58:59], v[0:1], v[60:61] op_sel_hi:[1,0,1] neg_lo:[0,0,1] neg_hi:[0,0,1]
	s_nop 0
	v_pk_fma_f32 v[58:59], v[60:61], v[60:61], v[98:99]
	v_mul_f32_e32 v98, v61, v61
	v_pk_add_f32 v[58:59], v[58:59], v[98:99] op_sel_hi:[1,0]
	v_mul_f32_e32 v98, v55, v55
	v_pk_fma_f32 v[58:59], v[54:55], v[54:55], v[58:59]
	s_nop 0
	v_pk_add_f32 v[98:99], v[58:59], v[98:99] op_sel_hi:[1,0]
	v_pk_mul_f32 v[58:59], v[188:189], v[110:111]
	s_nop 0
	v_pk_fma_f32 v[58:59], v[64:65], v[0:1], v[58:59] op_sel_hi:[1,0,1] neg_lo:[0,0,1] neg_hi:[0,0,1]
	v_pk_mul_f32 v[64:65], v[188:189], v[108:109]
	s_nop 0
	v_pk_fma_f32 v[62:63], v[62:63], v[0:1], v[64:65] op_sel_hi:[1,0,1] neg_lo:[0,0,1] neg_hi:[0,0,1]
	s_nop 0
	v_pk_fma_f32 v[64:65], v[62:63], v[62:63], v[98:99]
	v_mul_f32_e32 v98, v63, v63
	v_pk_add_f32 v[64:65], v[64:65], v[98:99] op_sel_hi:[1,0]
	v_mul_f32_e32 v98, v59, v59
	v_pk_fma_f32 v[64:65], v[58:59], v[58:59], v[64:65]
	s_nop 0
	v_pk_add_f32 v[98:99], v[64:65], v[98:99] op_sel_hi:[1,0]
	v_pk_mul_f32 v[64:65], v[188:189], v[114:115]
	s_nop 0
	v_pk_fma_f32 v[36:37], v[36:37], v[0:1], v[64:65] op_sel_hi:[1,0,1] neg_lo:[0,0,1] neg_hi:[0,0,1]
	v_pk_mul_f32 v[64:65], v[188:189], v[112:113]
	s_nop 0
	v_pk_fma_f32 v[64:65], v[34:35], v[0:1], v[64:65] op_sel_hi:[1,0,1] neg_lo:[0,0,1] neg_hi:[0,0,1]
	s_nop 0
	v_pk_fma_f32 v[34:35], v[64:65], v[64:65], v[98:99]
	v_mul_f32_e32 v98, v65, v65
	v_pk_add_f32 v[34:35], v[34:35], v[98:99] op_sel_hi:[1,0]
	v_mul_f32_e32 v98, v37, v37
	v_pk_fma_f32 v[34:35], v[36:37], v[36:37], v[34:35]
	s_nop 0
	v_pk_add_f32 v[98:99], v[34:35], v[98:99] op_sel_hi:[1,0]
	v_pk_mul_f32 v[34:35], v[188:189], v[118:119]
	s_nop 0
	v_pk_fma_f32 v[34:35], v[40:41], v[0:1], v[34:35] op_sel_hi:[1,0,1] neg_lo:[0,0,1] neg_hi:[0,0,1]
	v_pk_mul_f32 v[40:41], v[188:189], v[116:117]
	s_nop 0
	v_pk_fma_f32 v[40:41], v[38:39], v[0:1], v[40:41] op_sel_hi:[1,0,1] neg_lo:[0,0,1] neg_hi:[0,0,1]
	s_nop 0
	v_pk_fma_f32 v[38:39], v[40:41], v[40:41], v[98:99]
	v_mul_f32_e32 v98, v41, v41
	v_pk_add_f32 v[38:39], v[38:39], v[98:99] op_sel_hi:[1,0]
	v_mul_f32_e32 v98, v35, v35
	v_pk_fma_f32 v[38:39], v[34:35], v[34:35], v[38:39]
	s_nop 0
	v_pk_add_f32 v[98:99], v[38:39], v[98:99] op_sel_hi:[1,0]
	v_pk_mul_f32 v[38:39], v[188:189], v[122:123]
	s_nop 0
	v_pk_fma_f32 v[38:39], v[44:45], v[0:1], v[38:39] op_sel_hi:[1,0,1] neg_lo:[0,0,1] neg_hi:[0,0,1]
	v_pk_mul_f32 v[44:45], v[188:189], v[120:121]
	s_nop 0
	v_pk_fma_f32 v[44:45], v[42:43], v[0:1], v[44:45] op_sel_hi:[1,0,1] neg_lo:[0,0,1] neg_hi:[0,0,1]
	s_nop 0
	v_pk_fma_f32 v[42:43], v[44:45], v[44:45], v[98:99]
	v_mul_f32_e32 v98, v45, v45
	v_pk_add_f32 v[42:43], v[42:43], v[98:99] op_sel_hi:[1,0]
	v_mul_f32_e32 v98, v39, v39
	v_pk_fma_f32 v[42:43], v[38:39], v[38:39], v[42:43]
	s_nop 0
	v_pk_add_f32 v[98:99], v[42:43], v[98:99] op_sel_hi:[1,0]
	v_pk_mul_f32 v[42:43], v[188:189], v[126:127]
	s_nop 0
	v_pk_fma_f32 v[42:43], v[48:49], v[0:1], v[42:43] op_sel_hi:[1,0,1] neg_lo:[0,0,1] neg_hi:[0,0,1]
	v_pk_mul_f32 v[48:49], v[188:189], v[124:125]
	s_nop 0
	v_pk_fma_f32 v[46:47], v[46:47], v[0:1], v[48:49] op_sel_hi:[1,0,1] neg_lo:[0,0,1] neg_hi:[0,0,1]
	s_nop 0
	v_pk_fma_f32 v[48:49], v[46:47], v[46:47], v[98:99]
	v_mul_f32_e32 v98, v47, v47
	v_pk_add_f32 v[48:49], v[48:49], v[98:99] op_sel_hi:[1,0]
	v_mul_f32_e32 v98, v43, v43
	v_pk_fma_f32 v[48:49], v[42:43], v[42:43], v[48:49]
	s_nop 0
	v_pk_add_f32 v[48:49], v[48:49], v[98:99] op_sel_hi:[1,0]
	v_pk_mul_f32 v[98:99], v[188:189], v[130:131]
	s_nop 0
	v_pk_fma_f32 v[20:21], v[20:21], v[0:1], v[98:99] op_sel_hi:[1,0,1] neg_lo:[0,0,1] neg_hi:[0,0,1]
	v_pk_mul_f32 v[98:99], v[188:189], v[128:129]
	s_nop 0
	v_pk_fma_f32 v[18:19], v[18:19], v[0:1], v[98:99] op_sel_hi:[1,0,1] neg_lo:[0,0,1] neg_hi:[0,0,1]
	s_nop 0
	v_pk_fma_f32 v[48:49], v[18:19], v[18:19], v[48:49]
	v_mul_f32_e32 v98, v19, v19
	v_pk_add_f32 v[48:49], v[48:49], v[98:99] op_sel_hi:[1,0]
	v_mul_f32_e32 v98, v21, v21
	v_pk_fma_f32 v[48:49], v[20:21], v[20:21], v[48:49]
	s_nop 0
	v_pk_add_f32 v[98:99], v[48:49], v[98:99] op_sel_hi:[1,0]
	v_pk_mul_f32 v[48:49], v[188:189], v[134:135]
	s_nop 0
	v_pk_fma_f32 v[24:25], v[24:25], v[0:1], v[48:49] op_sel_hi:[1,0,1] neg_lo:[0,0,1] neg_hi:[0,0,1]
	v_pk_mul_f32 v[48:49], v[188:189], v[132:133]
	s_nop 0
	v_pk_fma_f32 v[48:49], v[22:23], v[0:1], v[48:49] op_sel_hi:[1,0,1] neg_lo:[0,0,1] neg_hi:[0,0,1]
	s_nop 0
	v_pk_fma_f32 v[22:23], v[48:49], v[48:49], v[98:99]
	v_mul_f32_e32 v98, v49, v49
	v_pk_add_f32 v[22:23], v[22:23], v[98:99] op_sel_hi:[1,0]
	v_mul_f32_e32 v98, v25, v25
	v_pk_fma_f32 v[22:23], v[24:25], v[24:25], v[22:23]
	s_nop 0
	v_pk_add_f32 v[98:99], v[22:23], v[98:99] op_sel_hi:[1,0]
	v_pk_mul_f32 v[22:23], v[188:189], v[96:97]
	s_nop 0
	v_pk_fma_f32 v[22:23], v[28:29], v[0:1], v[22:23] op_sel_hi:[1,0,1] neg_lo:[0,0,1] neg_hi:[0,0,1]
	v_pk_mul_f32 v[28:29], v[188:189], v[92:93]
	s_nop 0
	v_pk_fma_f32 v[28:29], v[26:27], v[0:1], v[28:29] op_sel_hi:[1,0,1] neg_lo:[0,0,1] neg_hi:[0,0,1]
	s_nop 0
	v_pk_fma_f32 v[26:27], v[28:29], v[28:29], v[98:99]
	v_mul_f32_e32 v92, v29, v29
	v_pk_add_f32 v[26:27], v[26:27], v[92:93] op_sel_hi:[1,0]
	v_mul_f32_e32 v92, v23, v23
	v_pk_fma_f32 v[26:27], v[22:23], v[22:23], v[26:27]
	s_nop 0
	v_pk_add_f32 v[92:93], v[26:27], v[92:93] op_sel_hi:[1,0]
	v_pk_mul_f32 v[26:27], v[188:189], v[88:89]
	s_nop 0
	v_pk_fma_f32 v[26:27], v[32:33], v[0:1], v[26:27] op_sel_hi:[1,0,1] neg_lo:[0,0,1] neg_hi:[0,0,1]
	v_pk_mul_f32 v[32:33], v[188:189], v[86:87]
	s_nop 0
	v_pk_fma_f32 v[30:31], v[30:31], v[0:1], v[32:33] op_sel_hi:[1,0,1] neg_lo:[0,0,1] neg_hi:[0,0,1]
	s_nop 0
	v_pk_fma_f32 v[32:33], v[30:31], v[30:31], v[92:93]
	v_mul_f32_e32 v86, v31, v31
	v_pk_add_f32 v[32:33], v[32:33], v[86:87] op_sel_hi:[1,0]
	v_mul_f32_e32 v86, v27, v27
	v_pk_fma_f32 v[32:33], v[26:27], v[26:27], v[32:33]
	s_nop 0
	v_pk_add_f32 v[86:87], v[32:33], v[86:87] op_sel_hi:[1,0]
	s_waitcnt lgkmcnt(2)
	v_pk_mul_f32 v[32:33], v[188:189], v[94:95]
	s_nop 0
	v_pk_fma_f32 v[4:5], v[4:5], v[0:1], v[32:33] op_sel_hi:[1,0,1] neg_lo:[0,0,1] neg_hi:[0,0,1]
	v_pk_mul_f32 v[32:33], v[188:189], v[90:91]
	s_nop 0
	v_pk_fma_f32 v[32:33], v[2:3], v[0:1], v[32:33] op_sel_hi:[1,0,1] neg_lo:[0,0,1] neg_hi:[0,0,1]
	s_nop 0
	v_pk_fma_f32 v[2:3], v[32:33], v[32:33], v[86:87]
	v_mul_f32_e32 v86, v33, v33
	v_pk_add_f32 v[2:3], v[2:3], v[86:87] op_sel_hi:[1,0]
	v_mul_f32_e32 v86, v5, v5
	v_pk_fma_f32 v[2:3], v[4:5], v[4:5], v[2:3]
	s_nop 0
	v_pk_add_f32 v[86:87], v[2:3], v[86:87] op_sel_hi:[1,0]
	s_waitcnt lgkmcnt(0)
	v_pk_mul_f32 v[2:3], v[188:189], v[84:85]
	s_nop 0
	v_pk_fma_f32 v[2:3], v[8:9], v[0:1], v[2:3] op_sel_hi:[1,0,1] neg_lo:[0,0,1] neg_hi:[0,0,1]
	v_pk_mul_f32 v[8:9], v[188:189], v[82:83]
	s_nop 0
	v_pk_fma_f32 v[8:9], v[6:7], v[0:1], v[8:9] op_sel_hi:[1,0,1] neg_lo:[0,0,1] neg_hi:[0,0,1]
	s_nop 0
	v_pk_fma_f32 v[6:7], v[8:9], v[8:9], v[86:87]
	v_mul_f32_e32 v82, v9, v9
	v_pk_add_f32 v[6:7], v[6:7], v[82:83] op_sel_hi:[1,0]
	v_mul_f32_e32 v82, v3, v3
	v_pk_fma_f32 v[6:7], v[2:3], v[2:3], v[6:7]
	s_nop 0
	v_pk_add_f32 v[82:83], v[6:7], v[82:83] op_sel_hi:[1,0]
	v_pk_mul_f32 v[6:7], v[188:189], v[80:81]
	s_nop 0
	v_pk_fma_f32 v[6:7], v[12:13], v[0:1], v[6:7] op_sel_hi:[1,0,1] neg_lo:[0,0,1] neg_hi:[0,0,1]
	v_pk_mul_f32 v[12:13], v[188:189], v[78:79]
	s_nop 0
	v_pk_fma_f32 v[10:11], v[10:11], v[0:1], v[12:13] op_sel_hi:[1,0,1] neg_lo:[0,0,1] neg_hi:[0,0,1]
	s_nop 0
	v_pk_fma_f32 v[12:13], v[10:11], v[10:11], v[82:83]
	v_mul_f32_e32 v78, v11, v11
	v_pk_add_f32 v[12:13], v[12:13], v[78:79] op_sel_hi:[1,0]
	v_mul_f32_e32 v78, v7, v7
	v_pk_fma_f32 v[12:13], v[6:7], v[6:7], v[12:13]
	s_nop 0
	v_pk_add_f32 v[78:79], v[12:13], v[78:79] op_sel_hi:[1,0]
	v_pk_mul_f32 v[12:13], v[188:189], v[76:77]
	s_nop 0
	v_pk_fma_f32 v[12:13], v[14:15], v[0:1], v[12:13] op_sel_hi:[1,0,1] neg_lo:[0,0,1] neg_hi:[0,0,1]
	s_nop 0
	v_pk_fma_f32 v[14:15], v[12:13], v[12:13], v[78:79]
	v_mul_f32_e32 v0, v13, v13
	v_pk_add_f32 v[14:15], v[14:15], v[0:1] op_sel_hi:[1,0]
	v_mul_f32_e32 v0, v17, v17
	v_pk_fma_f32 v[14:15], v[16:17], v[16:17], v[14:15]
	s_nop 0
	v_pk_add_f32 v[14:15], v[14:15], v[0:1] op_sel_hi:[1,0]
	s_nop 0
	v_mov_b32_e32 v0, v14
	s_nop 1
	v_permlane32_swap_b32_e32 v14, v0
	v_add_f32_e32 v0, v14, v0
	v_fmamk_f32 v0, v0, 0x3c000000, v240
	v_mul_f32_e32 v14, 0x4f800000, v0
	v_cmp_gt_f32_e32 vcc, s40, v0
	s_nop 1
	v_cndmask_b32_e32 v0, v0, v14, vcc
	v_sqrt_f32_e32 v76, v0
	v_lshl_add_u64 v[14:15], v[72:73], 0, s[14:15]
	v_lshlrev_b64 v[14:15], 7, v[14:15]
	v_lshl_add_u64 v[14:15], s[64:65], 0, v[14:15]
	v_add_u32_e32 v72, -1, v76
	v_fma_f32 v73, -v72, v76, v0
	v_cmp_ge_f32_e64 s[10:11], 0, v73
	v_add_u32_e32 v73, 1, v76
	v_lshl_add_u64 v[14:15], v[14:15], 0, s[12:13]
	v_cndmask_b32_e64 v72, v76, v72, s[10:11]
	v_fma_f32 v76, -v73, v76, v0
	v_cmp_lt_f32_e64 s[10:11], 0, v76
	v_lshl_add_u64 v[14:15], v[184:185], 1, v[14:15]
	s_nop 0
	v_cndmask_b32_e64 v72, v72, v73, s[10:11]
	v_mul_f32_e32 v73, 0x37800000, v72
	v_cndmask_b32_e32 v72, v72, v73, vcc
	v_cmp_class_f32_e32 vcc, v0, v241
	s_nop 1
	v_cndmask_b32_e32 v0, v72, v0, vcc
	v_div_scale_f32 v72, s[10:11], v0, v0, s41
	v_rcp_f32_e32 v73, v72
	s_nop 0
	v_fma_f32 v76, -v72, v73, 1.0
	v_fmac_f32_e32 v73, v76, v73
	v_div_scale_f32 v76, vcc, s41, v0, s41
	v_mul_f32_e32 v77, v76, v73
	v_fma_f32 v78, -v72, v77, v76
	v_fmac_f32_e32 v77, v78, v73
	v_fma_f32 v72, -v72, v77, v76
	v_div_fmas_f32 v72, v72, v73, v77
	v_div_fixup_f32 v0, v72, v0, s41
	v_pk_mul_f32 v[72:73], v[74:75], v[0:1] op_sel_hi:[1,0]
	v_pk_mul_f32 v[52:53], v[52:53], v[0:1] op_sel_hi:[1,0]
	s_waitcnt vmcnt(0)
	v_pk_mul_f32 v[66:67], v[66:67], v[72:73]
	v_pk_mul_f32 v[52:53], v[68:69], v[52:53]
	v_cvt_pk_bf16_f32 v66, v66, v67
	v_cvt_pk_bf16_f32 v67, v52, v53
	v_add_co_u32_e32 v52, vcc, s42, v14
	v_pk_mul_f32 v[50:51], v[50:51], v[0:1] op_sel_hi:[1,0]
	s_nop 0
	v_addc_co_u32_e32 v53, vcc, 0, v15, vcc
	global_store_dwordx2 v[52:53], v[66:67], off nt
	global_load_dwordx4 v[66:69], v[70:71], off offset:32
	v_pk_mul_f32 v[52:53], v[56:57], v[0:1] op_sel_hi:[1,0]
	v_lshl_add_u64 v[72:73], v[14:15], 0, s[26:27]
	v_pk_mul_f32 v[56:57], v[60:61], v[0:1] op_sel_hi:[1,0]
	v_pk_mul_f32 v[54:55], v[54:55], v[0:1] op_sel_hi:[1,0]
	v_pk_mul_f32 v[36:37], v[36:37], v[0:1] op_sel_hi:[1,0]
	v_pk_mul_f32 v[34:35], v[34:35], v[0:1] op_sel_hi:[1,0]
	v_pk_mul_f32 v[38:39], v[38:39], v[0:1] op_sel_hi:[1,0]
	v_pk_mul_f32 v[18:19], v[18:19], v[0:1] op_sel_hi:[1,0]
	v_pk_mul_f32 v[20:21], v[20:21], v[0:1] op_sel_hi:[1,0]
	v_add_co_u32_e32 v14, vcc, s43, v14
	v_pk_mul_f32 v[24:25], v[24:25], v[0:1] op_sel_hi:[1,0]
	s_nop 0
	v_addc_co_u32_e32 v15, vcc, 0, v15, vcc
	v_pk_mul_f32 v[22:23], v[22:23], v[0:1] op_sel_hi:[1,0]
	v_pk_mul_f32 v[4:5], v[4:5], v[0:1] op_sel_hi:[1,0]
	v_pk_mul_f32 v[2:3], v[2:3], v[0:1] op_sel_hi:[1,0]
	v_pk_mul_f32 v[6:7], v[6:7], v[0:1] op_sel_hi:[1,0]
	s_waitcnt vmcnt(0)
	v_pk_mul_f32 v[52:53], v[66:67], v[52:53]
	v_pk_mul_f32 v[50:51], v[68:69], v[50:51]
	v_cvt_pk_bf16_f32 v52, v52, v53
	v_cvt_pk_bf16_f32 v53, v50, v51
	global_store_dwordx2 v[72:73], v[52:53], off offset:16 nt
	global_load_dwordx4 v[50:53], v[70:71], off offset:64
	s_waitcnt vmcnt(0)
	v_pk_mul_f32 v[50:51], v[50:51], v[56:57]
	v_pk_mul_f32 v[52:53], v[52:53], v[54:55]
	v_cvt_pk_bf16_f32 v50, v50, v51
	v_cvt_pk_bf16_f32 v51, v52, v53
	global_store_dwordx2 v[72:73], v[50:51], off offset:32 nt
	global_load_dwordx4 v[50:53], v[70:71], off offset:96
	v_pk_mul_f32 v[54:55], v[62:63], v[0:1] op_sel_hi:[1,0]
	v_pk_mul_f32 v[56:57], v[58:59], v[0:1] op_sel_hi:[1,0]
	s_waitcnt vmcnt(0)
	v_pk_mul_f32 v[50:51], v[54:55], v[50:51]
	v_pk_mul_f32 v[52:53], v[56:57], v[52:53]
	v_cvt_pk_bf16_f32 v50, v50, v51
	v_cvt_pk_bf16_f32 v51, v52, v53
	global_store_dwordx2 v[72:73], v[50:51], off offset:48 nt
	global_load_dwordx4 v[50:53], v[70:71], off offset:128
	v_pk_mul_f32 v[54:55], v[64:65], v[0:1] op_sel_hi:[1,0]
	s_waitcnt vmcnt(0)
	v_pk_mul_f32 v[36:37], v[36:37], v[52:53]
	v_pk_mul_f32 v[50:51], v[54:55], v[50:51]
	s_nop 0
	v_cvt_pk_bf16_f32 v50, v50, v51
	v_cvt_pk_bf16_f32 v51, v36, v37
	global_store_dwordx2 v[72:73], v[50:51], off offset:64 nt
	global_load_dwordx4 v[50:53], v[70:71], off offset:160
	v_pk_mul_f32 v[36:37], v[40:41], v[0:1] op_sel_hi:[1,0]
	v_pk_mul_f32 v[40:41], v[44:45], v[0:1] op_sel_hi:[1,0]
	s_waitcnt vmcnt(0)
	v_pk_mul_f32 v[36:37], v[36:37], v[50:51]
	v_pk_mul_f32 v[34:35], v[34:35], v[52:53]
	v_cvt_pk_bf16_f32 v36, v36, v37
	v_cvt_pk_bf16_f32 v37, v34, v35
	global_store_dwordx2 v[72:73], v[36:37], off offset:80 nt
	global_load_dwordx4 v[34:37], v[70:71], off offset:192
	s_waitcnt vmcnt(0)
	v_pk_mul_f32 v[34:35], v[40:41], v[34:35]
	v_pk_mul_f32 v[36:37], v[38:39], v[36:37]
	v_cvt_pk_bf16_f32 v34, v34, v35
	v_cvt_pk_bf16_f32 v35, v36, v37
	global_store_dwordx2 v[72:73], v[34:35], off offset:96 nt
	global_load_dwordx4 v[34:37], v[70:71], off offset:224
	v_pk_mul_f32 v[38:39], v[46:47], v[0:1] op_sel_hi:[1,0]
	v_pk_mul_f32 v[40:41], v[42:43], v[0:1] op_sel_hi:[1,0]
	s_waitcnt vmcnt(0)
	v_pk_mul_f32 v[34:35], v[38:39], v[34:35]
	v_pk_mul_f32 v[36:37], v[40:41], v[36:37]
	v_cvt_pk_bf16_f32 v34, v34, v35
	v_cvt_pk_bf16_f32 v35, v36, v37
	global_store_dwordx2 v[72:73], v[34:35], off offset:112 nt
	global_load_dwordx4 v[34:37], v[70:71], off offset:256
	s_waitcnt vmcnt(0)
	v_pk_mul_f32 v[18:19], v[18:19], v[34:35]
	v_pk_mul_f32 v[20:21], v[20:21], v[36:37]
	v_cvt_pk_bf16_f32 v18, v18, v19
	v_cvt_pk_bf16_f32 v19, v20, v21
	global_store_dwordx2 v[14:15], v[18:19], off nt
	global_load_dwordx4 v[18:21], v[70:71], off offset:288
	v_pk_mul_f32 v[34:35], v[48:49], v[0:1] op_sel_hi:[1,0]
	s_waitcnt vmcnt(0)
	v_pk_mul_f32 v[20:21], v[24:25], v[20:21]
	v_pk_mul_f32 v[18:19], v[34:35], v[18:19]
	v_pk_mul_f32 v[24:25], v[28:29], v[0:1] op_sel_hi:[1,0]
	v_cvt_pk_bf16_f32 v18, v18, v19
	v_cvt_pk_bf16_f32 v19, v20, v21
	global_store_dwordx2 v[14:15], v[18:19], off offset:16 nt
	global_load_dwordx4 v[18:21], v[70:71], off offset:320
	s_waitcnt vmcnt(0)
	v_pk_mul_f32 v[18:19], v[24:25], v[18:19]
	v_pk_mul_f32 v[20:21], v[22:23], v[20:21]
	v_cvt_pk_bf16_f32 v18, v18, v19
	v_cvt_pk_bf16_f32 v19, v20, v21
	global_store_dwordx2 v[14:15], v[18:19], off offset:32 nt
	global_load_dwordx4 v[18:21], v[70:71], off offset:352
	v_pk_mul_f32 v[22:23], v[30:31], v[0:1] op_sel_hi:[1,0]
	v_pk_mul_f32 v[24:25], v[26:27], v[0:1] op_sel_hi:[1,0]
	s_waitcnt vmcnt(0)
	v_pk_mul_f32 v[18:19], v[22:23], v[18:19]
	v_pk_mul_f32 v[20:21], v[24:25], v[20:21]
	v_cvt_pk_bf16_f32 v18, v18, v19
	v_cvt_pk_bf16_f32 v19, v20, v21
	global_store_dwordx2 v[14:15], v[18:19], off offset:48 nt
	global_load_dwordx4 v[18:21], v[70:71], off offset:384
	v_pk_mul_f32 v[22:23], v[32:33], v[0:1] op_sel_hi:[1,0]
	s_waitcnt vmcnt(0)
	v_pk_mul_f32 v[4:5], v[4:5], v[20:21]
	v_pk_mul_f32 v[18:19], v[22:23], v[18:19]
	s_nop 0
	v_cvt_pk_bf16_f32 v18, v18, v19
	v_cvt_pk_bf16_f32 v19, v4, v5
	global_store_dwordx2 v[14:15], v[18:19], off offset:64 nt
	global_load_dwordx4 v[18:21], v[70:71], off offset:416
	v_pk_mul_f32 v[4:5], v[8:9], v[0:1] op_sel_hi:[1,0]
	v_pk_mul_f32 v[8:9], v[10:11], v[0:1] op_sel_hi:[1,0]
	s_waitcnt vmcnt(0)
	v_pk_mul_f32 v[4:5], v[4:5], v[18:19]
	v_pk_mul_f32 v[2:3], v[2:3], v[20:21]
	v_cvt_pk_bf16_f32 v4, v4, v5
	v_cvt_pk_bf16_f32 v5, v2, v3
	global_store_dwordx2 v[14:15], v[4:5], off offset:80 nt
	global_load_dwordx4 v[2:5], v[70:71], off offset:448
	s_waitcnt vmcnt(0)
	v_pk_mul_f32 v[2:3], v[8:9], v[2:3]
	v_pk_mul_f32 v[4:5], v[6:7], v[4:5]
	v_cvt_pk_bf16_f32 v2, v2, v3
	v_cvt_pk_bf16_f32 v3, v4, v5
	global_store_dwordx2 v[14:15], v[2:3], off offset:96 nt
	global_load_dwordx4 v[2:5], v[70:71], off offset:480
	v_pk_mul_f32 v[6:7], v[12:13], v[0:1] op_sel_hi:[1,0]
	v_pk_mul_f32 v[8:9], v[16:17], v[0:1] op_sel_hi:[1,0]
	s_waitcnt vmcnt(0)
	v_pk_mul_f32 v[2:3], v[6:7], v[2:3]
	v_pk_mul_f32 v[4:5], v[8:9], v[4:5]
	v_cvt_pk_bf16_f32 v2, v2, v3
	v_cvt_pk_bf16_f32 v3, v4, v5
	global_store_dwordx2 v[14:15], v[2:3], off offset:112 nt
	s_branch .LBB0_1070

.LBB0_2184:
	s_or_b64 exec, exec, s[10:11]
	ds_read_b128 v[56:59], v196
	ds_read_b128 v[60:63], v196 offset:16
	ds_read_b128 v[64:67], v205
	v_mov_b32_e32 v68, s5
	v_add_f32_e32 v101, s4, v68
	v_subrev_u32_e32 v72, 48, v92
	s_waitcnt lgkmcnt(2)
	v_add_f32_e32 v68, v56, v57
	v_add_f32_e32 v70, v58, v59
	s_waitcnt lgkmcnt(1)
	v_add_f32_e32 v60, v60, v61
	v_add_f32_e32 v62, v62, v63
	s_waitcnt lgkmcnt(0)
	v_mov_b32_e32 v69, v64
	v_mov_b32_e32 v71, v65
	v_mov_b32_e32 v61, v66
	v_mov_b32_e32 v63, v67
	ds_read_b128 v[56:59], v197
	ds_read_b32 v66, v186
	v_pk_add_f32 v[64:65], v[68:69], v[70:71]
	v_pk_add_f32 v[60:61], v[60:61], v[62:63]
	v_and_b32_e32 v62, 0xffff0000, v98
	v_pk_add_f32 v[60:61], v[64:65], v[60:61]
	v_mul_f32_e32 v62, 0xbfb8aa3b, v62
	v_add_f32_e32 v60, v60, v61
	v_lshlrev_b32_e32 v61, 16, v98
	v_mul_f32_e32 v61, 0xbfb8aa3b, v61
	v_exp_f32_e32 v61, v61
	s_waitcnt lgkmcnt(0)
	v_mul_f32_e32 v66, 0xbfb8aa3b, v66
	v_exp_f32_e32 v63, v62
	v_exp_f32_e32 v66, v66
	v_add_f32_e32 v61, 1.0, v61
	v_lshlrev_b32_e32 v64, 16, v99
	v_rcp_f32_e32 v62, v61
	v_add_f32_e32 v61, 1.0, v63
	v_max_f32_e64 v60, |v60|, v66
	v_and_b32_e32 v65, 0xffff0000, v99
	v_rcp_f32_e32 v63, v61
	v_mul_f32_e32 v61, 0xbfb8aa3b, v64
	v_rcp_f32_e32 v60, v60
	v_exp_f32_e32 v61, v61
	v_mul_f32_e32 v64, 0xbfb8aa3b, v65
	v_exp_f32_e32 v65, v64
	ds_read_b32 v67, v188
	ds_read_b32 v68, v190
	ds_read_b32 v69, v192
	v_pk_mul_f32 v[52:53], v[52:53], v[60:61] op_sel_hi:[1,0]
	v_add_f32_e32 v61, 1.0, v61
	v_rcp_f32_e32 v64, v61
	v_add_f32_e32 v61, 1.0, v65
	v_rcp_f32_e32 v65, v61
	v_pk_mul_f32 v[52:53], v[62:63], v[52:53]
	v_add_f32_e32 v56, v56, v57
	v_cvt_pk_bf16_f32 v62, v52, v53
	v_pk_mul_f32 v[52:53], v[54:55], v[60:61] op_sel_hi:[1,0]
	v_add_f32_e32 v58, v58, v59
	v_pk_mul_f32 v[52:53], v[64:65], v[52:53]
	v_mov_b32_e32 v93, v73
	v_cvt_pk_bf16_f32 v63, v52, v53
	v_lshlrev_b64 v[52:53], 7, v[72:73]
	v_lshl_add_u64 v[60:61], v[76:77], 0, v[52:53]
	ds_read_b128 v[52:55], v197 offset:16
	global_store_dwordx2 v[60:61], v[62:63], off nt
	ds_read_b128 v[60:63], v206
	v_subrev_u32_e32 v72, 32, v92
	s_add_i32 s3, s3, 2
	s_waitcnt lgkmcnt(1)
	v_add_f32_e32 v52, v52, v53
	v_add_f32_e32 v54, v54, v55
	s_waitcnt lgkmcnt(0)
	v_mov_b32_e32 v57, v60
	v_mov_b32_e32 v59, v61
	v_mov_b32_e32 v53, v62
	v_mov_b32_e32 v55, v63
	v_pk_add_f32 v[56:57], v[56:57], v[58:59]
	v_pk_add_f32 v[52:53], v[52:53], v[54:55]
	v_and_b32_e32 v54, 0xffff0000, v96
	v_pk_add_f32 v[52:53], v[56:57], v[52:53]
	v_mul_f32_e32 v54, 0xbfb8aa3b, v54
	v_add_f32_e32 v52, v52, v53
	v_lshlrev_b32_e32 v53, 16, v96
	v_mul_f32_e32 v53, 0xbfb8aa3b, v53
	v_exp_f32_e32 v53, v53
	v_mul_f32_e32 v58, 0xbfb8aa3b, v67
	v_exp_f32_e32 v55, v54
	v_exp_f32_e32 v58, v58
	v_add_f32_e32 v53, 1.0, v53
	v_lshlrev_b32_e32 v56, 16, v97
	v_rcp_f32_e32 v54, v53
	v_add_f32_e32 v53, 1.0, v55
	v_max_f32_e64 v52, |v52|, v58
	v_and_b32_e32 v57, 0xffff0000, v97
	v_rcp_f32_e32 v55, v53
	v_mul_f32_e32 v53, 0xbfb8aa3b, v56
	v_rcp_f32_e32 v52, v52
	v_exp_f32_e32 v53, v53
	v_mul_f32_e32 v56, 0xbfb8aa3b, v57
	v_exp_f32_e32 v57, v56
	v_lshl_add_u64 v[78:79], v[78:79], 0, s[44:45]
	v_pk_mul_f32 v[48:49], v[48:49], v[52:53] op_sel_hi:[1,0]
	v_add_f32_e32 v53, 1.0, v53
	v_rcp_f32_e32 v56, v53
	v_add_f32_e32 v53, 1.0, v57
	v_rcp_f32_e32 v57, v53
	v_pk_mul_f32 v[48:49], v[54:55], v[48:49]
	v_lshl_add_u64 v[82:83], v[82:83], 0, s[44:45]
	v_cvt_pk_bf16_f32 v58, v48, v49
	v_pk_mul_f32 v[48:49], v[50:51], v[52:53] op_sel_hi:[1,0]
	v_lshlrev_b64 v[52:53], 7, v[72:73]
	v_pk_mul_f32 v[48:49], v[56:57], v[48:49]
	v_lshl_add_u64 v[56:57], v[76:77], 0, v[52:53]
	v_cvt_pk_bf16_f32 v59, v48, v49
	ds_read_b128 v[48:51], v198
	ds_read_b128 v[52:55], v198 offset:16
	global_store_dwordx2 v[56:57], v[58:59], off nt
	ds_read_b128 v[56:59], v207
	v_add_u32_e32 v72, -16, v92
	s_waitcnt lgkmcnt(2)
	v_add_f32_e32 v60, v48, v49
	v_add_f32_e32 v62, v50, v51
	s_waitcnt lgkmcnt(1)
	v_add_f32_e32 v52, v52, v53
	v_add_f32_e32 v54, v54, v55
	s_waitcnt lgkmcnt(0)
	v_mov_b32_e32 v61, v56
	v_mov_b32_e32 v63, v57
	v_mov_b32_e32 v53, v58
	v_mov_b32_e32 v55, v59
	v_pk_add_f32 v[56:57], v[60:61], v[62:63]
	v_pk_add_f32 v[52:53], v[52:53], v[54:55]
	v_and_b32_e32 v54, 0xffff0000, v80
	v_pk_add_f32 v[52:53], v[56:57], v[52:53]
	v_mul_f32_e32 v54, 0xbfb8aa3b, v54
	v_add_f32_e32 v52, v52, v53
	v_lshlrev_b32_e32 v53, 16, v80
	v_mul_f32_e32 v53, 0xbfb8aa3b, v53
	v_exp_f32_e32 v53, v53
	v_mul_f32_e32 v58, 0xbfb8aa3b, v68
	v_exp_f32_e32 v55, v54
	v_exp_f32_e32 v58, v58
	v_add_f32_e32 v53, 1.0, v53
	v_lshlrev_b32_e32 v56, 16, v81
	v_rcp_f32_e32 v54, v53
	v_add_f32_e32 v53, 1.0, v55
	v_max_f32_e64 v52, |v52|, v58
	v_and_b32_e32 v57, 0xffff0000, v81
	v_rcp_f32_e32 v55, v53
	v_mul_f32_e32 v53, 0xbfb8aa3b, v56
	v_rcp_f32_e32 v52, v52
	v_exp_f32_e32 v53, v53
	v_mul_f32_e32 v56, 0xbfb8aa3b, v57
	v_exp_f32_e32 v57, v56
	ds_read_b128 v[48:51], v199
	v_pk_mul_f32 v[44:45], v[44:45], v[52:53] op_sel_hi:[1,0]
	v_add_f32_e32 v53, 1.0, v53
	v_rcp_f32_e32 v56, v53
	v_add_f32_e32 v53, 1.0, v57
	v_rcp_f32_e32 v57, v53
	v_pk_mul_f32 v[44:45], v[54:55], v[44:45]
	v_lshl_add_u64 v[84:85], v[84:85], 0, s[44:45]
	v_cvt_pk_bf16_f32 v54, v44, v45
	v_pk_mul_f32 v[44:45], v[46:47], v[52:53] op_sel_hi:[1,0]
	v_lshl_add_u64 v[86:87], v[86:87], 0, s[46:47]
	v_pk_mul_f32 v[44:45], v[56:57], v[44:45]
	v_lshl_add_u64 v[88:89], v[88:89], 0, s[46:47]
	v_cvt_pk_bf16_f32 v55, v44, v45
	v_lshlrev_b64 v[44:45], 7, v[72:73]
	v_lshl_add_u64 v[52:53], v[76:77], 0, v[44:45]
	ds_read_b128 v[44:47], v199 offset:16
	global_store_dwordx2 v[52:53], v[54:55], off nt
	ds_read_b128 v[52:55], v208
	s_waitcnt lgkmcnt(2)
	v_add_f32_e32 v48, v48, v49
	v_add_f32_e32 v50, v50, v51
	s_waitcnt lgkmcnt(1)
	v_add_f32_e32 v44, v44, v45
	v_add_f32_e32 v46, v46, v47
	s_waitcnt lgkmcnt(0)
	v_mov_b32_e32 v49, v52
	v_mov_b32_e32 v51, v53
	v_mov_b32_e32 v45, v54
	v_mov_b32_e32 v47, v55
	v_pk_add_f32 v[48:49], v[48:49], v[50:51]
	v_pk_add_f32 v[44:45], v[44:45], v[46:47]
	v_and_b32_e32 v46, 0xffff0000, v74
	v_pk_add_f32 v[44:45], v[48:49], v[44:45]
	v_mul_f32_e32 v46, 0xbfb8aa3b, v46
	v_add_f32_e32 v44, v44, v45
	v_lshlrev_b32_e32 v45, 16, v74
	v_mul_f32_e32 v45, 0xbfb8aa3b, v45
	v_exp_f32_e32 v45, v45
	v_mul_f32_e32 v50, 0xbfb8aa3b, v69
	v_exp_f32_e32 v47, v46
	v_exp_f32_e32 v50, v50
	v_add_f32_e32 v45, 1.0, v45
	v_lshlrev_b32_e32 v48, 16, v75
	v_rcp_f32_e32 v46, v45
	v_add_f32_e32 v45, 1.0, v47
	v_max_f32_e64 v44, |v44|, v50
	v_and_b32_e32 v49, 0xffff0000, v75
	v_rcp_f32_e32 v47, v45
	v_mul_f32_e32 v45, 0xbfb8aa3b, v48
	v_rcp_f32_e32 v44, v44
	v_exp_f32_e32 v45, v45
	v_mul_f32_e32 v48, 0xbfb8aa3b, v49
	v_exp_f32_e32 v49, v48
	v_lshl_add_u64 v[90:91], v[90:91], 0, s[46:47]
	v_pk_mul_f32 v[40:41], v[40:41], v[44:45] op_sel_hi:[1,0]
	v_add_f32_e32 v45, 1.0, v45
	v_rcp_f32_e32 v48, v45
	v_add_f32_e32 v45, 1.0, v49
	v_rcp_f32_e32 v49, v45
	v_pk_mul_f32 v[42:43], v[42:43], v[44:45] op_sel_hi:[1,0]
	v_pk_mul_f32 v[40:41], v[46:47], v[40:41]
	v_lshl_add_u64 v[94:95], v[94:95], 0, s[46:47]
	v_pk_mul_f32 v[42:43], v[48:49], v[42:43]
	v_cvt_pk_bf16_f32 v40, v40, v41
	v_cvt_pk_bf16_f32 v41, v42, v43
	v_lshlrev_b64 v[42:43], 7, v[92:93]
	v_lshl_add_u64 v[42:43], v[76:77], 0, v[42:43]
	global_store_dwordx2 v[42:43], v[40:41], off nt
	s_waitcnt lgkmcnt(0)
	s_barrier
	v_add_u32_e32 v92, 0x80, v92
	s_andn2_b64 vcc, exec, s[66:67]
	s_waitcnt vmcnt(10)
	v_mov_b32_e32 v100, v110
	s_waitcnt vmcnt(8)
	v_mov_b64_e32 v[110:111], v[108:109]
	s_waitcnt vmcnt(7)
	v_mov_b64_e32 v[98:99], v[112:113]
	s_waitcnt vmcnt(6)
	v_mov_b64_e32 v[96:97], v[154:155]
	s_waitcnt vmcnt(5)
	v_mov_b64_e32 v[80:81], v[114:115]
	s_waitcnt vmcnt(4)
	v_mov_b64_e32 v[74:75], v[116:117]
	v_mov_b64_e32 v[112:113], v[106:107]
	v_mov_b32_e32 v154, v203
	v_mov_b64_e32 v[114:115], v[104:105]
	v_mov_b64_e32 v[116:117], v[102:103]
	s_cbranch_vccz .LBB0_2213

.LBB0_2224:
	s_or_b64 exec, exec, s[22:23]
	s_waitcnt lgkmcnt(0)
	s_barrier
	ds_read_b128 v[132:135], v216
	ds_read_b128 v[136:139], v216 offset:16
	v_subrev_u32_e32 v154, 48, v170
	v_mov_b32_e32 v171, v155
	s_add_i32 s2, s2, 2
	s_waitcnt lgkmcnt(1)
	v_mov_b32_e32 v140, v132
	s_waitcnt lgkmcnt(0)
	v_mov_b32_e32 v141, v136
	v_mov_b32_e32 v136, v133
	v_pk_add_f32 v[132:133], v[140:141], v[136:137]
	v_mov_b32_e32 v136, v134
	v_mov_b32_e32 v137, v138
	v_mov_b32_e32 v138, v135
	v_pk_add_f32 v[134:135], v[136:137], v[138:139]
	v_lshl_add_u64 v[160:161], v[160:161], 0, s[36:37]
	v_pk_add_f32 v[132:133], v[132:133], v[134:135]
	v_lshlrev_b32_e32 v134, 16, v177
	v_add_f32_e32 v132, v132, v133
	v_fmamk_f32 v132, v132, 0x3c000000, v151
	v_rsq_f32_e32 v132, v132
	v_and_b32_e32 v135, 0xffff0000, v177
	v_mul_f32_e32 v138, 0xbfb8aa3b, v134
	v_mul_f32_e32 v139, 0xbfb8aa3b, v135
	v_pk_mul_f32 v[130:131], v[130:131], v[132:133] op_sel_hi:[1,0]
	v_pk_mul_f32 v[128:129], v[128:129], v[132:133] op_sel_hi:[1,0]
	v_pk_mul_f32 v[136:137], v[2:3], v[130:131]
	v_lshlrev_b32_e32 v130, 16, v176
	v_and_b32_e32 v131, 0xffff0000, v176
	v_mul_f32_e32 v132, 0xbfb8aa3b, v130
	v_mul_f32_e32 v133, 0xbfb8aa3b, v131
	v_exp_f32_e32 v132, v132
	v_exp_f32_e32 v133, v133
	v_exp_f32_e32 v138, v138
	v_exp_f32_e32 v139, v139
	v_add_f32_e32 v132, 1.0, v132
	v_add_f32_e32 v133, 1.0, v133
	v_rcp_f32_e32 v132, v132
	v_rcp_f32_e32 v133, v133
	v_add_f32_e32 v138, 1.0, v138
	v_add_f32_e32 v139, 1.0, v139
	v_rcp_f32_e32 v138, v138
	v_rcp_f32_e32 v139, v139
	v_pk_mul_f32 v[128:129], v[0:1], v[128:129]
	v_pk_mul_f32 v[130:131], v[132:133], v[130:131]
	v_lshl_add_u64 v[162:163], v[162:163], 0, s[36:37]
	v_pk_mul_f32 v[128:129], v[130:131], v[128:129]
	v_pk_mul_f32 v[138:139], v[138:139], v[134:135]
	v_cvt_pk_bf16_f32 v140, v128, v129
	ds_read_b128 v[128:131], v216 offset:512
	ds_read_b128 v[132:135], v216 offset:528
	v_pk_mul_f32 v[136:137], v[138:139], v[136:137]
	v_lshl_add_u64 v[164:165], v[164:165], 0, s[36:37]
	v_cvt_pk_bf16_f32 v141, v136, v137
	s_waitcnt lgkmcnt(1)
	v_mov_b32_e32 v136, v128
	s_waitcnt lgkmcnt(0)
	v_mov_b32_e32 v137, v132
	v_mov_b32_e32 v132, v129
	v_pk_add_f32 v[128:129], v[136:137], v[132:133]
	v_mov_b32_e32 v132, v130
	v_mov_b32_e32 v133, v134
	v_mov_b32_e32 v134, v131
	v_pk_add_f32 v[130:131], v[132:133], v[134:135]
	v_lshl_add_u64 v[166:167], v[166:167], 0, s[38:39]
	v_pk_add_f32 v[128:129], v[128:129], v[130:131]
	v_lshlrev_b64 v[130:131], 7, v[154:155]
	v_add_f32_e32 v128, v128, v129
	v_fmamk_f32 v128, v128, 0x3c000000, v151
	v_rsq_f32_e32 v128, v128
	v_lshl_add_u64 v[130:131], v[158:159], 0, v[130:131]
	global_store_dwordx2 v[130:131], v[140:141], off nt
	v_lshlrev_b32_e32 v130, 16, v175
	v_pk_mul_f32 v[126:127], v[126:127], v[128:129] op_sel_hi:[1,0]
	v_pk_mul_f32 v[124:125], v[124:125], v[128:129] op_sel_hi:[1,0]
	v_pk_mul_f32 v[132:133], v[2:3], v[126:127]
	v_lshlrev_b32_e32 v126, 16, v174
	v_and_b32_e32 v127, 0xffff0000, v174
	v_mul_f32_e32 v128, 0xbfb8aa3b, v126
	v_mul_f32_e32 v129, 0xbfb8aa3b, v127
	v_exp_f32_e32 v128, v128
	v_exp_f32_e32 v129, v129
	v_and_b32_e32 v131, 0xffff0000, v175
	v_mul_f32_e32 v134, 0xbfb8aa3b, v130
	v_mul_f32_e32 v135, 0xbfb8aa3b, v131
	v_exp_f32_e32 v134, v134
	v_exp_f32_e32 v135, v135
	v_add_f32_e32 v128, 1.0, v128
	v_add_f32_e32 v129, 1.0, v129
	v_rcp_f32_e32 v128, v128
	v_rcp_f32_e32 v129, v129
	v_add_f32_e32 v134, 1.0, v134
	v_add_f32_e32 v135, 1.0, v135
	v_rcp_f32_e32 v134, v134
	v_rcp_f32_e32 v135, v135
	v_pk_mul_f32 v[124:125], v[0:1], v[124:125]
	v_pk_mul_f32 v[126:127], v[128:129], v[126:127]
	v_subrev_u32_e32 v154, 32, v170
	v_pk_mul_f32 v[124:125], v[126:127], v[124:125]
	v_pk_mul_f32 v[134:135], v[134:135], v[130:131]
	v_cvt_pk_bf16_f32 v136, v124, v125
	ds_read_b128 v[124:127], v216 offset:1024
	ds_read_b128 v[128:131], v216 offset:1040
	v_pk_mul_f32 v[132:133], v[134:135], v[132:133]
	v_lshl_add_u64 v[168:169], v[168:169], 0, s[38:39]
	v_cvt_pk_bf16_f32 v137, v132, v133
	s_waitcnt lgkmcnt(1)
	v_mov_b32_e32 v132, v124
	s_waitcnt lgkmcnt(0)
	v_mov_b32_e32 v133, v128
	v_mov_b32_e32 v128, v125
	v_pk_add_f32 v[124:125], v[132:133], v[128:129]
	v_mov_b32_e32 v128, v126
	v_mov_b32_e32 v129, v130
	v_mov_b32_e32 v130, v127
	v_pk_add_f32 v[126:127], v[128:129], v[130:131]
	s_andn2_b64 vcc, exec, s[40:41]
	v_pk_add_f32 v[124:125], v[124:125], v[126:127]
	v_lshlrev_b64 v[126:127], 7, v[154:155]
	v_add_f32_e32 v124, v124, v125
	v_fmamk_f32 v124, v124, 0x3c000000, v151
	v_rsq_f32_e32 v124, v124
	v_lshl_add_u64 v[126:127], v[158:159], 0, v[126:127]
	global_store_dwordx2 v[126:127], v[136:137], off nt
	v_lshlrev_b32_e32 v126, 16, v173
	v_pk_mul_f32 v[122:123], v[122:123], v[124:125] op_sel_hi:[1,0]
	v_pk_mul_f32 v[120:121], v[120:121], v[124:125] op_sel_hi:[1,0]
	v_pk_mul_f32 v[128:129], v[2:3], v[122:123]
	v_lshlrev_b32_e32 v122, 16, v172
	v_and_b32_e32 v123, 0xffff0000, v172
	v_mul_f32_e32 v124, 0xbfb8aa3b, v122
	v_mul_f32_e32 v125, 0xbfb8aa3b, v123
	v_exp_f32_e32 v124, v124
	v_exp_f32_e32 v125, v125
	v_and_b32_e32 v127, 0xffff0000, v173
	v_mul_f32_e32 v130, 0xbfb8aa3b, v126
	v_mul_f32_e32 v131, 0xbfb8aa3b, v127
	v_exp_f32_e32 v130, v130
	v_exp_f32_e32 v131, v131
	v_add_f32_e32 v124, 1.0, v124
	v_add_f32_e32 v125, 1.0, v125
	v_rcp_f32_e32 v124, v124
	v_rcp_f32_e32 v125, v125
	v_add_f32_e32 v130, 1.0, v130
	v_add_f32_e32 v131, 1.0, v131
	v_rcp_f32_e32 v130, v130
	v_rcp_f32_e32 v131, v131
	v_pk_mul_f32 v[120:121], v[0:1], v[120:121]
	v_pk_mul_f32 v[122:123], v[124:125], v[122:123]
	v_add_u32_e32 v154, -16, v170
	v_pk_mul_f32 v[120:121], v[122:123], v[120:121]
	v_pk_mul_f32 v[130:131], v[130:131], v[126:127]
	v_cvt_pk_bf16_f32 v132, v120, v121
	ds_read_b128 v[120:123], v216 offset:1536
	ds_read_b128 v[124:127], v216 offset:1552
	v_pk_mul_f32 v[128:129], v[130:131], v[128:129]
	s_waitcnt vmcnt(6)
	v_mov_b64_e32 v[188:189], v[186:187]
	v_cvt_pk_bf16_f32 v133, v128, v129
	s_waitcnt lgkmcnt(1)
	v_mov_b32_e32 v128, v120
	s_waitcnt lgkmcnt(0)
	v_mov_b32_e32 v129, v124
	v_mov_b32_e32 v124, v121
	v_pk_add_f32 v[120:121], v[128:129], v[124:125]
	v_mov_b32_e32 v124, v122
	v_mov_b32_e32 v125, v126
	v_mov_b32_e32 v126, v123
	v_pk_add_f32 v[122:123], v[124:125], v[126:127]
	v_lshlrev_b32_e32 v124, 16, v157
	v_pk_add_f32 v[120:121], v[120:121], v[122:123]
	v_lshlrev_b64 v[122:123], 7, v[154:155]
	v_add_f32_e32 v120, v120, v121
	v_fmamk_f32 v120, v120, 0x3c000000, v151
	v_rsq_f32_e32 v120, v120
	v_lshl_add_u64 v[122:123], v[158:159], 0, v[122:123]
	global_store_dwordx2 v[122:123], v[132:133], off nt
	v_and_b32_e32 v125, 0xffff0000, v157
	v_pk_mul_f32 v[116:117], v[116:117], v[120:121] op_sel_hi:[1,0]
	v_pk_mul_f32 v[118:119], v[118:119], v[120:121] op_sel_hi:[1,0]
	v_lshlrev_b32_e32 v120, 16, v156
	v_and_b32_e32 v121, 0xffff0000, v156
	v_mul_f32_e32 v122, 0xbfb8aa3b, v120
	v_mul_f32_e32 v123, 0xbfb8aa3b, v121
	v_exp_f32_e32 v122, v122
	v_exp_f32_e32 v123, v123
	v_mul_f32_e32 v126, 0xbfb8aa3b, v124
	v_mul_f32_e32 v127, 0xbfb8aa3b, v125
	v_exp_f32_e32 v126, v126
	v_exp_f32_e32 v127, v127
	v_add_f32_e32 v122, 1.0, v122
	v_add_f32_e32 v123, 1.0, v123
	v_rcp_f32_e32 v122, v122
	v_rcp_f32_e32 v123, v123
	v_add_f32_e32 v126, 1.0, v126
	v_add_f32_e32 v127, 1.0, v127
	v_rcp_f32_e32 v126, v126
	v_rcp_f32_e32 v127, v127
	v_pk_mul_f32 v[116:117], v[0:1], v[116:117]
	v_pk_mul_f32 v[120:121], v[122:123], v[120:121]
	v_pk_mul_f32 v[118:119], v[2:3], v[118:119]
	v_pk_mul_f32 v[116:117], v[120:121], v[116:117]
	v_pk_mul_f32 v[120:121], v[126:127], v[124:125]
	v_cvt_pk_bf16_f32 v116, v116, v117
	v_pk_mul_f32 v[118:119], v[120:121], v[118:119]
	s_waitcnt vmcnt(6)
	v_mov_b64_e32 v[176:177], v[190:191]
	v_cvt_pk_bf16_f32 v117, v118, v119
	v_lshlrev_b64 v[118:119], 7, v[170:171]
	v_lshl_add_u64 v[118:119], v[158:159], 0, v[118:119]
	v_add_u32_e32 v170, 0x80, v170
	s_waitcnt vmcnt(5)
	v_mov_b64_e32 v[174:175], v[192:193]
	s_waitcnt vmcnt(4)
	v_mov_b64_e32 v[172:173], v[194:195]
	s_waitcnt vmcnt(3)
	v_mov_b64_e32 v[156:157], v[198:199]
	v_mov_b64_e32 v[190:191], v[184:185]
	v_mov_b64_e32 v[192:193], v[182:183]
	v_mov_b64_e32 v[194:195], v[178:179]
	global_store_dwordx2 v[118:119], v[116:117], off nt
	s_cbranch_vccz .LBB0_2277

.LBB0_2243:
	v_mov_b32_e32 v140, s28
	s_nop 5
	v_cndmask_b32_e64 v140, v136, v140, s[12:13]
	v_cndmask_b32_e64 v140, v140, v136, s[14:15]
	v_cndmask_b32_e64 v140, v136, v140, s[8:9]
	v_mov_b32_e32 v136, s28
	v_cndmask_b32_e64 v141, 0, v137, s[14:15]
	v_cndmask_b32_e64 v142, v138, 0, s[16:17]
	v_cndmask_b32_e64 v143, v139, 0, s[18:19]
	v_cndmask_b32_e64 v136, v132, v136, s[12:13]
	v_cndmask_b32_e64 v137, v137, v141, s[8:9]
	v_cndmask_b32_e64 v139, v139, v143, s[8:9]
	v_cndmask_b32_e64 v138, v138, v142, s[8:9]
	v_cndmask_b32_e64 v141, 0, v133, s[14:15]
	v_cndmask_b32_e64 v136, v136, v132, s[14:15]
	v_cndmask_b32_e64 v142, v134, 0, s[16:17]
	v_cndmask_b32_e64 v143, v135, 0, s[18:19]
	v_cndmask_b32_e64 v141, v133, v141, s[10:11]
	v_cndmask_b32_e64 v135, v135, v143, s[10:11]
	v_cndmask_b32_e64 v142, v134, v142, s[10:11]
	v_cndmask_b32_e64 v134, v132, v136, s[10:11]
	v_cvt_pk_bf16_f32 v132, v140, v137
	v_cvt_pk_bf16_f32 v133, v138, v139
	v_cvt_pk_bf16_f32 v134, v134, v141
	v_cvt_pk_bf16_f32 v135, v142, v135
	ds_write2_b64 v222, v[132:133], v[134:135] offset1:4
	v_add_u32_e32 v132, 0, v213
	s_waitcnt lgkmcnt(0)
	s_barrier
	v_add_u32_e32 v171, 0x20000, v132
	ds_read_b128 v[132:135], v171
	ds_read_b128 v[136:139], v171 offset:64
	ds_read_b64_tr_b16 v[140:141], v214
	ds_read_b64_tr_b16 v[142:143], v214 offset:1088
	s_waitcnt lgkmcnt(3)
	v_pk_mul_f32 v[112:113], v[112:113], v[132:133]
	v_pk_mul_f32 v[114:115], v[114:115], v[134:135]
	ds_read_b128 v[132:135], v223
	ds_read_b128 v[144:147], v171 offset:128
	ds_read_b128 v[224:227], v223 offset:2304
	ds_read_b64_tr_b16 v[228:229], v214 offset:8704
	ds_read_b64_tr_b16 v[230:231], v214 offset:9792
	s_waitcnt lgkmcnt(7)
	v_pk_mul_f32 v[92:93], v[92:93], v[136:137]
	s_waitcnt lgkmcnt(4)
	v_mfma_f32_16x16x32_bf16 v[128:131], v[140:143], v[132:135], v[128:131]
	v_mul_f32_e64 v94, v94, v138
	v_mul_f32_e64 v95, v95, v139
	ds_read_b128 v[132:135], v171 offset:192
	ds_read_b128 v[136:139], v223 offset:4608
	s_waitcnt lgkmcnt(5)
	v_pk_mul_f32 v[84:85], v[84:85], v[144:145]
	s_waitcnt lgkmcnt(4)
	v_mfma_f32_16x16x32_bf16 v[124:127], v[140:143], v[224:227], v[124:127]
	ds_read_b128 v[224:227], v223 offset:6912
	ds_read_b128 v[232:235], v223 offset:4672
	v_pk_mul_f32 v[86:87], v[86:87], v[146:147]
	s_waitcnt lgkmcnt(3)
	v_pk_mul_f32 v[88:89], v[88:89], v[132:133]
	s_waitcnt lgkmcnt(2)
	v_mfma_f32_16x16x32_bf16 v[120:123], v[140:143], v[136:139], v[120:123]
	ds_read_b64_tr_b16 v[138:139], v215 offset:53312
	ds_read_b64_tr_b16 v[136:137], v215 offset:52224
	ds_read_b128 v[236:239], v223 offset:6976
	v_pk_mul_f32 v[90:91], v[90:91], v[134:135]
	s_waitcnt lgkmcnt(4)
	v_mfma_f32_16x16x32_bf16 v[116:119], v[140:143], v[224:227], v[116:119]
	ds_read_b64_tr_b16 v[226:227], v215 offset:53344
	ds_read_b64_tr_b16 v[224:225], v215 offset:52256
	ds_read_b64_tr_b16 v[240:241], v215 offset:52288
	ds_read_b64_tr_b16 v[244:245], v215 offset:52320
	ds_read_b64_tr_b16 v[242:243], v215 offset:53376
	ds_read_b64_tr_b16 v[246:247], v215 offset:53408
	ds_read_b128 v[132:135], v171 offset:320
	s_waitcnt lgkmcnt(0)
	v_pk_mul_f32 v[96:97], v[96:97], v[132:133]
	v_mfma_f32_16x16x32_bf16 v[112:115], v[136:139], v[140:143], v[112:115]
	ds_read_b128 v[136:139], v171 offset:256
	ds_read_b64_tr_b16 v[144:145], v215 offset:52352
	ds_read_b64_tr_b16 v[146:147], v215 offset:53440
	v_pk_mul_f32 v[98:99], v[98:99], v[134:135]
	v_mfma_f32_16x16x32_bf16 v[92:95], v[224:227], v[140:143], v[92:95]
	s_waitcnt lgkmcnt(2)
	v_pk_mul_f32 v[104:105], v[104:105], v[136:137]
	v_pk_mul_f32 v[106:107], v[106:107], v[138:139]
	v_mfma_f32_16x16x32_bf16 v[84:87], v[240:243], v[140:143], v[84:87]
	ds_read_b64_tr_b16 v[138:139], v215 offset:53472
	ds_read_b64_tr_b16 v[136:137], v215 offset:52384
	ds_read_b64_tr_b16 v[224:225], v215 offset:52416
	ds_read_b64_tr_b16 v[240:241], v215 offset:52448
	ds_read_b64_tr_b16 v[226:227], v215 offset:53504
	ds_read_b64_tr_b16 v[242:243], v215 offset:53536
	ds_read_b128 v[132:135], v171 offset:448
	s_waitcnt lgkmcnt(7)
	v_mfma_f32_16x16x32_bf16 v[104:107], v[144:147], v[140:143], v[104:107]
	ds_read_b128 v[144:147], v171 offset:384
	s_waitcnt lgkmcnt(0)
	v_pk_mul_f32 v[100:101], v[100:101], v[144:145]
	v_pk_mul_f32 v[102:103], v[102:103], v[146:147]
	v_mfma_f32_16x16x32_bf16 v[96:99], v[136:139], v[140:143], v[96:99]
	s_nop 0
	v_mfma_f32_16x16x32_bf16 v[136:139], v[224:227], v[140:143], v[100:103]
	v_add_u32_e32 v224, v211, v209
	s_nop 1
	v_pk_mul_f32 v[100:101], v[108:109], v[132:133]
	v_pk_mul_f32 v[102:103], v[110:111], v[134:135]
	v_mfma_f32_16x16x32_bf16 v[88:91], v[244:247], v[140:143], v[88:91]
	s_nop 0
	v_mfma_f32_16x16x32_bf16 v[132:135], v[240:243], v[140:143], v[100:103]
	s_nop 2
	ds_read_b64_tr_b16 v[100:101], v215 offset:60928
	ds_read_b64_tr_b16 v[102:103], v215 offset:62016
	ds_read_b64_tr_b16 v[110:111], v215 offset:62048
	ds_read_b64_tr_b16 v[108:109], v215 offset:60960
	ds_read_b64_tr_b16 v[140:141], v215 offset:60992
	ds_read_b64_tr_b16 v[144:145], v215 offset:61024
	ds_read_b64_tr_b16 v[142:143], v215 offset:62080
	ds_read_b64_tr_b16 v[146:147], v215 offset:62112
	s_waitcnt lgkmcnt(4)
	v_mfma_f32_16x16x32_bf16 v[108:111], v[108:111], v[228:231], v[92:95]
	s_nop 2
	ds_read_b64_tr_b16 v[92:93], v215 offset:61056
	ds_read_b64_tr_b16 v[94:95], v215 offset:62144
	v_mfma_f32_16x16x32_bf16 v[112:115], v[100:103], v[228:231], v[112:115]
	s_waitcnt lgkmcnt(3)
	v_mfma_f32_16x16x32_bf16 v[84:87], v[140:143], v[228:231], v[84:87]
	s_waitcnt lgkmcnt(2)
	v_mfma_f32_16x16x32_bf16 v[88:91], v[144:147], v[228:231], v[88:91]
	ds_read_b64_tr_b16 v[102:103], v215 offset:62176
	ds_read_b64_tr_b16 v[100:101], v215 offset:61088
	ds_read_b64_tr_b16 v[140:141], v215 offset:61120
	ds_read_b64_tr_b16 v[144:145], v215 offset:61152
	ds_read_b64_tr_b16 v[142:143], v215 offset:62208
	ds_read_b64_tr_b16 v[146:147], v215 offset:62240
	s_waitcnt lgkmcnt(6)
	v_mfma_f32_16x16x32_bf16 v[104:107], v[92:95], v[228:231], v[104:107]
	s_waitcnt lgkmcnt(4)
	v_mfma_f32_16x16x32_bf16 v[100:103], v[100:103], v[228:231], v[96:99]
	s_waitcnt lgkmcnt(1)
	v_mfma_f32_16x16x32_bf16 v[92:95], v[140:143], v[228:231], v[136:139]
	s_waitcnt lgkmcnt(0)
	v_mfma_f32_16x16x32_bf16 v[96:99], v[144:147], v[228:231], v[132:135]
	s_nop 2
	v_cvt_pk_bf16_f32 v132, v112, v113
	v_cvt_pk_bf16_f32 v133, v114, v115
	v_cvt_pk_bf16_f32 v134, v108, v109
	v_cvt_pk_bf16_f32 v135, v110, v111
	ds_write2_b64 v224, v[132:133], v[134:135] offset1:4
	v_cvt_pk_bf16_f32 v132, v84, v85
	v_cvt_pk_bf16_f32 v133, v86, v87
	v_cvt_pk_bf16_f32 v134, v88, v89
	v_cvt_pk_bf16_f32 v135, v90, v91
	ds_write2_b64 v224, v[132:133], v[134:135] offset0:8 offset1:12
	v_cvt_pk_bf16_f32 v132, v104, v105
	v_cvt_pk_bf16_f32 v133, v106, v107
	v_cvt_pk_bf16_f32 v134, v100, v101
	v_cvt_pk_bf16_f32 v135, v102, v103
	ds_write2_b64 v224, v[132:133], v[134:135] offset0:16 offset1:20
	v_cvt_pk_bf16_f32 v132, v92, v93
	v_cvt_pk_bf16_f32 v133, v94, v95
	v_cvt_pk_bf16_f32 v134, v96, v97
	v_cvt_pk_bf16_f32 v135, v98, v99
	ds_write2_b64 v224, v[132:133], v[134:135] offset0:24 offset1:28
	v_mul_f32_e32 v132, v129, v129
	v_mul_f32_e32 v133, v131, v131
	v_fmac_f32_e32 v132, v128, v128
	v_fmac_f32_e32 v133, v130, v130
	v_add_f32_e32 v132, v132, v133
	v_mov_b32_e32 v133, v132
	v_mfma_f32_16x16x32_bf16 v[120:123], v[228:231], v[232:235], v[120:123]
	s_nop 0
	v_permlane16_swap_b32_e32 v132, v133
	v_add_f32_e32 v132, v132, v133
	v_mfma_f32_16x16x32_bf16 v[116:119], v[228:231], v[236:239], v[116:119]
	v_mov_b32_e32 v133, v132
	s_nop 1
	v_permlane32_swap_b32_e32 v132, v133
	s_and_saveexec_b64 s[30:31], s[20:21]
	v_add_f32_e32 v132, v132, v133
	ds_write_b32 v217, v132
	s_or_b64 exec, exec, s[30:31]
	v_mul_f32_e32 v132, v125, v125
	v_mul_f32_e32 v133, v127, v127
	v_fmac_f32_e32 v132, v124, v124
	v_fmac_f32_e32 v133, v126, v126
	v_add_f32_e32 v132, v132, v133
	v_mov_b32_e32 v133, v132
	s_nop 1
	v_permlane16_swap_b32_e32 v132, v133
	v_add_f32_e32 v132, v132, v133
	v_mov_b32_e32 v133, v132
	s_nop 1
	v_permlane32_swap_b32_e32 v132, v133
	s_and_saveexec_b64 s[30:31], s[20:21]
	v_add_f32_e32 v132, v132, v133
	ds_write_b32 v217, v132 offset:512
	s_or_b64 exec, exec, s[30:31]
	v_mul_f32_e32 v132, v121, v121
	v_mul_f32_e32 v133, v123, v123
	v_fmac_f32_e32 v132, v120, v120
	v_fmac_f32_e32 v133, v122, v122
	v_add_f32_e32 v132, v132, v133
	v_mov_b32_e32 v133, v132
	s_nop 1
	v_permlane16_swap_b32_e32 v132, v133
	v_add_f32_e32 v132, v132, v133
	v_mov_b32_e32 v133, v132
	s_nop 1
	v_permlane32_swap_b32_e32 v132, v133
	s_and_saveexec_b64 s[30:31], s[20:21]
	v_add_f32_e32 v132, v132, v133
	ds_write_b32 v217, v132 offset:1024
	s_or_b64 exec, exec, s[30:31]
	v_mul_f32_e32 v132, v117, v117
	v_mul_f32_e32 v133, v119, v119
	v_fmac_f32_e32 v132, v116, v116
	v_fmac_f32_e32 v133, v118, v118
	v_add_f32_e32 v132, v132, v133
	v_mov_b32_e32 v133, v132
	s_nop 1
	v_permlane16_swap_b32_e32 v132, v133
	v_add_f32_e32 v132, v132, v133
	v_mov_b32_e32 v133, v132
	s_nop 1
	v_permlane32_swap_b32_e32 v132, v133
	s_and_saveexec_b64 s[30:31], s[20:21]
	v_add_f32_e32 v132, v132, v133
	ds_write_b32 v217, v132 offset:1536
	s_or_b64 exec, exec, s[30:31]
	s_waitcnt lgkmcnt(0)
	s_barrier
	ds_read_b128 v[132:135], v216
	ds_read_b128 v[136:139], v216 offset:16
	v_add_u32_e32 v154, 0xffffff90, v170
	s_waitcnt lgkmcnt(1)
	v_mov_b32_e32 v140, v132
	s_waitcnt lgkmcnt(0)
	v_mov_b32_e32 v141, v136
	v_mov_b32_e32 v136, v133
	v_pk_add_f32 v[132:133], v[140:141], v[136:137]
	v_mov_b32_e32 v136, v134
	v_mov_b32_e32 v137, v138
	v_mov_b32_e32 v138, v135
	v_pk_add_f32 v[134:135], v[136:137], v[138:139]
	s_nop 0
	v_pk_add_f32 v[132:133], v[132:133], v[134:135]
	v_lshlrev_b32_e32 v134, 16, v195
	v_add_f32_e32 v132, v132, v133
	v_fmamk_f32 v132, v132, 0x3c000000, v151
	v_rsq_f32_e32 v132, v132
	v_and_b32_e32 v135, 0xffff0000, v195
	v_mul_f32_e32 v138, 0xbfb8aa3b, v134
	v_mul_f32_e32 v139, 0xbfb8aa3b, v135
	v_pk_mul_f32 v[130:131], v[130:131], v[132:133] op_sel_hi:[1,0]
	v_pk_mul_f32 v[128:129], v[128:129], v[132:133] op_sel_hi:[1,0]
	v_pk_mul_f32 v[136:137], v[2:3], v[130:131]
	v_lshlrev_b32_e32 v130, 16, v194
	v_and_b32_e32 v131, 0xffff0000, v194
	v_mul_f32_e32 v132, 0xbfb8aa3b, v130
	v_mul_f32_e32 v133, 0xbfb8aa3b, v131
	v_exp_f32_e32 v132, v132
	v_exp_f32_e32 v133, v133
	v_exp_f32_e32 v138, v138
	v_exp_f32_e32 v139, v139
	v_add_f32_e32 v132, 1.0, v132
	v_add_f32_e32 v133, 1.0, v133
	v_rcp_f32_e32 v132, v132
	v_rcp_f32_e32 v133, v133
	v_add_f32_e32 v138, 1.0, v138
	v_add_f32_e32 v139, 1.0, v139
	v_rcp_f32_e32 v138, v138
	v_rcp_f32_e32 v139, v139
	v_pk_mul_f32 v[128:129], v[0:1], v[128:129]
	v_pk_mul_f32 v[130:131], v[132:133], v[130:131]
	v_pk_mul_f32 v[138:139], v[138:139], v[134:135]
	v_pk_mul_f32 v[128:129], v[130:131], v[128:129]
	v_pk_mul_f32 v[136:137], v[138:139], v[136:137]
	v_cvt_pk_bf16_f32 v140, v128, v129
	ds_read_b128 v[128:131], v216 offset:512
	ds_read_b128 v[132:135], v216 offset:528
	v_cvt_pk_bf16_f32 v141, v136, v137
	s_waitcnt lgkmcnt(1)
	v_mov_b32_e32 v136, v128
	s_waitcnt lgkmcnt(0)
	v_mov_b32_e32 v137, v132
	v_mov_b32_e32 v132, v129
	v_pk_add_f32 v[128:129], v[136:137], v[132:133]
	v_mov_b32_e32 v132, v130
	v_mov_b32_e32 v133, v134
	v_mov_b32_e32 v134, v131
	v_pk_add_f32 v[130:131], v[132:133], v[134:135]
	s_nop 0
	v_pk_add_f32 v[128:129], v[128:129], v[130:131]
	v_lshlrev_b64 v[130:131], 7, v[154:155]
	v_add_f32_e32 v128, v128, v129
	v_fmamk_f32 v128, v128, 0x3c000000, v151
	v_rsq_f32_e32 v128, v128
	v_lshl_add_u64 v[130:131], v[158:159], 0, v[130:131]
	global_store_dwordx2 v[130:131], v[140:141], off nt
	v_lshlrev_b32_e32 v130, 16, v193
	v_pk_mul_f32 v[126:127], v[126:127], v[128:129] op_sel_hi:[1,0]
	v_pk_mul_f32 v[124:125], v[124:125], v[128:129] op_sel_hi:[1,0]
	v_pk_mul_f32 v[132:133], v[2:3], v[126:127]
	v_lshlrev_b32_e32 v126, 16, v192
	v_and_b32_e32 v127, 0xffff0000, v192
	v_mul_f32_e32 v128, 0xbfb8aa3b, v126
	v_mul_f32_e32 v129, 0xbfb8aa3b, v127
	v_exp_f32_e32 v128, v128
	v_exp_f32_e32 v129, v129
	v_and_b32_e32 v131, 0xffff0000, v193
	v_mul_f32_e32 v134, 0xbfb8aa3b, v130
	v_mul_f32_e32 v135, 0xbfb8aa3b, v131
	v_exp_f32_e32 v134, v134
	v_exp_f32_e32 v135, v135
	v_add_f32_e32 v128, 1.0, v128
	v_add_f32_e32 v129, 1.0, v129
	v_rcp_f32_e32 v128, v128
	v_rcp_f32_e32 v129, v129
	v_add_f32_e32 v134, 1.0, v134
	v_add_f32_e32 v135, 1.0, v135
	v_rcp_f32_e32 v134, v134
	v_rcp_f32_e32 v135, v135
	v_pk_mul_f32 v[124:125], v[0:1], v[124:125]
	v_pk_mul_f32 v[126:127], v[128:129], v[126:127]
	v_add_u32_e32 v154, 0xffffffa0, v170
	v_pk_mul_f32 v[124:125], v[126:127], v[124:125]
	v_pk_mul_f32 v[134:135], v[134:135], v[130:131]
	v_cvt_pk_bf16_f32 v136, v124, v125
	ds_read_b128 v[124:127], v216 offset:1024
	ds_read_b128 v[128:131], v216 offset:1040
	v_pk_mul_f32 v[132:133], v[134:135], v[132:133]
	s_nop 0
	v_cvt_pk_bf16_f32 v137, v132, v133
	s_waitcnt lgkmcnt(1)
	v_mov_b32_e32 v132, v124
	s_waitcnt lgkmcnt(0)
	v_mov_b32_e32 v133, v128
	v_mov_b32_e32 v128, v125
	v_pk_add_f32 v[124:125], v[132:133], v[128:129]
	v_mov_b32_e32 v128, v126
	v_mov_b32_e32 v129, v130
	v_mov_b32_e32 v130, v127
	v_pk_add_f32 v[126:127], v[128:129], v[130:131]
	s_nop 0
	v_pk_add_f32 v[124:125], v[124:125], v[126:127]
	v_lshlrev_b64 v[126:127], 7, v[154:155]
	v_add_f32_e32 v124, v124, v125
	v_fmamk_f32 v124, v124, 0x3c000000, v151
	v_rsq_f32_e32 v124, v124
	v_lshl_add_u64 v[126:127], v[158:159], 0, v[126:127]
	global_store_dwordx2 v[126:127], v[136:137], off nt
	v_lshlrev_b32_e32 v126, 16, v191
	v_pk_mul_f32 v[122:123], v[122:123], v[124:125] op_sel_hi:[1,0]
	v_pk_mul_f32 v[120:121], v[120:121], v[124:125] op_sel_hi:[1,0]
	v_pk_mul_f32 v[128:129], v[2:3], v[122:123]
	v_lshlrev_b32_e32 v122, 16, v190
	v_and_b32_e32 v123, 0xffff0000, v190
	v_mul_f32_e32 v124, 0xbfb8aa3b, v122
	v_mul_f32_e32 v125, 0xbfb8aa3b, v123
	v_exp_f32_e32 v124, v124
	v_exp_f32_e32 v125, v125
	v_and_b32_e32 v127, 0xffff0000, v191
	v_mul_f32_e32 v130, 0xbfb8aa3b, v126
	v_mul_f32_e32 v131, 0xbfb8aa3b, v127
	v_exp_f32_e32 v130, v130
	v_exp_f32_e32 v131, v131
	v_add_f32_e32 v124, 1.0, v124
	v_add_f32_e32 v125, 1.0, v125
	v_rcp_f32_e32 v124, v124
	v_rcp_f32_e32 v125, v125
	v_add_f32_e32 v130, 1.0, v130
	v_add_f32_e32 v131, 1.0, v131
	v_rcp_f32_e32 v130, v130
	v_rcp_f32_e32 v131, v131
	v_pk_mul_f32 v[120:121], v[0:1], v[120:121]
	v_pk_mul_f32 v[122:123], v[124:125], v[122:123]
	v_add_u32_e32 v154, 0xffffffb0, v170
	v_pk_mul_f32 v[120:121], v[122:123], v[120:121]
	v_pk_mul_f32 v[130:131], v[130:131], v[126:127]
	v_cvt_pk_bf16_f32 v132, v120, v121
	ds_read_b128 v[120:123], v216 offset:1536
	ds_read_b128 v[124:127], v216 offset:1552
	v_pk_mul_f32 v[128:129], v[130:131], v[128:129]
	s_nop 0
	v_cvt_pk_bf16_f32 v133, v128, v129
	s_waitcnt lgkmcnt(1)
	v_mov_b32_e32 v128, v120
	s_waitcnt lgkmcnt(0)
	v_mov_b32_e32 v129, v124
	v_mov_b32_e32 v124, v121
	v_pk_add_f32 v[120:121], v[128:129], v[124:125]
	v_mov_b32_e32 v124, v122
	v_mov_b32_e32 v125, v126
	v_mov_b32_e32 v126, v123
	v_pk_add_f32 v[122:123], v[124:125], v[126:127]
	v_lshlrev_b32_e32 v124, 16, v189
	v_pk_add_f32 v[120:121], v[120:121], v[122:123]
	v_lshlrev_b64 v[122:123], 7, v[154:155]
	v_add_f32_e32 v120, v120, v121
	v_fmamk_f32 v120, v120, 0x3c000000, v151
	v_rsq_f32_e32 v120, v120
	v_lshl_add_u64 v[122:123], v[158:159], 0, v[122:123]
	global_store_dwordx2 v[122:123], v[132:133], off nt
	v_and_b32_e32 v125, 0xffff0000, v189
	v_pk_mul_f32 v[116:117], v[116:117], v[120:121] op_sel_hi:[1,0]
	v_pk_mul_f32 v[118:119], v[118:119], v[120:121] op_sel_hi:[1,0]
	v_lshlrev_b32_e32 v120, 16, v188
	v_and_b32_e32 v121, 0xffff0000, v188
	v_mul_f32_e32 v122, 0xbfb8aa3b, v120
	v_mul_f32_e32 v123, 0xbfb8aa3b, v121
	v_exp_f32_e32 v122, v122
	v_exp_f32_e32 v123, v123
	v_mul_f32_e32 v126, 0xbfb8aa3b, v124
	v_mul_f32_e32 v127, 0xbfb8aa3b, v125
	v_exp_f32_e32 v126, v126
	v_exp_f32_e32 v127, v127
	v_add_f32_e32 v122, 1.0, v122
	v_add_f32_e32 v123, 1.0, v123
	v_rcp_f32_e32 v122, v122
	v_rcp_f32_e32 v123, v123
	v_add_f32_e32 v126, 1.0, v126
	v_add_f32_e32 v127, 1.0, v127
	v_rcp_f32_e32 v126, v126
	v_rcp_f32_e32 v127, v127
	v_pk_mul_f32 v[116:117], v[0:1], v[116:117]
	v_pk_mul_f32 v[120:121], v[122:123], v[120:121]
	v_pk_mul_f32 v[118:119], v[2:3], v[118:119]
	v_pk_mul_f32 v[116:117], v[120:121], v[116:117]
	v_pk_mul_f32 v[120:121], v[126:127], v[124:125]
	v_subrev_u32_e32 v154, 64, v170
	v_pk_mul_f32 v[118:119], v[120:121], v[118:119]
	v_cvt_pk_bf16_f32 v116, v116, v117
	v_cvt_pk_bf16_f32 v117, v118, v119
	v_lshlrev_b64 v[118:119], 7, v[154:155]
	v_lshl_add_u64 v[118:119], v[158:159], 0, v[118:119]
	global_store_dwordx2 v[118:119], v[116:117], off nt
	ds_write_b128 v204, v[36:39]
	ds_write_b128 v204, v[44:47] offset:34816
	ds_write_b128 v204, v[56:59] offset:52224
	ds_write_b128 v218, v[40:43]
	ds_write_b128 v205, v[60:63]
	ds_write_b128 v205, v[68:71] offset:34816
	ds_write_b128 v205, v[72:75] offset:52224
	ds_write_b128 v219, v[64:67]
	s_and_saveexec_b64 s[30:31], s[6:7]
	ds_write_b32 v206, v203
	s_or_b64 exec, exec, s[30:31]
	s_andn2_b64 vcc, exec, s[42:43]
	v_mov_b64_e32 v[190:191], v[176:177]
	v_mov_b64_e32 v[192:193], v[174:175]
	v_mov_b64_e32 v[194:195], v[172:173]
	v_mov_b64_e32 v[198:199], v[156:157]
	ds_write_b128 v207, v[76:79]
	ds_write_b128 v208, v[80:83]
	s_cbranch_vccnz .LBB0_2257
	v_add_co_u32_e32 v36, vcc, 0x49ab0000, v196
	v_mov_b32_e32 v203, 0
	s_nop 0
	v_addc_co_u32_e32 v37, vcc, 0, v197, vcc
	v_add_co_u32_e32 v40, vcc, 0x49ab4000, v196
	s_nop 1
	v_addc_co_u32_e32 v41, vcc, 0, v197, vcc
	v_add_co_u32_e32 v44, vcc, 0x49ab8000, v196
	global_load_dwordx4 v[36:39], v[36:37], off offset:1536
	s_nop 0
	global_load_dwordx4 v[40:43], v[40:41], off offset:1536
	v_addc_co_u32_e32 v45, vcc, 0, v197, vcc
	v_add_co_u32_e32 v56, vcc, 0x49abc000, v196
	s_nop 1
	v_addc_co_u32_e32 v57, vcc, 0, v197, vcc
	v_add_co_u32_e32 v60, vcc, 0x49ab2000, v196
	global_load_dwordx4 v[44:47], v[44:45], off offset:1536
	s_nop 0
	global_load_dwordx4 v[56:59], v[56:57], off offset:1536
	v_addc_co_u32_e32 v61, vcc, 0, v197, vcc
	v_add_co_u32_e32 v64, vcc, 0x49ab6000, v196
	s_nop 1
	v_addc_co_u32_e32 v65, vcc, 0, v197, vcc
	v_add_co_u32_e32 v68, vcc, 0x49aba000, v196
	global_load_dwordx4 v[60:63], v[60:61], off offset:1536
	s_nop 0
	global_load_dwordx4 v[64:67], v[64:65], off offset:1536
	v_addc_co_u32_e32 v69, vcc, 0, v197, vcc
	v_add_co_u32_e32 v72, vcc, 0x49abe000, v196
	s_nop 1
	v_addc_co_u32_e32 v73, vcc, 0, v197, vcc
	global_load_dwordx4 v[68:71], v[68:69], off offset:1536
	s_nop 0
	global_load_dwordx4 v[72:75], v[72:73], off offset:1536
	s_and_saveexec_b64 s[30:31], s[6:7]
	s_cbranch_execz .LBB0_2256
	v_lshl_add_u64 v[76:77], s[48:49], 0, v[168:169]
	v_add_co_u32_e32 v76, vcc, 0x49ac0000, v76
	s_nop 1
	v_addc_co_u32_e32 v77, vcc, 0, v77, vcc
	global_load_dword v203, v[76:77], off offset:1536

.LBB0_2287:
	s_or_b64 exec, exec, s[22:23]
	s_waitcnt lgkmcnt(0)
	s_barrier
	ds_read_b128 v[84:87], v158
	ds_read_b128 v[88:91], v158 offset:16
	s_add_i32 s33, s33, 2
	v_lshl_add_u64 v[102:103], v[102:103], 0, s[36:37]
	v_lshl_add_u64 v[104:105], v[104:105], 0, s[36:37]
	s_waitcnt lgkmcnt(1)
	v_mov_b32_e32 v92, v84
	s_waitcnt lgkmcnt(0)
	v_mov_b32_e32 v93, v88
	v_mov_b32_e32 v88, v85
	v_pk_add_f32 v[84:85], v[92:93], v[88:89]
	v_mov_b32_e32 v88, v86
	v_mov_b32_e32 v89, v90
	v_mov_b32_e32 v90, v87
	v_pk_add_f32 v[86:87], v[88:89], v[90:91]
	v_lshlrev_b32_e32 v88, 16, v119
	v_pk_add_f32 v[84:85], v[84:85], v[86:87]
	v_and_b32_e32 v89, 0xffff0000, v119
	v_add_f32_e32 v84, v84, v85
	v_fmamk_f32 v84, v84, 0x3c000000, v151
	v_rsq_f32_e32 v84, v84
	v_mul_f32_e32 v90, 0xbfb8aa3b, v88
	v_mul_f32_e32 v91, 0xbfb8aa3b, v89
	v_exp_f32_e32 v90, v90
	v_pk_mul_f32 v[80:81], v[80:81], v[84:85] op_sel_hi:[1,0]
	v_pk_mul_f32 v[82:83], v[82:83], v[84:85] op_sel_hi:[1,0]
	v_lshlrev_b32_e32 v84, 16, v118
	v_and_b32_e32 v85, 0xffff0000, v118
	v_mul_f32_e32 v86, 0xbfb8aa3b, v84
	v_mul_f32_e32 v87, 0xbfb8aa3b, v85
	v_exp_f32_e32 v86, v86
	v_exp_f32_e32 v87, v87
	v_exp_f32_e32 v91, v91
	v_add_f32_e32 v90, 1.0, v90
	v_add_f32_e32 v86, 1.0, v86
	v_add_f32_e32 v87, 1.0, v87
	v_rcp_f32_e32 v86, v86
	v_rcp_f32_e32 v87, v87
	v_add_f32_e32 v91, 1.0, v91
	v_rcp_f32_e32 v90, v90
	v_rcp_f32_e32 v91, v91
	v_pk_mul_f32 v[80:81], v[0:1], v[80:81]
	v_pk_mul_f32 v[84:85], v[86:87], v[84:85]
	v_pk_mul_f32 v[82:83], v[2:3], v[82:83]
	v_pk_mul_f32 v[80:81], v[84:85], v[80:81]
	v_lshl_add_u64 v[106:107], v[106:107], 0, s[36:37]
	v_cvt_pk_bf16_f32 v92, v80, v81
	v_pk_mul_f32 v[80:81], v[90:91], v[88:89]
	v_add_co_u32_e32 v88, vcc, s4, v134
	v_pk_mul_f32 v[80:81], v[80:81], v[82:83]
	s_nop 0
	v_addc_co_u32_e32 v89, vcc, 0, v135, vcc
	v_cvt_pk_bf16_f32 v93, v80, v81
	ds_read_b128 v[80:83], v158 offset:512
	ds_read_b128 v[84:87], v158 offset:528
	v_lshl_add_u64 v[108:109], v[108:109], 0, s[38:39]
	v_lshl_add_u64 v[110:111], v[110:111], 0, s[38:39]
	v_lshl_add_u64 v[112:113], v[112:113], 0, s[40:41]
	s_waitcnt lgkmcnt(1)
	v_mov_b32_e32 v90, v80
	s_waitcnt lgkmcnt(0)
	v_mov_b32_e32 v91, v84
	v_mov_b32_e32 v84, v81
	v_pk_add_f32 v[80:81], v[90:91], v[84:85]
	v_mov_b32_e32 v84, v82
	v_mov_b32_e32 v85, v86
	v_mov_b32_e32 v86, v83
	v_pk_add_f32 v[82:83], v[84:85], v[86:87]
	v_add_co_u32_e32 v84, vcc, s5, v134
	v_pk_add_f32 v[80:81], v[80:81], v[82:83]
	s_nop 0
	v_addc_co_u32_e32 v85, vcc, 0, v135, vcc
	v_add_f32_e32 v80, v80, v81
	v_fmamk_f32 v80, v80, 0x3c000000, v151
	v_rsq_f32_e32 v80, v80
	global_store_dwordx2 v[84:85], v[92:93], off offset:-4096 nt
	v_lshlrev_b32_e32 v92, 16, v117
	v_and_b32_e32 v93, 0xffff0000, v117
	v_pk_mul_f32 v[78:79], v[78:79], v[80:81] op_sel_hi:[1,0]
	v_pk_mul_f32 v[76:77], v[76:77], v[80:81] op_sel_hi:[1,0]
	v_pk_mul_f32 v[86:87], v[2:3], v[78:79]
	v_lshlrev_b32_e32 v78, 16, v116
	v_and_b32_e32 v79, 0xffff0000, v116
	v_mul_f32_e32 v80, 0xbfb8aa3b, v78
	v_mul_f32_e32 v81, 0xbfb8aa3b, v79
	v_exp_f32_e32 v80, v80
	v_exp_f32_e32 v81, v81
	v_pk_mul_f32 v[90:91], v[0:1], v[76:77]
	s_andn2_b64 vcc, exec, s[42:43]
	v_add_f32_e32 v76, 1.0, v80
	v_add_f32_e32 v77, 1.0, v81
	v_mul_f32_e32 v80, 0xbfb8aa3b, v92
	v_rcp_f32_e32 v76, v76
	v_rcp_f32_e32 v77, v77
	v_exp_f32_e32 v80, v80
	v_mul_f32_e32 v81, 0xbfb8aa3b, v93
	v_exp_f32_e32 v81, v81
	v_pk_mul_f32 v[94:95], v[76:77], v[78:79]
	v_add_f32_e32 v76, 1.0, v80
	v_rcp_f32_e32 v96, v76
	v_add_f32_e32 v76, 1.0, v81
	v_rcp_f32_e32 v97, v76
	ds_read_b128 v[76:79], v158 offset:1024
	ds_read_b128 v[80:83], v158 offset:1040
	v_pk_mul_f32 v[90:91], v[94:95], v[90:91]
	s_waitcnt vmcnt(5)
	v_mov_b64_e32 v[128:129], v[126:127]
	v_pk_mul_f32 v[92:93], v[96:97], v[92:93]
	s_waitcnt lgkmcnt(1)
	v_mov_b32_e32 v94, v76
	s_waitcnt lgkmcnt(0)
	v_mov_b32_e32 v95, v80
	v_mov_b32_e32 v80, v77
	v_pk_add_f32 v[76:77], v[94:95], v[80:81]
	v_mov_b32_e32 v80, v78
	v_mov_b32_e32 v81, v82
	v_mov_b32_e32 v82, v79
	v_pk_add_f32 v[78:79], v[80:81], v[82:83]
	v_cvt_pk_bf16_f32 v90, v90, v91
	v_pk_add_f32 v[76:77], v[76:77], v[78:79]
	v_pk_mul_f32 v[78:79], v[92:93], v[86:87]
	v_add_f32_e32 v76, v76, v77
	v_fmamk_f32 v76, v76, 0x3c000000, v151
	v_rsq_f32_e32 v76, v76
	v_lshlrev_b32_e32 v86, 16, v115
	v_and_b32_e32 v87, 0xffff0000, v115
	v_cvt_pk_bf16_f32 v91, v78, v79
	v_pk_mul_f32 v[74:75], v[74:75], v[76:77] op_sel_hi:[1,0]
	v_pk_mul_f32 v[72:73], v[72:73], v[76:77] op_sel_hi:[1,0]
	v_pk_mul_f32 v[80:81], v[2:3], v[74:75]
	v_lshlrev_b32_e32 v74, 16, v114
	v_and_b32_e32 v75, 0xffff0000, v114
	v_mul_f32_e32 v76, 0xbfb8aa3b, v74
	v_mul_f32_e32 v77, 0xbfb8aa3b, v75
	v_exp_f32_e32 v76, v76
	v_exp_f32_e32 v77, v77
	v_pk_mul_f32 v[82:83], v[0:1], v[72:73]
	global_store_dwordx2 v[88:89], v[90:91], off offset:2048 nt
	v_add_f32_e32 v72, 1.0, v76
	v_add_f32_e32 v73, 1.0, v77
	v_mul_f32_e32 v76, 0xbfb8aa3b, v86
	v_rcp_f32_e32 v72, v72
	v_rcp_f32_e32 v73, v73
	v_exp_f32_e32 v76, v76
	v_mul_f32_e32 v77, 0xbfb8aa3b, v87
	v_exp_f32_e32 v77, v77
	v_pk_mul_f32 v[88:89], v[72:73], v[74:75]
	v_add_f32_e32 v72, 1.0, v76
	v_rcp_f32_e32 v90, v72
	v_add_f32_e32 v72, 1.0, v77
	v_rcp_f32_e32 v91, v72
	ds_read_b128 v[72:75], v158 offset:1536
	ds_read_b128 v[76:79], v158 offset:1552
	v_pk_mul_f32 v[82:83], v[88:89], v[82:83]
	s_waitcnt vmcnt(5)
	v_mov_b64_e32 v[118:119], v[130:131]
	v_pk_mul_f32 v[86:87], v[90:91], v[86:87]
	s_waitcnt lgkmcnt(1)
	v_mov_b32_e32 v88, v72
	s_waitcnt lgkmcnt(0)
	v_mov_b32_e32 v89, v76
	v_mov_b32_e32 v76, v73
	v_pk_add_f32 v[72:73], v[88:89], v[76:77]
	v_mov_b32_e32 v76, v74
	v_mov_b32_e32 v77, v78
	v_mov_b32_e32 v78, v75
	v_pk_add_f32 v[74:75], v[76:77], v[78:79]
	v_cvt_pk_bf16_f32 v82, v82, v83
	v_pk_add_f32 v[72:73], v[72:73], v[74:75]
	v_pk_mul_f32 v[74:75], v[86:87], v[80:81]
	v_add_f32_e32 v72, v72, v73
	v_fmamk_f32 v72, v72, 0x3c000000, v151
	v_rsq_f32_e32 v72, v72
	v_cvt_pk_bf16_f32 v83, v74, v75
	v_lshlrev_b32_e32 v76, 16, v101
	v_and_b32_e32 v77, 0xffff0000, v101
	v_pk_mul_f32 v[68:69], v[68:69], v[72:73] op_sel_hi:[1,0]
	v_pk_mul_f32 v[70:71], v[70:71], v[72:73] op_sel_hi:[1,0]
	v_lshlrev_b32_e32 v72, 16, v100
	v_and_b32_e32 v73, 0xffff0000, v100
	v_mul_f32_e32 v74, 0xbfb8aa3b, v72
	v_mul_f32_e32 v75, 0xbfb8aa3b, v73
	v_exp_f32_e32 v74, v74
	v_exp_f32_e32 v75, v75
	v_mul_f32_e32 v78, 0xbfb8aa3b, v76
	v_mul_f32_e32 v79, 0xbfb8aa3b, v77
	v_exp_f32_e32 v78, v78
	v_exp_f32_e32 v79, v79
	v_add_f32_e32 v74, 1.0, v74
	v_add_f32_e32 v75, 1.0, v75
	v_rcp_f32_e32 v74, v74
	v_rcp_f32_e32 v75, v75
	v_add_f32_e32 v78, 1.0, v78
	v_add_f32_e32 v79, 1.0, v79
	v_rcp_f32_e32 v78, v78
	v_rcp_f32_e32 v79, v79
	v_pk_mul_f32 v[68:69], v[0:1], v[68:69]
	v_pk_mul_f32 v[72:73], v[74:75], v[72:73]
	v_pk_mul_f32 v[70:71], v[2:3], v[70:71]
	v_pk_mul_f32 v[68:69], v[72:73], v[68:69]
	v_pk_mul_f32 v[72:73], v[78:79], v[76:77]
	v_cvt_pk_bf16_f32 v68, v68, v69
	v_pk_mul_f32 v[70:71], v[72:73], v[70:71]
	s_waitcnt vmcnt(4)
	v_mov_b64_e32 v[116:117], v[132:133]
	v_cvt_pk_bf16_f32 v69, v70, v71
	s_waitcnt vmcnt(3)
	v_mov_b64_e32 v[114:115], v[138:139]
	s_waitcnt vmcnt(2)
	v_mov_b64_e32 v[100:101], v[140:141]
	v_mov_b64_e32 v[130:131], v[124:125]
	v_mov_b64_e32 v[132:133], v[122:123]
	v_mov_b64_e32 v[134:135], v[120:121]
	global_store_dwordx2 v[84:85], v[82:83], off nt
	global_store_dwordx2 v[84:85], v[68:69], off offset:2048 nt
	s_cbranch_vccz .LBB0_2328

.LBB0_2300:
	v_mov_b32_e32 v92, s28
	s_nop 5
	v_cndmask_b32_e64 v92, v88, v92, s[12:13]
	v_cndmask_b32_e64 v92, v92, v88, s[14:15]
	v_cndmask_b32_e64 v92, v88, v92, s[8:9]
	v_mov_b32_e32 v88, s28
	v_cndmask_b32_e64 v93, 0, v89, s[14:15]
	v_cndmask_b32_e64 v94, v90, 0, s[16:17]
	v_cndmask_b32_e64 v95, v91, 0, s[18:19]
	v_cndmask_b32_e64 v88, v84, v88, s[12:13]
	v_cndmask_b32_e64 v89, v89, v93, s[8:9]
	v_cndmask_b32_e64 v91, v91, v95, s[8:9]
	v_cndmask_b32_e64 v90, v90, v94, s[8:9]
	v_cndmask_b32_e64 v93, 0, v85, s[14:15]
	v_cndmask_b32_e64 v88, v88, v84, s[14:15]
	v_cndmask_b32_e64 v94, v86, 0, s[16:17]
	v_cndmask_b32_e64 v95, v87, 0, s[18:19]
	v_cndmask_b32_e64 v93, v85, v93, s[10:11]
	v_cndmask_b32_e64 v87, v87, v95, s[10:11]
	v_cndmask_b32_e64 v94, v86, v94, s[10:11]
	v_cndmask_b32_e64 v86, v84, v88, s[10:11]
	v_cvt_pk_bf16_f32 v84, v92, v89
	v_cvt_pk_bf16_f32 v85, v90, v91
	v_cvt_pk_bf16_f32 v86, v86, v93
	v_cvt_pk_bf16_f32 v87, v94, v87
	ds_write2_b64 v163, v[84:85], v[86:87] offset1:4
	s_waitcnt lgkmcnt(0)
	s_barrier
	ds_read_b64_tr_b16 v[84:85], v164 offset:36864
	ds_read_b64_tr_b16 v[86:87], v164 offset:37952
	v_add_u32_e32 v88, 0, v157
	v_add_u32_e32 v167, 0x14000, v88
	ds_read_b128 v[88:91], v165
	ds_read_b128 v[92:95], v167
	ds_read_b128 v[96:99], v165 offset:2304
	ds_read_b64_tr_b16 v[138:139], v164 offset:45568
	ds_read_b64_tr_b16 v[140:141], v164 offset:46656
	s_waitcnt lgkmcnt(4)
	v_mfma_f32_16x16x32_bf16 v[80:83], v[84:87], v[88:91], v[80:83]
	ds_read_b128 v[88:91], v167 offset:64
	ds_read_b128 v[168:171], v165 offset:4608
	s_waitcnt lgkmcnt(5)
	v_pk_mul_f32 v[52:53], v[52:53], v[92:93]
	s_waitcnt lgkmcnt(4)
	v_mfma_f32_16x16x32_bf16 v[76:79], v[84:87], v[96:99], v[76:79]
	v_mul_f32_e64 v54, v54, v94
	v_mul_f32_e64 v55, v55, v95
	ds_read_b128 v[92:95], v165 offset:6912
	ds_read_b128 v[96:99], v165 offset:4672
	s_waitcnt lgkmcnt(3)
	v_pk_mul_f32 v[56:57], v[56:57], v[88:89]
	s_waitcnt lgkmcnt(2)
	v_mfma_f32_16x16x32_bf16 v[72:75], v[84:87], v[168:171], v[72:75]
	ds_read_b64_tr_b16 v[170:171], v166 offset:28224
	ds_read_b64_tr_b16 v[168:169], v166 offset:27648
	ds_read_b128 v[172:175], v165 offset:6976
	v_pk_mul_f32 v[58:59], v[58:59], v[90:91]
	s_waitcnt lgkmcnt(4)
	v_mfma_f32_16x16x32_bf16 v[68:71], v[84:87], v[92:95], v[68:71]
	ds_read_b64_tr_b16 v[94:95], v166 offset:28256
	ds_read_b64_tr_b16 v[92:93], v166 offset:27680
	ds_read_b64_tr_b16 v[176:177], v166 offset:27712
	ds_read_b64_tr_b16 v[182:183], v166 offset:27744
	ds_read_b64_tr_b16 v[178:179], v166 offset:28288
	ds_read_b64_tr_b16 v[184:185], v166 offset:28320
	ds_read_b128 v[88:91], v167 offset:192
	s_waitcnt lgkmcnt(8)
	v_mfma_f32_16x16x32_bf16 v[52:55], v[168:171], v[84:87], v[52:55]
	ds_read_b128 v[168:171], v167 offset:128
	s_waitcnt lgkmcnt(0)
	v_pk_mul_f32 v[60:61], v[60:61], v[168:169]
	v_pk_mul_f32 v[62:63], v[62:63], v[170:171]
	v_mfma_f32_16x16x32_bf16 v[56:59], v[92:95], v[84:87], v[56:59]
	s_nop 0
	v_mfma_f32_16x16x32_bf16 v[92:95], v[176:179], v[84:87], v[60:63]
	s_nop 2
	v_mul_f32_e64 v60, v64, v88
	v_mul_f32_e64 v61, v65, v89
	v_pk_mul_f32 v[62:63], v[66:67], v[90:91]
	v_mfma_f32_16x16x32_bf16 v[72:75], v[138:141], v[96:99], v[72:75]
	s_nop 0
	v_mfma_f32_16x16x32_bf16 v[84:87], v[182:185], v[84:87], v[60:63]
	s_nop 2
	ds_read_b64_tr_b16 v[60:61], v166 offset:32256
	ds_read_b64_tr_b16 v[62:63], v166 offset:32832
	ds_read_b64_tr_b16 v[90:91], v166 offset:32864
	ds_read_b64_tr_b16 v[88:89], v166 offset:32288
	ds_read_b64_tr_b16 v[96:97], v166 offset:32320
	ds_read_b64_tr_b16 v[168:169], v166 offset:32352
	ds_read_b64_tr_b16 v[98:99], v166 offset:32896
	ds_read_b64_tr_b16 v[170:171], v166 offset:32928
	s_waitcnt lgkmcnt(6)
	v_mfma_f32_16x16x32_bf16 v[64:67], v[60:63], v[138:141], v[52:55]
	s_waitcnt lgkmcnt(4)
	v_mfma_f32_16x16x32_bf16 v[60:63], v[88:91], v[138:141], v[56:59]
	v_add_u32_e32 v88, v155, v149
	s_waitcnt lgkmcnt(1)
	v_mfma_f32_16x16x32_bf16 v[52:55], v[96:99], v[138:141], v[92:95]
	s_waitcnt lgkmcnt(0)
	v_mfma_f32_16x16x32_bf16 v[56:59], v[168:171], v[138:141], v[84:87]
	v_add_u32_e32 v168, 0xd000, v88
	s_nop 1
	v_cvt_pk_bf16_f32 v84, v64, v65
	v_cvt_pk_bf16_f32 v85, v66, v67
	v_cvt_pk_bf16_f32 v86, v60, v61
	v_cvt_pk_bf16_f32 v87, v62, v63
	ds_write2_b64 v168, v[84:85], v[86:87] offset0:128 offset1:132
	v_cvt_pk_bf16_f32 v84, v52, v53
	v_cvt_pk_bf16_f32 v85, v54, v55
	v_cvt_pk_bf16_f32 v86, v56, v57
	v_cvt_pk_bf16_f32 v87, v58, v59
	ds_write2_b64 v168, v[84:85], v[86:87] offset0:136 offset1:140
	v_mul_f32_e32 v84, v81, v81
	v_mul_f32_e32 v85, v83, v83
	v_fmac_f32_e32 v84, v80, v80
	v_fmac_f32_e32 v85, v82, v82
	v_add_f32_e32 v84, v84, v85
	v_mov_b32_e32 v85, v84
	v_mfma_f32_16x16x32_bf16 v[68:71], v[138:141], v[172:175], v[68:71]
	s_nop 0
	v_permlane16_swap_b32_e32 v84, v85
	v_add_f32_e32 v84, v84, v85
	v_mov_b32_e32 v85, v84
	s_nop 1
	v_permlane32_swap_b32_e32 v84, v85
	s_and_saveexec_b64 s[30:31], s[20:21]
	v_add_f32_e32 v84, v84, v85
	ds_write_b32 v159, v84
	s_or_b64 exec, exec, s[30:31]
	v_mul_f32_e32 v84, v77, v77
	v_mul_f32_e32 v85, v79, v79
	v_fmac_f32_e32 v84, v76, v76
	v_fmac_f32_e32 v85, v78, v78
	v_add_f32_e32 v84, v84, v85
	v_mov_b32_e32 v85, v84
	s_nop 1
	v_permlane16_swap_b32_e32 v84, v85
	v_add_f32_e32 v84, v84, v85
	v_mov_b32_e32 v85, v84
	s_nop 1
	v_permlane32_swap_b32_e32 v84, v85
	s_and_saveexec_b64 s[30:31], s[20:21]
	v_add_f32_e32 v84, v84, v85
	ds_write_b32 v159, v84 offset:512
	s_or_b64 exec, exec, s[30:31]
	v_mul_f32_e32 v84, v73, v73
	v_mul_f32_e32 v85, v75, v75
	v_fmac_f32_e32 v84, v72, v72
	v_fmac_f32_e32 v85, v74, v74
	v_add_f32_e32 v84, v84, v85
	v_mov_b32_e32 v85, v84
	s_nop 1
	v_permlane16_swap_b32_e32 v84, v85
	v_add_f32_e32 v84, v84, v85
	v_mov_b32_e32 v85, v84
	s_nop 1
	v_permlane32_swap_b32_e32 v84, v85
	s_and_saveexec_b64 s[30:31], s[20:21]
	v_add_f32_e32 v84, v84, v85
	ds_write_b32 v159, v84 offset:1024
	s_or_b64 exec, exec, s[30:31]
	v_mul_f32_e32 v84, v69, v69
	v_mul_f32_e32 v85, v71, v71
	v_fmac_f32_e32 v84, v68, v68
	v_fmac_f32_e32 v85, v70, v70
	v_add_f32_e32 v84, v84, v85
	v_mov_b32_e32 v85, v84
	s_nop 1
	v_permlane16_swap_b32_e32 v84, v85
	v_add_f32_e32 v84, v84, v85
	v_mov_b32_e32 v85, v84
	s_nop 1
	v_permlane32_swap_b32_e32 v84, v85
	s_and_saveexec_b64 s[30:31], s[20:21]
	v_add_f32_e32 v84, v84, v85
	ds_write_b32 v159, v84 offset:1536
	s_or_b64 exec, exec, s[30:31]
	s_waitcnt lgkmcnt(0)
	s_barrier
	ds_read_b128 v[84:87], v158
	ds_read_b128 v[88:91], v158 offset:16
	s_waitcnt lgkmcnt(1)
	v_mov_b32_e32 v92, v84
	s_waitcnt lgkmcnt(0)
	v_mov_b32_e32 v93, v88
	v_mov_b32_e32 v88, v85
	v_pk_add_f32 v[84:85], v[92:93], v[88:89]
	v_mov_b32_e32 v88, v86
	v_mov_b32_e32 v89, v90
	v_mov_b32_e32 v90, v87
	v_pk_add_f32 v[86:87], v[88:89], v[90:91]
	v_lshlrev_b32_e32 v88, 16, v135
	v_pk_add_f32 v[84:85], v[84:85], v[86:87]
	v_and_b32_e32 v89, 0xffff0000, v135
	v_add_f32_e32 v84, v84, v85
	v_fmamk_f32 v84, v84, 0x3c000000, v151
	v_rsq_f32_e32 v84, v84
	v_mul_f32_e32 v90, 0xbfb8aa3b, v88
	v_mul_f32_e32 v91, 0xbfb8aa3b, v89
	v_exp_f32_e32 v90, v90
	v_pk_mul_f32 v[80:81], v[80:81], v[84:85] op_sel_hi:[1,0]
	v_pk_mul_f32 v[82:83], v[82:83], v[84:85] op_sel_hi:[1,0]
	v_lshlrev_b32_e32 v84, 16, v134
	v_and_b32_e32 v85, 0xffff0000, v134
	v_mul_f32_e32 v86, 0xbfb8aa3b, v84
	v_mul_f32_e32 v87, 0xbfb8aa3b, v85
	v_exp_f32_e32 v86, v86
	v_exp_f32_e32 v87, v87
	v_exp_f32_e32 v91, v91
	v_add_f32_e32 v90, 1.0, v90
	v_add_f32_e32 v86, 1.0, v86
	v_add_f32_e32 v87, 1.0, v87
	v_rcp_f32_e32 v86, v86
	v_rcp_f32_e32 v87, v87
	v_add_f32_e32 v91, 1.0, v91
	v_rcp_f32_e32 v90, v90
	v_rcp_f32_e32 v91, v91
	v_pk_mul_f32 v[80:81], v[0:1], v[80:81]
	v_pk_mul_f32 v[84:85], v[86:87], v[84:85]
	v_pk_mul_f32 v[82:83], v[2:3], v[82:83]
	v_pk_mul_f32 v[80:81], v[84:85], v[80:81]
	v_lshl_add_u64 v[134:135], s[48:49], 0, v[112:113]
	v_cvt_pk_bf16_f32 v92, v80, v81
	v_pk_mul_f32 v[80:81], v[90:91], v[88:89]
	v_add_co_u32_e32 v88, vcc, s2, v134
	v_pk_mul_f32 v[80:81], v[80:81], v[82:83]
	s_nop 0
	v_addc_co_u32_e32 v89, vcc, 0, v135, vcc
	v_cvt_pk_bf16_f32 v93, v80, v81
	ds_read_b128 v[80:83], v158 offset:512
	ds_read_b128 v[84:87], v158 offset:528
	s_waitcnt lgkmcnt(1)
	v_mov_b32_e32 v90, v80
	s_waitcnt lgkmcnt(0)
	v_mov_b32_e32 v91, v84
	v_mov_b32_e32 v84, v81
	v_pk_add_f32 v[80:81], v[90:91], v[84:85]
	v_mov_b32_e32 v84, v82
	v_mov_b32_e32 v85, v86
	v_mov_b32_e32 v86, v83
	v_pk_add_f32 v[82:83], v[84:85], v[86:87]
	v_add_co_u32_e32 v84, vcc, s3, v134
	v_pk_add_f32 v[80:81], v[80:81], v[82:83]
	s_nop 0
	v_addc_co_u32_e32 v85, vcc, 0, v135, vcc
	v_add_f32_e32 v80, v80, v81
	v_fmamk_f32 v80, v80, 0x3c000000, v151
	v_rsq_f32_e32 v80, v80
	global_store_dwordx2 v[84:85], v[92:93], off offset:-4096 nt
	v_lshlrev_b32_e32 v92, 16, v133
	v_and_b32_e32 v93, 0xffff0000, v133
	v_pk_mul_f32 v[78:79], v[78:79], v[80:81] op_sel_hi:[1,0]
	v_pk_mul_f32 v[76:77], v[76:77], v[80:81] op_sel_hi:[1,0]
	v_pk_mul_f32 v[86:87], v[2:3], v[78:79]
	v_lshlrev_b32_e32 v78, 16, v132
	v_and_b32_e32 v79, 0xffff0000, v132
	v_mul_f32_e32 v80, 0xbfb8aa3b, v78
	v_mul_f32_e32 v81, 0xbfb8aa3b, v79
	v_exp_f32_e32 v80, v80
	v_exp_f32_e32 v81, v81
	v_pk_mul_f32 v[90:91], v[0:1], v[76:77]
	v_add_f32_e32 v76, 1.0, v80
	v_add_f32_e32 v77, 1.0, v81
	v_mul_f32_e32 v80, 0xbfb8aa3b, v92
	v_rcp_f32_e32 v76, v76
	v_rcp_f32_e32 v77, v77
	v_exp_f32_e32 v80, v80
	v_mul_f32_e32 v81, 0xbfb8aa3b, v93
	v_exp_f32_e32 v81, v81
	v_pk_mul_f32 v[94:95], v[76:77], v[78:79]
	v_add_f32_e32 v76, 1.0, v80
	v_rcp_f32_e32 v96, v76
	v_add_f32_e32 v76, 1.0, v81
	v_rcp_f32_e32 v97, v76
	ds_read_b128 v[76:79], v158 offset:1024
	ds_read_b128 v[80:83], v158 offset:1040
	v_pk_mul_f32 v[90:91], v[94:95], v[90:91]
	v_pk_mul_f32 v[92:93], v[96:97], v[92:93]
	s_waitcnt lgkmcnt(1)
	v_mov_b32_e32 v94, v76
	s_waitcnt lgkmcnt(0)
	v_mov_b32_e32 v95, v80
	v_mov_b32_e32 v80, v77
	v_pk_add_f32 v[76:77], v[94:95], v[80:81]
	v_mov_b32_e32 v80, v78
	v_mov_b32_e32 v81, v82
	v_mov_b32_e32 v82, v79
	v_pk_add_f32 v[78:79], v[80:81], v[82:83]
	v_cvt_pk_bf16_f32 v90, v90, v91
	v_pk_add_f32 v[76:77], v[76:77], v[78:79]
	v_pk_mul_f32 v[78:79], v[92:93], v[86:87]
	v_add_f32_e32 v76, v76, v77
	v_fmamk_f32 v76, v76, 0x3c000000, v151
	v_rsq_f32_e32 v76, v76
	v_lshlrev_b32_e32 v86, 16, v131
	v_and_b32_e32 v87, 0xffff0000, v131
	v_cvt_pk_bf16_f32 v91, v78, v79
	v_pk_mul_f32 v[74:75], v[74:75], v[76:77] op_sel_hi:[1,0]
	v_pk_mul_f32 v[72:73], v[72:73], v[76:77] op_sel_hi:[1,0]
	v_pk_mul_f32 v[80:81], v[2:3], v[74:75]
	v_lshlrev_b32_e32 v74, 16, v130
	v_and_b32_e32 v75, 0xffff0000, v130
	v_mul_f32_e32 v76, 0xbfb8aa3b, v74
	v_mul_f32_e32 v77, 0xbfb8aa3b, v75
	v_exp_f32_e32 v76, v76
	v_exp_f32_e32 v77, v77
	v_pk_mul_f32 v[82:83], v[0:1], v[72:73]
	global_store_dwordx2 v[88:89], v[90:91], off offset:2048 nt
	v_add_f32_e32 v72, 1.0, v76
	v_add_f32_e32 v73, 1.0, v77
	v_mul_f32_e32 v76, 0xbfb8aa3b, v86
	v_rcp_f32_e32 v72, v72
	v_rcp_f32_e32 v73, v73
	v_exp_f32_e32 v76, v76
	v_mul_f32_e32 v77, 0xbfb8aa3b, v87
	v_exp_f32_e32 v77, v77
	v_pk_mul_f32 v[88:89], v[72:73], v[74:75]
	v_add_f32_e32 v72, 1.0, v76
	v_rcp_f32_e32 v90, v72
	v_add_f32_e32 v72, 1.0, v77
	v_rcp_f32_e32 v91, v72
	ds_read_b128 v[72:75], v158 offset:1536
	ds_read_b128 v[76:79], v158 offset:1552
	v_pk_mul_f32 v[82:83], v[88:89], v[82:83]
	v_pk_mul_f32 v[86:87], v[90:91], v[86:87]
	s_waitcnt lgkmcnt(1)
	v_mov_b32_e32 v88, v72
	s_waitcnt lgkmcnt(0)
	v_mov_b32_e32 v89, v76
	v_mov_b32_e32 v76, v73
	v_pk_add_f32 v[72:73], v[88:89], v[76:77]
	v_mov_b32_e32 v76, v74
	v_mov_b32_e32 v77, v78
	v_mov_b32_e32 v78, v75
	v_pk_add_f32 v[74:75], v[76:77], v[78:79]
	v_cvt_pk_bf16_f32 v82, v82, v83
	v_pk_add_f32 v[72:73], v[72:73], v[74:75]
	v_pk_mul_f32 v[74:75], v[86:87], v[80:81]
	v_add_f32_e32 v72, v72, v73
	v_fmamk_f32 v72, v72, 0x3c000000, v151
	v_rsq_f32_e32 v72, v72
	v_cvt_pk_bf16_f32 v83, v74, v75
	v_lshlrev_b32_e32 v76, 16, v129
	v_and_b32_e32 v77, 0xffff0000, v129
	v_pk_mul_f32 v[68:69], v[68:69], v[72:73] op_sel_hi:[1,0]
	v_pk_mul_f32 v[70:71], v[70:71], v[72:73] op_sel_hi:[1,0]
	v_lshlrev_b32_e32 v72, 16, v128
	v_and_b32_e32 v73, 0xffff0000, v128
	v_mul_f32_e32 v74, 0xbfb8aa3b, v72
	v_mul_f32_e32 v75, 0xbfb8aa3b, v73
	v_exp_f32_e32 v74, v74
	v_exp_f32_e32 v75, v75
	v_mul_f32_e32 v78, 0xbfb8aa3b, v76
	v_mul_f32_e32 v79, 0xbfb8aa3b, v77
	v_exp_f32_e32 v78, v78
	v_exp_f32_e32 v79, v79
	v_add_f32_e32 v74, 1.0, v74
	v_add_f32_e32 v75, 1.0, v75
	v_rcp_f32_e32 v74, v74
	v_rcp_f32_e32 v75, v75
	v_add_f32_e32 v78, 1.0, v78
	v_add_f32_e32 v79, 1.0, v79
	v_rcp_f32_e32 v78, v78
	v_rcp_f32_e32 v79, v79
	v_pk_mul_f32 v[68:69], v[0:1], v[68:69]
	v_pk_mul_f32 v[72:73], v[74:75], v[72:73]
	v_pk_mul_f32 v[70:71], v[2:3], v[70:71]
	v_pk_mul_f32 v[68:69], v[72:73], v[68:69]
	v_pk_mul_f32 v[72:73], v[78:79], v[76:77]
	v_cvt_pk_bf16_f32 v68, v68, v69
	v_pk_mul_f32 v[70:71], v[72:73], v[70:71]
	global_store_dwordx2 v[84:85], v[82:83], off nt
	v_cvt_pk_bf16_f32 v69, v70, v71
	global_store_dwordx2 v[84:85], v[68:69], off offset:2048 nt
	ds_write_b128 v144, v[24:27]
	ds_write_b128 v144, v[36:39] offset:18432
	ds_write_b128 v144, v[40:43] offset:27648
	ds_write_b128 v160, v[32:35]
	s_and_saveexec_b64 s[30:31], s[6:7]
	ds_write_b32 v145, v143
	s_or_b64 exec, exec, s[30:31]
	s_andn2_b64 vcc, exec, s[44:45]
	v_mov_b64_e32 v[130:131], v[118:119]
	v_mov_b64_e32 v[132:133], v[116:117]
	v_mov_b64_e32 v[138:139], v[114:115]
	v_mov_b64_e32 v[140:141], v[100:101]
	ds_write_b128 v146, v[44:47] offset:36864
	ds_write_b128 v147, v[48:51] offset:36864
	s_cbranch_vccnz .LBB0_2314
	v_add_co_u32_e32 v24, vcc, 0x45a18000, v136
	v_mov_b32_e32 v143, 0
	s_nop 0
	v_addc_co_u32_e32 v25, vcc, 0, v137, vcc
	v_add_co_u32_e32 v32, vcc, 0x45a1a000, v136
	s_nop 1
	v_addc_co_u32_e32 v33, vcc, 0, v137, vcc
	v_add_co_u32_e32 v36, vcc, 0x45a1c000, v136
	global_load_dwordx4 v[24:27], v[24:25], off offset:768
	s_nop 0
	global_load_dwordx4 v[32:35], v[32:33], off offset:768
	v_addc_co_u32_e32 v37, vcc, 0, v137, vcc
	v_add_co_u32_e32 v40, vcc, 0x45a1e000, v136
	s_nop 1
	v_addc_co_u32_e32 v41, vcc, 0, v137, vcc
	global_load_dwordx4 v[36:39], v[36:37], off offset:768
	s_nop 0
	global_load_dwordx4 v[40:43], v[40:41], off offset:768
	s_and_saveexec_b64 s[30:31], s[6:7]
	s_cbranch_execz .LBB0_2313
	v_lshl_add_u64 v[44:45], s[48:49], 0, v[110:111]
	v_add_co_u32_e32 v44, vcc, 0x45a20000, v44
	s_nop 1
	v_addc_co_u32_e32 v45, vcc, 0, v45, vcc
	global_load_dword v143, v[44:45], off offset:768

.LBB0_2486:
	s_waitcnt lgkmcnt(0)
	s_barrier
	s_andn2_b64 vcc, exec, s[22:23]
	s_cbranch_vccnz .LBB0_2330
	ds_read2st64_b32 v[74:75], v238 offset1:1
	ds_read2st64_b32 v[98:99], v238 offset0:2 offset1:3
	ds_read2st64_b32 v[100:101], v238 offset0:4 offset1:5
	ds_read2st64_b32 v[102:103], v238 offset0:6 offset1:7
	ds_read2st64_b32 v[104:105], v238 offset0:8 offset1:9
	ds_read2st64_b32 v[106:107], v238 offset0:10 offset1:11
	ds_read2st64_b32 v[108:109], v238 offset0:12 offset1:13
	ds_read2st64_b32 v[110:111], v238 offset0:14 offset1:15
	ds_read2st64_b32 v[112:113], v238 offset0:16 offset1:17
	ds_read2st64_b32 v[114:115], v238 offset0:18 offset1:19
	ds_read2st64_b32 v[116:117], v238 offset0:20 offset1:21
	ds_read2st64_b32 v[118:119], v238 offset0:22 offset1:23
	ds_read2st64_b32 v[120:121], v238 offset0:24 offset1:25
	ds_read2st64_b32 v[122:123], v238 offset0:26 offset1:27
	ds_read2st64_b32 v[124:125], v238 offset0:28 offset1:29
	ds_read2st64_b32 v[126:127], v238 offset0:30 offset1:31
	ds_read2st64_b32 v[128:129], v238 offset0:32 offset1:33
	ds_read2st64_b32 v[130:131], v238 offset0:34 offset1:35
	ds_read2st64_b32 v[132:133], v238 offset0:36 offset1:37
	ds_read2st64_b32 v[134:135], v238 offset0:38 offset1:39
	ds_read2st64_b32 v[92:93], v238 offset0:40 offset1:41
	ds_read2st64_b32 v[96:97], v238 offset0:42 offset1:43
	ds_read2st64_b32 v[86:87], v238 offset0:44 offset1:45
	ds_read2st64_b32 v[88:89], v238 offset0:46 offset1:47
	ds_read2st64_b32 v[78:79], v238 offset0:56 offset1:57
	ds_read2st64_b32 v[80:81], v238 offset0:58 offset1:59
	ds_read2st64_b32 v[76:77], v238 offset0:60 offset1:61
	ds_read2st64_b32 v[66:67], v238 offset0:62 offset1:63
	ds_read2st64_b32 v[90:91], v238 offset0:48 offset1:49
	ds_read2st64_b32 v[94:95], v238 offset0:50 offset1:51
	ds_read2st64_b32 v[82:83], v238 offset0:52 offset1:53
	ds_read2st64_b32 v[84:85], v238 offset0:54 offset1:55
	s_waitcnt lgkmcnt(14)
	v_pk_mul_f32 v[74:75], v[188:189], v[74:75]
	v_pk_mul_f32 v[98:99], v[188:189], v[98:99]
	v_pk_fma_f32 v[74:75], v[50:51], v[0:1], v[74:75] op_sel_hi:[1,0,1] neg_lo:[0,0,1] neg_hi:[0,0,1]
	v_pk_fma_f32 v[52:53], v[52:53], v[0:1], v[98:99] op_sel_hi:[1,0,1] neg_lo:[0,0,1] neg_hi:[0,0,1]
	v_mul_f32_e32 v50, v75, v75
	v_pk_fma_f32 v[50:51], v[74:75], v[74:75], v[50:51] op_sel_hi:[1,1,0]
	v_mul_f32_e32 v98, v53, v53
	v_pk_fma_f32 v[50:51], v[52:53], v[52:53], v[50:51]
	v_or_b32_e32 v72, s55, v229
	v_pk_add_f32 v[98:99], v[50:51], v[98:99] op_sel_hi:[1,0]
	v_pk_mul_f32 v[50:51], v[188:189], v[102:103]
	s_waitcnt lgkmcnt(4)
	v_pk_mul_f32 v[66:67], v[188:189], v[66:67]
	v_pk_fma_f32 v[50:51], v[56:57], v[0:1], v[50:51] op_sel_hi:[1,0,1] neg_lo:[0,0,1] neg_hi:[0,0,1]
	v_pk_mul_f32 v[56:57], v[188:189], v[100:101]
	v_lshl_add_u64 v[70:71], v[184:185], 2, s[10:11]
	v_pk_fma_f32 v[56:57], v[54:55], v[0:1], v[56:57] op_sel_hi:[1,0,1] neg_lo:[0,0,1] neg_hi:[0,0,1]
	v_pk_fma_f32 v[16:17], v[16:17], v[0:1], v[66:67] op_sel_hi:[1,0,1] neg_lo:[0,0,1] neg_hi:[0,0,1]
	v_pk_fma_f32 v[54:55], v[56:57], v[56:57], v[98:99]
	v_mul_f32_e32 v98, v57, v57
	v_pk_add_f32 v[54:55], v[54:55], v[98:99] op_sel_hi:[1,0]
	v_mul_f32_e32 v98, v51, v51
	v_pk_fma_f32 v[54:55], v[50:51], v[50:51], v[54:55]
	global_load_dwordx4 v[66:69], v[70:71], off offset:512
	v_pk_add_f32 v[98:99], v[54:55], v[98:99] op_sel_hi:[1,0]
	v_pk_mul_f32 v[54:55], v[188:189], v[106:107]
	v_ashrrev_i32_e32 v73, 31, v72
	v_pk_fma_f32 v[54:55], v[60:61], v[0:1], v[54:55] op_sel_hi:[1,0,1] neg_lo:[0,0,1] neg_hi:[0,0,1]
	v_pk_mul_f32 v[60:61], v[188:189], v[104:105]
	s_lshl_b32 s12, s54, 1
	v_pk_fma_f32 v[60:61], v[58:59], v[0:1], v[60:61] op_sel_hi:[1,0,1] neg_lo:[0,0,1] neg_hi:[0,0,1]
	s_nop 0
	v_pk_fma_f32 v[58:59], v[60:61], v[60:61], v[98:99]
	v_mul_f32_e32 v98, v61, v61
	v_pk_add_f32 v[58:59], v[58:59], v[98:99] op_sel_hi:[1,0]
	v_mul_f32_e32 v98, v55, v55
	v_pk_fma_f32 v[58:59], v[54:55], v[54:55], v[58:59]
	s_nop 0
	v_pk_add_f32 v[98:99], v[58:59], v[98:99] op_sel_hi:[1,0]
	v_pk_mul_f32 v[58:59], v[188:189], v[110:111]
	s_nop 0
	v_pk_fma_f32 v[58:59], v[64:65], v[0:1], v[58:59] op_sel_hi:[1,0,1] neg_lo:[0,0,1] neg_hi:[0,0,1]
	v_pk_mul_f32 v[64:65], v[188:189], v[108:109]
	s_nop 0
	v_pk_fma_f32 v[62:63], v[62:63], v[0:1], v[64:65] op_sel_hi:[1,0,1] neg_lo:[0,0,1] neg_hi:[0,0,1]
	s_nop 0
	v_pk_fma_f32 v[64:65], v[62:63], v[62:63], v[98:99]
	v_mul_f32_e32 v98, v63, v63
	v_pk_add_f32 v[64:65], v[64:65], v[98:99] op_sel_hi:[1,0]
	v_mul_f32_e32 v98, v59, v59
	v_pk_fma_f32 v[64:65], v[58:59], v[58:59], v[64:65]
	s_nop 0
	v_pk_add_f32 v[98:99], v[64:65], v[98:99] op_sel_hi:[1,0]
	v_pk_mul_f32 v[64:65], v[188:189], v[114:115]
	s_nop 0
	v_pk_fma_f32 v[36:37], v[36:37], v[0:1], v[64:65] op_sel_hi:[1,0,1] neg_lo:[0,0,1] neg_hi:[0,0,1]
	v_pk_mul_f32 v[64:65], v[188:189], v[112:113]
	s_nop 0
	v_pk_fma_f32 v[64:65], v[34:35], v[0:1], v[64:65] op_sel_hi:[1,0,1] neg_lo:[0,0,1] neg_hi:[0,0,1]
	s_nop 0
	v_pk_fma_f32 v[34:35], v[64:65], v[64:65], v[98:99]
	v_mul_f32_e32 v98, v65, v65
	v_pk_add_f32 v[34:35], v[34:35], v[98:99] op_sel_hi:[1,0]
	v_mul_f32_e32 v98, v37, v37
	v_pk_fma_f32 v[34:35], v[36:37], v[36:37], v[34:35]
	s_nop 0
	v_pk_add_f32 v[98:99], v[34:35], v[98:99] op_sel_hi:[1,0]
	v_pk_mul_f32 v[34:35], v[188:189], v[118:119]
	s_nop 0
	v_pk_fma_f32 v[34:35], v[40:41], v[0:1], v[34:35] op_sel_hi:[1,0,1] neg_lo:[0,0,1] neg_hi:[0,0,1]
	v_pk_mul_f32 v[40:41], v[188:189], v[116:117]
	s_nop 0
	v_pk_fma_f32 v[40:41], v[38:39], v[0:1], v[40:41] op_sel_hi:[1,0,1] neg_lo:[0,0,1] neg_hi:[0,0,1]
	s_nop 0
	v_pk_fma_f32 v[38:39], v[40:41], v[40:41], v[98:99]
	v_mul_f32_e32 v98, v41, v41
	v_pk_add_f32 v[38:39], v[38:39], v[98:99] op_sel_hi:[1,0]
	v_mul_f32_e32 v98, v35, v35
	v_pk_fma_f32 v[38:39], v[34:35], v[34:35], v[38:39]
	s_nop 0
	v_pk_add_f32 v[98:99], v[38:39], v[98:99] op_sel_hi:[1,0]
	v_pk_mul_f32 v[38:39], v[188:189], v[122:123]
	s_nop 0
	v_pk_fma_f32 v[38:39], v[44:45], v[0:1], v[38:39] op_sel_hi:[1,0,1] neg_lo:[0,0,1] neg_hi:[0,0,1]
	v_pk_mul_f32 v[44:45], v[188:189], v[120:121]
	s_nop 0
	v_pk_fma_f32 v[44:45], v[42:43], v[0:1], v[44:45] op_sel_hi:[1,0,1] neg_lo:[0,0,1] neg_hi:[0,0,1]
	s_nop 0
	v_pk_fma_f32 v[42:43], v[44:45], v[44:45], v[98:99]
	v_mul_f32_e32 v98, v45, v45
	v_pk_add_f32 v[42:43], v[42:43], v[98:99] op_sel_hi:[1,0]
	v_mul_f32_e32 v98, v39, v39
	v_pk_fma_f32 v[42:43], v[38:39], v[38:39], v[42:43]
	s_nop 0
	v_pk_add_f32 v[98:99], v[42:43], v[98:99] op_sel_hi:[1,0]
	v_pk_mul_f32 v[42:43], v[188:189], v[126:127]
	s_nop 0
	v_pk_fma_f32 v[42:43], v[48:49], v[0:1], v[42:43] op_sel_hi:[1,0,1] neg_lo:[0,0,1] neg_hi:[0,0,1]
	v_pk_mul_f32 v[48:49], v[188:189], v[124:125]
	s_nop 0
	v_pk_fma_f32 v[46:47], v[46:47], v[0:1], v[48:49] op_sel_hi:[1,0,1] neg_lo:[0,0,1] neg_hi:[0,0,1]
	s_nop 0
	v_pk_fma_f32 v[48:49], v[46:47], v[46:47], v[98:99]
	v_mul_f32_e32 v98, v47, v47
	v_pk_add_f32 v[48:49], v[48:49], v[98:99] op_sel_hi:[1,0]
	v_mul_f32_e32 v98, v43, v43
	v_pk_fma_f32 v[48:49], v[42:43], v[42:43], v[48:49]
	s_nop 0
	v_pk_add_f32 v[48:49], v[48:49], v[98:99] op_sel_hi:[1,0]
	v_pk_mul_f32 v[98:99], v[188:189], v[130:131]
	s_nop 0
	v_pk_fma_f32 v[20:21], v[20:21], v[0:1], v[98:99] op_sel_hi:[1,0,1] neg_lo:[0,0,1] neg_hi:[0,0,1]
	v_pk_mul_f32 v[98:99], v[188:189], v[128:129]
	s_nop 0
	v_pk_fma_f32 v[18:19], v[18:19], v[0:1], v[98:99] op_sel_hi:[1,0,1] neg_lo:[0,0,1] neg_hi:[0,0,1]
	s_nop 0
	v_pk_fma_f32 v[48:49], v[18:19], v[18:19], v[48:49]
	v_mul_f32_e32 v98, v19, v19
	v_pk_add_f32 v[48:49], v[48:49], v[98:99] op_sel_hi:[1,0]
	v_mul_f32_e32 v98, v21, v21
	v_pk_fma_f32 v[48:49], v[20:21], v[20:21], v[48:49]
	s_nop 0
	v_pk_add_f32 v[98:99], v[48:49], v[98:99] op_sel_hi:[1,0]
	v_pk_mul_f32 v[48:49], v[188:189], v[134:135]
	s_nop 0
	v_pk_fma_f32 v[24:25], v[24:25], v[0:1], v[48:49] op_sel_hi:[1,0,1] neg_lo:[0,0,1] neg_hi:[0,0,1]
	v_pk_mul_f32 v[48:49], v[188:189], v[132:133]
	s_nop 0
	v_pk_fma_f32 v[48:49], v[22:23], v[0:1], v[48:49] op_sel_hi:[1,0,1] neg_lo:[0,0,1] neg_hi:[0,0,1]
	s_nop 0
	v_pk_fma_f32 v[22:23], v[48:49], v[48:49], v[98:99]
	v_mul_f32_e32 v98, v49, v49
	v_pk_add_f32 v[22:23], v[22:23], v[98:99] op_sel_hi:[1,0]
	v_mul_f32_e32 v98, v25, v25
	v_pk_fma_f32 v[22:23], v[24:25], v[24:25], v[22:23]
	s_nop 0
	v_pk_add_f32 v[98:99], v[22:23], v[98:99] op_sel_hi:[1,0]
	v_pk_mul_f32 v[22:23], v[188:189], v[96:97]
	s_nop 0
	v_pk_fma_f32 v[22:23], v[28:29], v[0:1], v[22:23] op_sel_hi:[1,0,1] neg_lo:[0,0,1] neg_hi:[0,0,1]
	v_pk_mul_f32 v[28:29], v[188:189], v[92:93]
	s_nop 0
	v_pk_fma_f32 v[28:29], v[26:27], v[0:1], v[28:29] op_sel_hi:[1,0,1] neg_lo:[0,0,1] neg_hi:[0,0,1]
	s_nop 0
	v_pk_fma_f32 v[26:27], v[28:29], v[28:29], v[98:99]
	v_mul_f32_e32 v92, v29, v29
	v_pk_add_f32 v[26:27], v[26:27], v[92:93] op_sel_hi:[1,0]
	v_mul_f32_e32 v92, v23, v23
	v_pk_fma_f32 v[26:27], v[22:23], v[22:23], v[26:27]
	s_nop 0
	v_pk_add_f32 v[92:93], v[26:27], v[92:93] op_sel_hi:[1,0]
	v_pk_mul_f32 v[26:27], v[188:189], v[88:89]
	s_nop 0
	v_pk_fma_f32 v[26:27], v[32:33], v[0:1], v[26:27] op_sel_hi:[1,0,1] neg_lo:[0,0,1] neg_hi:[0,0,1]
	v_pk_mul_f32 v[32:33], v[188:189], v[86:87]
	s_nop 0
	v_pk_fma_f32 v[30:31], v[30:31], v[0:1], v[32:33] op_sel_hi:[1,0,1] neg_lo:[0,0,1] neg_hi:[0,0,1]
	s_nop 0
	v_pk_fma_f32 v[32:33], v[30:31], v[30:31], v[92:93]
	v_mul_f32_e32 v86, v31, v31
	v_pk_add_f32 v[32:33], v[32:33], v[86:87] op_sel_hi:[1,0]
	v_mul_f32_e32 v86, v27, v27
	v_pk_fma_f32 v[32:33], v[26:27], v[26:27], v[32:33]
	s_nop 0
	v_pk_add_f32 v[86:87], v[32:33], v[86:87] op_sel_hi:[1,0]
	s_waitcnt lgkmcnt(2)
	v_pk_mul_f32 v[32:33], v[188:189], v[94:95]
	s_nop 0
	v_pk_fma_f32 v[4:5], v[4:5], v[0:1], v[32:33] op_sel_hi:[1,0,1] neg_lo:[0,0,1] neg_hi:[0,0,1]
	v_pk_mul_f32 v[32:33], v[188:189], v[90:91]
	s_nop 0
	v_pk_fma_f32 v[32:33], v[2:3], v[0:1], v[32:33] op_sel_hi:[1,0,1] neg_lo:[0,0,1] neg_hi:[0,0,1]
	s_nop 0
	v_pk_fma_f32 v[2:3], v[32:33], v[32:33], v[86:87]
	v_mul_f32_e32 v86, v33, v33
	v_pk_add_f32 v[2:3], v[2:3], v[86:87] op_sel_hi:[1,0]
	v_mul_f32_e32 v86, v5, v5
	v_pk_fma_f32 v[2:3], v[4:5], v[4:5], v[2:3]
	s_nop 0
	v_pk_add_f32 v[86:87], v[2:3], v[86:87] op_sel_hi:[1,0]
	s_waitcnt lgkmcnt(0)
	v_pk_mul_f32 v[2:3], v[188:189], v[84:85]
	s_nop 0
	v_pk_fma_f32 v[2:3], v[8:9], v[0:1], v[2:3] op_sel_hi:[1,0,1] neg_lo:[0,0,1] neg_hi:[0,0,1]
	v_pk_mul_f32 v[8:9], v[188:189], v[82:83]
	s_nop 0
	v_pk_fma_f32 v[8:9], v[6:7], v[0:1], v[8:9] op_sel_hi:[1,0,1] neg_lo:[0,0,1] neg_hi:[0,0,1]
	s_nop 0
	v_pk_fma_f32 v[6:7], v[8:9], v[8:9], v[86:87]
	v_mul_f32_e32 v82, v9, v9
	v_pk_add_f32 v[6:7], v[6:7], v[82:83] op_sel_hi:[1,0]
	v_mul_f32_e32 v82, v3, v3
	v_pk_fma_f32 v[6:7], v[2:3], v[2:3], v[6:7]
	s_nop 0
	v_pk_add_f32 v[82:83], v[6:7], v[82:83] op_sel_hi:[1,0]
	v_pk_mul_f32 v[6:7], v[188:189], v[80:81]
	s_nop 0
	v_pk_fma_f32 v[6:7], v[12:13], v[0:1], v[6:7] op_sel_hi:[1,0,1] neg_lo:[0,0,1] neg_hi:[0,0,1]
	v_pk_mul_f32 v[12:13], v[188:189], v[78:79]
	s_nop 0
	v_pk_fma_f32 v[10:11], v[10:11], v[0:1], v[12:13] op_sel_hi:[1,0,1] neg_lo:[0,0,1] neg_hi:[0,0,1]
	s_nop 0
	v_pk_fma_f32 v[12:13], v[10:11], v[10:11], v[82:83]
	v_mul_f32_e32 v78, v11, v11
	v_pk_add_f32 v[12:13], v[12:13], v[78:79] op_sel_hi:[1,0]
	v_mul_f32_e32 v78, v7, v7
	v_pk_fma_f32 v[12:13], v[6:7], v[6:7], v[12:13]
	s_nop 0
	v_pk_add_f32 v[78:79], v[12:13], v[78:79] op_sel_hi:[1,0]
	v_pk_mul_f32 v[12:13], v[188:189], v[76:77]
	s_nop 0
	v_pk_fma_f32 v[12:13], v[14:15], v[0:1], v[12:13] op_sel_hi:[1,0,1] neg_lo:[0,0,1] neg_hi:[0,0,1]
	s_nop 0
	v_pk_fma_f32 v[14:15], v[12:13], v[12:13], v[78:79]
	v_mul_f32_e32 v0, v13, v13
	v_pk_add_f32 v[14:15], v[14:15], v[0:1] op_sel_hi:[1,0]
	v_mul_f32_e32 v0, v17, v17
	v_pk_fma_f32 v[14:15], v[16:17], v[16:17], v[14:15]
	s_nop 0
	v_pk_add_f32 v[14:15], v[14:15], v[0:1] op_sel_hi:[1,0]
	s_nop 0
	v_mov_b32_e32 v0, v14
	s_nop 1
	v_permlane32_swap_b32_e32 v14, v0
	v_add_f32_e32 v0, v14, v0
	v_fmamk_f32 v0, v0, 0x3c000000, v240
	v_mul_f32_e32 v14, 0x4f800000, v0
	v_cmp_gt_f32_e32 vcc, s50, v0
	s_nop 1
	v_cndmask_b32_e32 v0, v0, v14, vcc
	v_sqrt_f32_e32 v76, v0
	v_lshl_add_u64 v[14:15], v[72:73], 0, s[14:15]
	v_lshlrev_b64 v[14:15], 7, v[14:15]
	v_lshl_add_u64 v[14:15], s[64:65], 0, v[14:15]
	v_add_u32_e32 v72, -1, v76
	v_fma_f32 v73, -v72, v76, v0
	v_cmp_ge_f32_e64 s[10:11], 0, v73
	v_add_u32_e32 v73, 1, v76
	v_lshl_add_u64 v[14:15], v[14:15], 0, s[12:13]
	v_cndmask_b32_e64 v72, v76, v72, s[10:11]
	v_fma_f32 v76, -v73, v76, v0
	v_cmp_lt_f32_e64 s[10:11], 0, v76
	v_lshl_add_u64 v[14:15], v[184:185], 1, v[14:15]
	s_nop 0
	v_cndmask_b32_e64 v72, v72, v73, s[10:11]
	v_mul_f32_e32 v73, 0x37800000, v72
	v_cndmask_b32_e32 v72, v72, v73, vcc
	v_cmp_class_f32_e32 vcc, v0, v241
	s_nop 1
	v_cndmask_b32_e32 v0, v72, v0, vcc
	v_div_scale_f32 v72, s[10:11], v0, v0, s51
	v_rcp_f32_e32 v73, v72
	s_nop 0
	v_fma_f32 v76, -v72, v73, 1.0
	v_fmac_f32_e32 v73, v76, v73
	v_div_scale_f32 v76, vcc, s51, v0, s51
	v_mul_f32_e32 v77, v76, v73
	v_fma_f32 v78, -v72, v77, v76
	v_fmac_f32_e32 v77, v78, v73
	v_fma_f32 v72, -v72, v77, v76
	v_div_fmas_f32 v72, v72, v73, v77
	v_div_fixup_f32 v0, v72, v0, s51
	v_pk_mul_f32 v[72:73], v[74:75], v[0:1] op_sel_hi:[1,0]
	v_pk_mul_f32 v[52:53], v[52:53], v[0:1] op_sel_hi:[1,0]
	s_waitcnt vmcnt(0)
	v_pk_mul_f32 v[66:67], v[66:67], v[72:73]
	v_pk_mul_f32 v[52:53], v[68:69], v[52:53]
	v_cvt_pk_bf16_f32 v66, v66, v67
	v_cvt_pk_bf16_f32 v67, v52, v53
	v_add_co_u32_e32 v52, vcc, s52, v14
	v_pk_mul_f32 v[50:51], v[50:51], v[0:1] op_sel_hi:[1,0]
	s_nop 0
	v_addc_co_u32_e32 v53, vcc, 0, v15, vcc
	global_store_dwordx2 v[52:53], v[66:67], off nt
	global_load_dwordx4 v[66:69], v[70:71], off offset:544
	v_pk_mul_f32 v[52:53], v[56:57], v[0:1] op_sel_hi:[1,0]
	v_lshl_add_u64 v[72:73], v[14:15], 0, s[34:35]
	v_pk_mul_f32 v[56:57], v[60:61], v[0:1] op_sel_hi:[1,0]
	v_pk_mul_f32 v[54:55], v[54:55], v[0:1] op_sel_hi:[1,0]
	v_pk_mul_f32 v[36:37], v[36:37], v[0:1] op_sel_hi:[1,0]
	v_pk_mul_f32 v[34:35], v[34:35], v[0:1] op_sel_hi:[1,0]
	v_pk_mul_f32 v[38:39], v[38:39], v[0:1] op_sel_hi:[1,0]
	v_pk_mul_f32 v[18:19], v[18:19], v[0:1] op_sel_hi:[1,0]
	v_pk_mul_f32 v[20:21], v[20:21], v[0:1] op_sel_hi:[1,0]
	v_add_co_u32_e32 v14, vcc, s53, v14
	v_pk_mul_f32 v[24:25], v[24:25], v[0:1] op_sel_hi:[1,0]
	s_nop 0
	v_addc_co_u32_e32 v15, vcc, 0, v15, vcc
	v_pk_mul_f32 v[22:23], v[22:23], v[0:1] op_sel_hi:[1,0]
	v_pk_mul_f32 v[4:5], v[4:5], v[0:1] op_sel_hi:[1,0]
	v_pk_mul_f32 v[2:3], v[2:3], v[0:1] op_sel_hi:[1,0]
	v_pk_mul_f32 v[6:7], v[6:7], v[0:1] op_sel_hi:[1,0]
	s_waitcnt vmcnt(0)
	v_pk_mul_f32 v[52:53], v[66:67], v[52:53]
	v_pk_mul_f32 v[50:51], v[68:69], v[50:51]
	v_cvt_pk_bf16_f32 v52, v52, v53
	v_cvt_pk_bf16_f32 v53, v50, v51
	global_store_dwordx2 v[72:73], v[52:53], off offset:16 nt
	global_load_dwordx4 v[50:53], v[70:71], off offset:576
	s_waitcnt vmcnt(0)
	v_pk_mul_f32 v[50:51], v[50:51], v[56:57]
	v_pk_mul_f32 v[52:53], v[52:53], v[54:55]
	v_cvt_pk_bf16_f32 v50, v50, v51
	v_cvt_pk_bf16_f32 v51, v52, v53
	global_store_dwordx2 v[72:73], v[50:51], off offset:32 nt
	global_load_dwordx4 v[50:53], v[70:71], off offset:608
	v_pk_mul_f32 v[54:55], v[62:63], v[0:1] op_sel_hi:[1,0]
	v_pk_mul_f32 v[56:57], v[58:59], v[0:1] op_sel_hi:[1,0]
	s_waitcnt vmcnt(0)
	v_pk_mul_f32 v[50:51], v[54:55], v[50:51]
	v_pk_mul_f32 v[52:53], v[56:57], v[52:53]
	v_cvt_pk_bf16_f32 v50, v50, v51
	v_cvt_pk_bf16_f32 v51, v52, v53
	global_store_dwordx2 v[72:73], v[50:51], off offset:48 nt
	global_load_dwordx4 v[50:53], v[70:71], off offset:640
	v_pk_mul_f32 v[54:55], v[64:65], v[0:1] op_sel_hi:[1,0]
	s_waitcnt vmcnt(0)
	v_pk_mul_f32 v[36:37], v[36:37], v[52:53]
	v_pk_mul_f32 v[50:51], v[54:55], v[50:51]
	s_nop 0
	v_cvt_pk_bf16_f32 v50, v50, v51
	v_cvt_pk_bf16_f32 v51, v36, v37
	global_store_dwordx2 v[72:73], v[50:51], off offset:64 nt
	global_load_dwordx4 v[50:53], v[70:71], off offset:672
	v_pk_mul_f32 v[36:37], v[40:41], v[0:1] op_sel_hi:[1,0]
	v_pk_mul_f32 v[40:41], v[44:45], v[0:1] op_sel_hi:[1,0]
	s_waitcnt vmcnt(0)
	v_pk_mul_f32 v[36:37], v[36:37], v[50:51]
	v_pk_mul_f32 v[34:35], v[34:35], v[52:53]
	v_cvt_pk_bf16_f32 v36, v36, v37
	v_cvt_pk_bf16_f32 v37, v34, v35
	global_store_dwordx2 v[72:73], v[36:37], off offset:80 nt
	global_load_dwordx4 v[34:37], v[70:71], off offset:704
	s_waitcnt vmcnt(0)
	v_pk_mul_f32 v[34:35], v[40:41], v[34:35]
	v_pk_mul_f32 v[36:37], v[38:39], v[36:37]
	v_cvt_pk_bf16_f32 v34, v34, v35
	v_cvt_pk_bf16_f32 v35, v36, v37
	global_store_dwordx2 v[72:73], v[34:35], off offset:96 nt
	global_load_dwordx4 v[34:37], v[70:71], off offset:736
	v_pk_mul_f32 v[38:39], v[46:47], v[0:1] op_sel_hi:[1,0]
	v_pk_mul_f32 v[40:41], v[42:43], v[0:1] op_sel_hi:[1,0]
	s_waitcnt vmcnt(0)
	v_pk_mul_f32 v[34:35], v[38:39], v[34:35]
	v_pk_mul_f32 v[36:37], v[40:41], v[36:37]
	v_cvt_pk_bf16_f32 v34, v34, v35
	v_cvt_pk_bf16_f32 v35, v36, v37
	global_store_dwordx2 v[72:73], v[34:35], off offset:112 nt
	global_load_dwordx4 v[34:37], v[70:71], off offset:768
	s_waitcnt vmcnt(0)
	v_pk_mul_f32 v[18:19], v[18:19], v[34:35]
	v_pk_mul_f32 v[20:21], v[20:21], v[36:37]
	v_cvt_pk_bf16_f32 v18, v18, v19
	v_cvt_pk_bf16_f32 v19, v20, v21
	global_store_dwordx2 v[14:15], v[18:19], off nt
	global_load_dwordx4 v[18:21], v[70:71], off offset:800
	v_pk_mul_f32 v[34:35], v[48:49], v[0:1] op_sel_hi:[1,0]
	s_waitcnt vmcnt(0)
	v_pk_mul_f32 v[20:21], v[24:25], v[20:21]
	v_pk_mul_f32 v[18:19], v[34:35], v[18:19]
	v_pk_mul_f32 v[24:25], v[28:29], v[0:1] op_sel_hi:[1,0]
	v_cvt_pk_bf16_f32 v18, v18, v19
	v_cvt_pk_bf16_f32 v19, v20, v21
	global_store_dwordx2 v[14:15], v[18:19], off offset:16 nt
	global_load_dwordx4 v[18:21], v[70:71], off offset:832
	s_waitcnt vmcnt(0)
	v_pk_mul_f32 v[18:19], v[24:25], v[18:19]
	v_pk_mul_f32 v[20:21], v[22:23], v[20:21]
	v_cvt_pk_bf16_f32 v18, v18, v19
	v_cvt_pk_bf16_f32 v19, v20, v21
	global_store_dwordx2 v[14:15], v[18:19], off offset:32 nt
	global_load_dwordx4 v[18:21], v[70:71], off offset:864
	v_pk_mul_f32 v[22:23], v[30:31], v[0:1] op_sel_hi:[1,0]
	v_pk_mul_f32 v[24:25], v[26:27], v[0:1] op_sel_hi:[1,0]
	s_waitcnt vmcnt(0)
	v_pk_mul_f32 v[18:19], v[22:23], v[18:19]
	v_pk_mul_f32 v[20:21], v[24:25], v[20:21]
	v_cvt_pk_bf16_f32 v18, v18, v19
	v_cvt_pk_bf16_f32 v19, v20, v21
	global_store_dwordx2 v[14:15], v[18:19], off offset:48 nt
	global_load_dwordx4 v[18:21], v[70:71], off offset:896
	v_pk_mul_f32 v[22:23], v[32:33], v[0:1] op_sel_hi:[1,0]
	s_waitcnt vmcnt(0)
	v_pk_mul_f32 v[4:5], v[4:5], v[20:21]
	v_pk_mul_f32 v[18:19], v[22:23], v[18:19]
	s_nop 0
	v_cvt_pk_bf16_f32 v18, v18, v19
	v_cvt_pk_bf16_f32 v19, v4, v5
	global_store_dwordx2 v[14:15], v[18:19], off offset:64 nt
	global_load_dwordx4 v[18:21], v[70:71], off offset:928
	v_pk_mul_f32 v[4:5], v[8:9], v[0:1] op_sel_hi:[1,0]
	v_pk_mul_f32 v[8:9], v[10:11], v[0:1] op_sel_hi:[1,0]
	s_waitcnt vmcnt(0)
	v_pk_mul_f32 v[4:5], v[4:5], v[18:19]
	v_pk_mul_f32 v[2:3], v[2:3], v[20:21]
	v_cvt_pk_bf16_f32 v4, v4, v5
	v_cvt_pk_bf16_f32 v5, v2, v3
	global_store_dwordx2 v[14:15], v[4:5], off offset:80 nt
	global_load_dwordx4 v[2:5], v[70:71], off offset:960
	s_waitcnt vmcnt(0)
	v_pk_mul_f32 v[2:3], v[8:9], v[2:3]
	v_pk_mul_f32 v[4:5], v[6:7], v[4:5]
	v_cvt_pk_bf16_f32 v2, v2, v3
	v_cvt_pk_bf16_f32 v3, v4, v5
	global_store_dwordx2 v[14:15], v[2:3], off offset:96 nt
	global_load_dwordx4 v[2:5], v[70:71], off offset:992
	v_pk_mul_f32 v[6:7], v[12:13], v[0:1] op_sel_hi:[1,0]
	v_pk_mul_f32 v[8:9], v[16:17], v[0:1] op_sel_hi:[1,0]
	s_waitcnt vmcnt(0)
	v_pk_mul_f32 v[2:3], v[6:7], v[2:3]
	v_pk_mul_f32 v[4:5], v[8:9], v[4:5]
	v_cvt_pk_bf16_f32 v2, v2, v3
	v_cvt_pk_bf16_f32 v3, v4, v5
	global_store_dwordx2 v[14:15], v[2:3], off offset:112 nt
	s_branch .LBB0_2330

.LBB0_3009:
	s_or_b64 exec, exec, s[2:3]
	s_lshl_b32 s0, s25, 3
	s_add_i32 s0, s0, 0
	s_waitcnt lgkmcnt(0)
	s_barrier
	s_ashr_i32 s35, s34, 31
	v_lshl_add_u32 v175, v177, 3, s0
	v_add_u32_e32 v193, 0x23000, v175
	ds_read_b64 v[178:179], v193
	ds_read_b64 v[180:181], v193 offset:1408
	s_lshl_b64 s[0:1], s[34:35], 2
	s_mov_b32 s31, s7
	s_add_u32 s2, s90, s0
	s_waitcnt lgkmcnt(1)
	v_sub_f32_e32 v53, v53, v178
	v_sub_f32_e32 v52, v52, v178
	v_sub_f32_e32 v55, v55, v178
	v_sub_f32_e32 v54, v54, v178
	v_sub_f32_e32 v49, v49, v178
	v_sub_f32_e32 v48, v48, v178
	v_sub_f32_e32 v51, v51, v178
	v_sub_f32_e32 v50, v50, v178
	s_addc_u32 s3, s91, s1
	s_lshl_b64 s[0:1], s[30:31], 2
	v_lshlrev_b32_e32 v176, 3, v176
	v_pk_mul_f32 v[54:55], v[178:179], v[54:55] op_sel:[1,0]
	v_pk_mul_f32 v[52:53], v[178:179], v[52:53] op_sel:[1,0]
	v_pk_mul_f32 v[50:51], v[178:179], v[50:51] op_sel:[1,0]
	v_pk_mul_f32 v[48:49], v[178:179], v[48:49] op_sel:[1,0]
	s_add_u32 s0, s2, s0
	v_add_u32_e32 v174, s25, v177
	v_ashrrev_i32_e32 v177, 31, v176
	s_waitcnt vmcnt(4)
	v_pk_fma_f32 v[52:53], v[152:153], v[52:53], v[156:157]
	v_pk_fma_f32 v[54:55], v[154:155], v[54:55], v[158:159]
	v_pk_fma_f32 v[178:179], v[144:145], v[48:49], v[148:149]
	v_pk_fma_f32 v[194:195], v[146:147], v[50:51], v[150:151]
	v_cmp_eq_u32_e32 vcc, 0, v192
	s_addc_u32 s1, s3, s1
	v_ashrrev_i32_e32 v175, 31, v174
	v_cndmask_b32_e32 v51, v191, v55, vcc
	v_cndmask_b32_e32 v50, v191, v54, vcc
	v_cndmask_b32_e32 v49, v191, v53, vcc
	v_cndmask_b32_e32 v48, v191, v52, vcc
	v_cndmask_b32_e32 v55, v191, v195, vcc
	v_cndmask_b32_e32 v54, v191, v194, vcc
	v_cndmask_b32_e32 v53, v191, v179, vcc
	v_cndmask_b32_e32 v52, v191, v178, vcc
	v_lshl_add_u64 v[194:195], v[176:177], 2, s[0:1]
	ds_read2_b64 v[176:179], v193 offset1:16
	v_lshlrev_b64 v[174:175], 13, v[174:175]
	v_lshl_add_u64 v[174:175], v[194:195], 0, v[174:175]
	global_store_dwordx4 v[174:175], v[48:51], off nt
	global_store_dwordx4 v[174:175], v[52:55], off offset:16 nt
	s_cmp_eq_u32 s50, 3
	s_waitcnt lgkmcnt(0)
	v_sub_f32_e32 v45, v45, v178
	v_sub_f32_e32 v44, v44, v178
	v_sub_f32_e32 v47, v47, v178
	v_sub_f32_e32 v46, v46, v178
	v_sub_f32_e32 v41, v41, v178
	v_sub_f32_e32 v40, v40, v178
	v_sub_f32_e32 v43, v43, v178
	v_sub_f32_e32 v42, v42, v178
	v_pk_mul_f32 v[46:47], v[178:179], v[46:47] op_sel:[1,0]
	v_pk_mul_f32 v[44:45], v[178:179], v[44:45] op_sel:[1,0]
	v_pk_mul_f32 v[42:43], v[178:179], v[42:43] op_sel:[1,0]
	v_pk_mul_f32 v[40:41], v[178:179], v[40:41] op_sel:[1,0]
	v_pk_fma_f32 v[44:45], v[152:153], v[44:45], v[156:157]
	v_pk_fma_f32 v[46:47], v[154:155], v[46:47], v[158:159]
	v_pk_fma_f32 v[48:49], v[144:145], v[40:41], v[148:149]
	v_pk_fma_f32 v[50:51], v[146:147], v[42:43], v[150:151]
	v_cndmask_b32_e32 v43, v191, v47, vcc
	v_cndmask_b32_e32 v42, v191, v46, vcc
	v_cndmask_b32_e32 v41, v191, v45, vcc
	v_cndmask_b32_e32 v40, v191, v44, vcc
	v_cndmask_b32_e32 v47, v191, v51, vcc
	v_cndmask_b32_e32 v46, v191, v50, vcc
	v_cndmask_b32_e32 v45, v191, v49, vcc
	v_cndmask_b32_e32 v44, v191, v48, vcc
	ds_read2_b64 v[48:51], v193 offset0:16 offset1:32
	v_add_co_u32_e64 v178, s[0:1], s77, v174
	v_sub_f32_e32 v13, v13, v176
	s_nop 0
	v_addc_co_u32_e64 v179, s[0:1], 0, v175, s[0:1]
	global_store_dwordx4 v[178:179], v[40:43], off nt
	global_store_dwordx4 v[178:179], v[44:47], off offset:16 nt
	v_add_co_u32_e64 v194, s[0:1], s78, v174
	s_waitcnt lgkmcnt(0)
	v_sub_f32_e32 v41, v65, v50
	v_sub_f32_e32 v40, v64, v50
	v_sub_f32_e32 v43, v67, v50
	v_sub_f32_e32 v42, v66, v50
	v_sub_f32_e32 v45, v69, v50
	v_sub_f32_e32 v44, v68, v50
	v_sub_f32_e32 v47, v71, v50
	v_sub_f32_e32 v46, v70, v50
	v_pk_mul_f32 v[42:43], v[50:51], v[42:43] op_sel:[1,0]
	v_pk_mul_f32 v[40:41], v[50:51], v[40:41] op_sel:[1,0]
	v_pk_mul_f32 v[46:47], v[50:51], v[46:47] op_sel:[1,0]
	v_pk_mul_f32 v[44:45], v[50:51], v[44:45] op_sel:[1,0]
	ds_read2_b64 v[50:53], v193 offset0:32 offset1:48
	v_pk_fma_f32 v[40:41], v[152:153], v[40:41], v[156:157]
	v_pk_fma_f32 v[42:43], v[154:155], v[42:43], v[158:159]
	v_pk_fma_f32 v[44:45], v[144:145], v[44:45], v[148:149]
	v_pk_fma_f32 v[46:47], v[146:147], v[46:47], v[150:151]
	v_cndmask_b32_e32 v43, v191, v43, vcc
	v_cndmask_b32_e32 v42, v191, v42, vcc
	v_cndmask_b32_e32 v41, v191, v41, vcc
	v_cndmask_b32_e32 v40, v191, v40, vcc
	v_cndmask_b32_e32 v47, v191, v47, vcc
	v_cndmask_b32_e32 v46, v191, v46, vcc
	v_cndmask_b32_e32 v45, v191, v45, vcc
	v_cndmask_b32_e32 v44, v191, v44, vcc
	v_addc_co_u32_e64 v195, s[0:1], 0, v175, s[0:1]
	global_store_dwordx4 v[194:195], v[40:43], off nt
	global_store_dwordx4 v[194:195], v[44:47], off offset:16 nt
	v_sub_f32_e32 v12, v12, v176
	s_waitcnt lgkmcnt(0)
	v_sub_f32_e32 v41, v81, v52
	v_sub_f32_e32 v40, v80, v52
	v_sub_f32_e32 v43, v83, v52
	v_sub_f32_e32 v42, v82, v52
	v_sub_f32_e32 v45, v85, v52
	v_sub_f32_e32 v44, v84, v52
	v_sub_f32_e32 v47, v87, v52
	v_sub_f32_e32 v46, v86, v52
	v_pk_mul_f32 v[42:43], v[52:53], v[42:43] op_sel:[1,0]
	v_pk_mul_f32 v[40:41], v[52:53], v[40:41] op_sel:[1,0]
	v_pk_mul_f32 v[46:47], v[52:53], v[46:47] op_sel:[1,0]
	v_pk_mul_f32 v[44:45], v[52:53], v[44:45] op_sel:[1,0]
	ds_read2_b64 v[52:55], v193 offset0:48 offset1:128
	v_pk_fma_f32 v[40:41], v[152:153], v[40:41], v[156:157]
	v_pk_fma_f32 v[42:43], v[154:155], v[42:43], v[158:159]
	v_add_co_u32_e64 v80, s[0:1], s79, v174
	v_pk_fma_f32 v[44:45], v[144:145], v[44:45], v[148:149]
	v_pk_fma_f32 v[46:47], v[146:147], v[46:47], v[150:151]
	v_cndmask_b32_e32 v43, v191, v43, vcc
	v_cndmask_b32_e32 v42, v191, v42, vcc
	v_cndmask_b32_e32 v41, v191, v41, vcc
	v_cndmask_b32_e32 v40, v191, v40, vcc
	v_addc_co_u32_e64 v81, s[0:1], 0, v175, s[0:1]
	v_cndmask_b32_e32 v47, v191, v47, vcc
	v_cndmask_b32_e32 v46, v191, v46, vcc
	v_cndmask_b32_e32 v45, v191, v45, vcc
	v_cndmask_b32_e32 v44, v191, v44, vcc
	global_store_dwordx4 v[80:81], v[40:43], off nt
	global_store_dwordx4 v[80:81], v[44:47], off offset:16 nt
	ds_read2_b64 v[64:67], v193 offset0:128 offset1:144
	s_waitcnt lgkmcnt(1)
	v_sub_f32_e32 v41, v105, v54
	v_sub_f32_e32 v40, v104, v54
	v_sub_f32_e32 v43, v107, v54
	v_sub_f32_e32 v42, v106, v54
	v_sub_f32_e32 v45, v109, v54
	v_sub_f32_e32 v44, v108, v54
	v_sub_f32_e32 v47, v111, v54
	v_sub_f32_e32 v46, v110, v54
	v_pk_mul_f32 v[42:43], v[54:55], v[42:43] op_sel:[1,0]
	v_pk_mul_f32 v[40:41], v[54:55], v[40:41] op_sel:[1,0]
	v_pk_mul_f32 v[46:47], v[54:55], v[46:47] op_sel:[1,0]
	v_pk_mul_f32 v[44:45], v[54:55], v[44:45] op_sel:[1,0]
	v_pk_fma_f32 v[40:41], v[152:153], v[40:41], v[156:157]
	v_pk_fma_f32 v[42:43], v[154:155], v[42:43], v[158:159]
	v_pk_fma_f32 v[44:45], v[144:145], v[44:45], v[148:149]
	v_pk_fma_f32 v[46:47], v[146:147], v[46:47], v[150:151]
	v_add_co_u32_e64 v54, s[0:1], s80, v174
	v_cndmask_b32_e32 v43, v191, v43, vcc
	v_cndmask_b32_e32 v42, v191, v42, vcc
	v_cndmask_b32_e32 v41, v191, v41, vcc
	v_cndmask_b32_e32 v40, v191, v40, vcc
	v_cndmask_b32_e32 v47, v191, v47, vcc
	v_cndmask_b32_e32 v46, v191, v46, vcc
	v_cndmask_b32_e32 v45, v191, v45, vcc
	v_cndmask_b32_e32 v44, v191, v44, vcc
	v_addc_co_u32_e64 v55, s[0:1], 0, v175, s[0:1]
	global_store_dwordx4 v[54:55], v[40:43], off nt
	global_store_dwordx4 v[54:55], v[44:47], off offset:16 nt
	v_add_co_u32_e64 v82, s[0:1], s84, v174
	s_waitcnt lgkmcnt(0)
	v_sub_f32_e32 v41, v121, v66
	v_sub_f32_e32 v40, v120, v66
	v_sub_f32_e32 v43, v123, v66
	v_sub_f32_e32 v42, v122, v66
	v_sub_f32_e32 v45, v125, v66
	v_sub_f32_e32 v44, v124, v66
	v_sub_f32_e32 v47, v127, v66
	v_sub_f32_e32 v46, v126, v66
	v_pk_mul_f32 v[42:43], v[66:67], v[42:43] op_sel:[1,0]
	v_pk_mul_f32 v[40:41], v[66:67], v[40:41] op_sel:[1,0]
	v_pk_mul_f32 v[46:47], v[66:67], v[46:47] op_sel:[1,0]
	v_pk_mul_f32 v[44:45], v[66:67], v[44:45] op_sel:[1,0]
	ds_read2_b64 v[66:69], v193 offset0:144 offset1:160
	v_pk_fma_f32 v[40:41], v[152:153], v[40:41], v[156:157]
	v_pk_fma_f32 v[42:43], v[154:155], v[42:43], v[158:159]
	v_pk_fma_f32 v[44:45], v[144:145], v[44:45], v[148:149]
	v_pk_fma_f32 v[46:47], v[146:147], v[46:47], v[150:151]
	v_cndmask_b32_e32 v43, v191, v43, vcc
	v_cndmask_b32_e32 v42, v191, v42, vcc
	v_cndmask_b32_e32 v41, v191, v41, vcc
	v_cndmask_b32_e32 v40, v191, v40, vcc
	v_cndmask_b32_e32 v47, v191, v47, vcc
	v_cndmask_b32_e32 v46, v191, v46, vcc
	v_cndmask_b32_e32 v45, v191, v45, vcc
	v_cndmask_b32_e32 v44, v191, v44, vcc
	v_addc_co_u32_e64 v83, s[0:1], 0, v175, s[0:1]
	global_store_dwordx4 v[82:83], v[40:43], off nt
	global_store_dwordx4 v[82:83], v[44:47], off offset:16 nt
	v_add_co_u32_e64 v84, s[0:1], s85, v174
	s_waitcnt lgkmcnt(0)
	v_sub_f32_e32 v41, v129, v68
	v_sub_f32_e32 v40, v128, v68
	v_sub_f32_e32 v43, v131, v68
	v_sub_f32_e32 v42, v130, v68
	v_sub_f32_e32 v45, v133, v68
	v_sub_f32_e32 v44, v132, v68
	v_sub_f32_e32 v47, v135, v68
	v_sub_f32_e32 v46, v134, v68
	v_pk_mul_f32 v[42:43], v[68:69], v[42:43] op_sel:[1,0]
	v_pk_mul_f32 v[40:41], v[68:69], v[40:41] op_sel:[1,0]
	v_pk_mul_f32 v[46:47], v[68:69], v[46:47] op_sel:[1,0]
	v_pk_mul_f32 v[44:45], v[68:69], v[44:45] op_sel:[1,0]
	ds_read2_b64 v[68:71], v193 offset0:160 offset1:176
	v_pk_fma_f32 v[40:41], v[152:153], v[40:41], v[156:157]
	v_pk_fma_f32 v[42:43], v[154:155], v[42:43], v[158:159]
	v_pk_fma_f32 v[44:45], v[144:145], v[44:45], v[148:149]
	v_pk_fma_f32 v[46:47], v[146:147], v[46:47], v[150:151]
	v_cndmask_b32_e32 v43, v191, v43, vcc
	v_cndmask_b32_e32 v42, v191, v42, vcc
	v_cndmask_b32_e32 v41, v191, v41, vcc
	v_cndmask_b32_e32 v40, v191, v40, vcc
	v_addc_co_u32_e64 v85, s[0:1], 0, v175, s[0:1]
	v_cndmask_b32_e32 v47, v191, v47, vcc
	v_cndmask_b32_e32 v46, v191, v46, vcc
	v_cndmask_b32_e32 v45, v191, v45, vcc
	v_cndmask_b32_e32 v44, v191, v44, vcc
	global_store_dwordx4 v[84:85], v[40:43], off nt
	global_store_dwordx4 v[84:85], v[44:47], off offset:16 nt
	v_sub_f32_e32 v15, v15, v176
	s_waitcnt lgkmcnt(0)
	v_sub_f32_e32 v41, v137, v70
	v_sub_f32_e32 v40, v136, v70
	v_sub_f32_e32 v43, v139, v70
	v_sub_f32_e32 v42, v138, v70
	v_pk_mul_f32 v[42:43], v[70:71], v[42:43] op_sel:[1,0]
	v_pk_mul_f32 v[40:41], v[70:71], v[40:41] op_sel:[1,0]
	v_sub_f32_e32 v45, v141, v70
	v_sub_f32_e32 v44, v140, v70
	v_sub_f32_e32 v47, v143, v70
	v_sub_f32_e32 v46, v142, v70
	v_sub_f32_e32 v14, v14, v176
	v_pk_fma_f32 v[40:41], v[152:153], v[40:41], v[156:157]
	v_pk_fma_f32 v[42:43], v[154:155], v[42:43], v[158:159]
	v_pk_mul_f32 v[46:47], v[70:71], v[46:47] op_sel:[1,0]
	v_pk_mul_f32 v[44:45], v[70:71], v[44:45] op_sel:[1,0]
	v_add_co_u32_e64 v70, s[0:1], s86, v174
	v_pk_mul_f32 v[14:15], v[176:177], v[14:15] op_sel:[1,0]
	v_pk_mul_f32 v[12:13], v[176:177], v[12:13] op_sel:[1,0]
	v_sub_f32_e32 v1, v1, v176
	v_sub_f32_e32 v0, v0, v176
	v_sub_f32_e32 v3, v3, v176
	v_sub_f32_e32 v2, v2, v176
	v_pk_fma_f32 v[44:45], v[144:145], v[44:45], v[148:149]
	v_pk_fma_f32 v[46:47], v[146:147], v[46:47], v[150:151]
	v_cndmask_b32_e32 v43, v191, v43, vcc
	v_cndmask_b32_e32 v42, v191, v42, vcc
	v_cndmask_b32_e32 v41, v191, v41, vcc
	v_cndmask_b32_e32 v40, v191, v40, vcc
	v_addc_co_u32_e64 v71, s[0:1], 0, v175, s[0:1]
	s_waitcnt vmcnt(14)
	v_pk_fma_f32 v[12:13], v[112:113], v[12:13], v[116:117]
	v_pk_fma_f32 v[14:15], v[114:115], v[14:15], v[118:119]
	v_pk_mul_f32 v[2:3], v[176:177], v[2:3] op_sel:[1,0]
	v_pk_mul_f32 v[0:1], v[176:177], v[0:1] op_sel:[1,0]
	v_cndmask_b32_e32 v47, v191, v47, vcc
	v_cndmask_b32_e32 v46, v191, v46, vcc
	v_cndmask_b32_e32 v45, v191, v45, vcc
	v_cndmask_b32_e32 v44, v191, v44, vcc
	global_store_dwordx4 v[70:71], v[40:43], off nt
	global_store_dwordx4 v[70:71], v[44:47], off offset:16 nt
	s_mov_b64 s[0:1], -1
	v_pk_fma_f32 v[40:41], v[96:97], v[0:1], v[100:101]
	v_pk_fma_f32 v[42:43], v[98:99], v[2:3], v[102:103]
	v_cndmask_b32_e32 v3, v191, v15, vcc
	v_cndmask_b32_e32 v2, v191, v14, vcc
	v_cndmask_b32_e32 v1, v191, v13, vcc
	v_cndmask_b32_e32 v0, v191, v12, vcc
	v_cndmask_b32_e32 v15, v191, v43, vcc
	v_cndmask_b32_e32 v14, v191, v42, vcc
	v_cndmask_b32_e32 v13, v191, v41, vcc
	v_cndmask_b32_e32 v12, v191, v40, vcc
	global_store_dwordx4 v[174:175], v[0:3], off offset:512 nt
	global_store_dwordx4 v[174:175], v[12:15], off offset:528 nt
	s_nop 0
	v_sub_f32_e32 v1, v5, v48
	v_sub_f32_e32 v0, v4, v48
	v_sub_f32_e32 v3, v7, v48
	v_sub_f32_e32 v2, v6, v48
	v_pk_mul_f32 v[2:3], v[48:49], v[2:3] op_sel:[1,0]
	v_pk_mul_f32 v[0:1], v[48:49], v[0:1] op_sel:[1,0]
	v_sub_f32_e32 v5, v9, v48
	v_sub_f32_e32 v4, v8, v48
	v_sub_f32_e32 v7, v11, v48
	v_sub_f32_e32 v6, v10, v48
	v_pk_fma_f32 v[0:1], v[112:113], v[0:1], v[116:117]
	v_pk_fma_f32 v[2:3], v[114:115], v[2:3], v[118:119]
	v_pk_mul_f32 v[6:7], v[48:49], v[6:7] op_sel:[1,0]
	v_pk_mul_f32 v[4:5], v[48:49], v[4:5] op_sel:[1,0]
	v_pk_fma_f32 v[6:7], v[98:99], v[6:7], v[102:103]
	v_pk_fma_f32 v[4:5], v[96:97], v[4:5], v[100:101]
	v_cndmask_b32_e32 v3, v191, v3, vcc
	v_cndmask_b32_e32 v2, v191, v2, vcc
	v_cndmask_b32_e32 v1, v191, v1, vcc
	v_cndmask_b32_e32 v0, v191, v0, vcc
	v_cndmask_b32_e32 v7, v191, v7, vcc
	v_cndmask_b32_e32 v6, v191, v6, vcc
	v_cndmask_b32_e32 v5, v191, v5, vcc
	v_cndmask_b32_e32 v4, v191, v4, vcc
	global_store_dwordx4 v[178:179], v[0:3], off offset:512 nt
	global_store_dwordx4 v[178:179], v[4:7], off offset:528 nt
	s_nop 0
	v_sub_f32_e32 v1, v17, v50
	v_sub_f32_e32 v0, v16, v50
	v_sub_f32_e32 v3, v19, v50
	v_sub_f32_e32 v2, v18, v50
	v_pk_mul_f32 v[2:3], v[50:51], v[2:3] op_sel:[1,0]
	v_pk_mul_f32 v[0:1], v[50:51], v[0:1] op_sel:[1,0]
	v_sub_f32_e32 v5, v21, v50
	v_sub_f32_e32 v4, v20, v50
	v_sub_f32_e32 v7, v23, v50
	v_sub_f32_e32 v6, v22, v50
	v_pk_fma_f32 v[0:1], v[112:113], v[0:1], v[116:117]
	v_pk_fma_f32 v[2:3], v[114:115], v[2:3], v[118:119]
	v_pk_mul_f32 v[6:7], v[50:51], v[6:7] op_sel:[1,0]
	v_pk_mul_f32 v[4:5], v[50:51], v[4:5] op_sel:[1,0]
	v_pk_fma_f32 v[6:7], v[98:99], v[6:7], v[102:103]
	v_pk_fma_f32 v[4:5], v[96:97], v[4:5], v[100:101]
	v_cndmask_b32_e32 v3, v191, v3, vcc
	v_cndmask_b32_e32 v2, v191, v2, vcc
	v_cndmask_b32_e32 v1, v191, v1, vcc
	v_cndmask_b32_e32 v0, v191, v0, vcc
	v_cndmask_b32_e32 v7, v191, v7, vcc
	v_cndmask_b32_e32 v6, v191, v6, vcc
	v_cndmask_b32_e32 v5, v191, v5, vcc
	v_cndmask_b32_e32 v4, v191, v4, vcc
	global_store_dwordx4 v[194:195], v[0:3], off offset:512 nt
	global_store_dwordx4 v[194:195], v[4:7], off offset:528 nt
	s_nop 0
	v_sub_f32_e32 v1, v25, v52
	v_sub_f32_e32 v0, v24, v52
	v_sub_f32_e32 v3, v27, v52
	v_sub_f32_e32 v2, v26, v52
	v_pk_mul_f32 v[2:3], v[52:53], v[2:3] op_sel:[1,0]
	v_pk_mul_f32 v[0:1], v[52:53], v[0:1] op_sel:[1,0]
	v_sub_f32_e32 v5, v29, v52
	v_sub_f32_e32 v4, v28, v52
	v_sub_f32_e32 v7, v31, v52
	v_sub_f32_e32 v6, v30, v52
	v_pk_fma_f32 v[0:1], v[112:113], v[0:1], v[116:117]
	v_pk_fma_f32 v[2:3], v[114:115], v[2:3], v[118:119]
	v_pk_mul_f32 v[6:7], v[52:53], v[6:7] op_sel:[1,0]
	v_pk_mul_f32 v[4:5], v[52:53], v[4:5] op_sel:[1,0]
	v_pk_fma_f32 v[6:7], v[98:99], v[6:7], v[102:103]
	v_pk_fma_f32 v[4:5], v[96:97], v[4:5], v[100:101]
	v_cndmask_b32_e32 v3, v191, v3, vcc
	v_cndmask_b32_e32 v2, v191, v2, vcc
	v_cndmask_b32_e32 v1, v191, v1, vcc
	v_cndmask_b32_e32 v0, v191, v0, vcc
	v_cndmask_b32_e32 v7, v191, v7, vcc
	v_cndmask_b32_e32 v6, v191, v6, vcc
	v_cndmask_b32_e32 v5, v191, v5, vcc
	v_cndmask_b32_e32 v4, v191, v4, vcc
	global_store_dwordx4 v[80:81], v[0:3], off offset:512 nt
	global_store_dwordx4 v[80:81], v[4:7], off offset:528 nt
	s_nop 0
	v_sub_f32_e32 v1, v33, v64
	v_sub_f32_e32 v0, v32, v64
	v_sub_f32_e32 v3, v35, v64
	v_sub_f32_e32 v2, v34, v64
	v_pk_mul_f32 v[2:3], v[64:65], v[2:3] op_sel:[1,0]
	v_pk_mul_f32 v[0:1], v[64:65], v[0:1] op_sel:[1,0]
	v_sub_f32_e32 v5, v37, v64
	v_sub_f32_e32 v4, v36, v64
	v_sub_f32_e32 v7, v39, v64
	v_sub_f32_e32 v6, v38, v64
	v_pk_fma_f32 v[0:1], v[112:113], v[0:1], v[116:117]
	v_pk_fma_f32 v[2:3], v[114:115], v[2:3], v[118:119]
	v_pk_mul_f32 v[6:7], v[64:65], v[6:7] op_sel:[1,0]
	v_pk_mul_f32 v[4:5], v[64:65], v[4:5] op_sel:[1,0]
	v_pk_fma_f32 v[6:7], v[98:99], v[6:7], v[102:103]
	v_pk_fma_f32 v[4:5], v[96:97], v[4:5], v[100:101]
	v_cndmask_b32_e32 v3, v191, v3, vcc
	v_cndmask_b32_e32 v2, v191, v2, vcc
	v_cndmask_b32_e32 v1, v191, v1, vcc
	v_cndmask_b32_e32 v0, v191, v0, vcc
	v_cndmask_b32_e32 v7, v191, v7, vcc
	v_cndmask_b32_e32 v6, v191, v6, vcc
	v_cndmask_b32_e32 v5, v191, v5, vcc
	v_cndmask_b32_e32 v4, v191, v4, vcc
	global_store_dwordx4 v[54:55], v[0:3], off offset:512 nt
	global_store_dwordx4 v[54:55], v[4:7], off offset:528 nt
	s_nop 0
	v_sub_f32_e32 v1, v57, v66
	v_sub_f32_e32 v0, v56, v66
	v_sub_f32_e32 v3, v59, v66
	v_sub_f32_e32 v2, v58, v66
	v_pk_mul_f32 v[2:3], v[66:67], v[2:3] op_sel:[1,0]
	v_pk_mul_f32 v[0:1], v[66:67], v[0:1] op_sel:[1,0]
	v_sub_f32_e32 v5, v61, v66
	v_sub_f32_e32 v4, v60, v66
	v_sub_f32_e32 v7, v63, v66
	v_sub_f32_e32 v6, v62, v66
	v_pk_fma_f32 v[0:1], v[112:113], v[0:1], v[116:117]
	v_pk_fma_f32 v[2:3], v[114:115], v[2:3], v[118:119]
	v_pk_mul_f32 v[6:7], v[66:67], v[6:7] op_sel:[1,0]
	v_pk_mul_f32 v[4:5], v[66:67], v[4:5] op_sel:[1,0]
	v_pk_fma_f32 v[6:7], v[98:99], v[6:7], v[102:103]
	v_pk_fma_f32 v[4:5], v[96:97], v[4:5], v[100:101]
	v_cndmask_b32_e32 v3, v191, v3, vcc
	v_cndmask_b32_e32 v2, v191, v2, vcc
	v_cndmask_b32_e32 v1, v191, v1, vcc
	v_cndmask_b32_e32 v0, v191, v0, vcc
	v_cndmask_b32_e32 v7, v191, v7, vcc
	v_cndmask_b32_e32 v6, v191, v6, vcc
	v_cndmask_b32_e32 v5, v191, v5, vcc
	v_cndmask_b32_e32 v4, v191, v4, vcc
	global_store_dwordx4 v[82:83], v[0:3], off offset:512 nt
	global_store_dwordx4 v[82:83], v[4:7], off offset:528 nt
	s_nop 0
	v_sub_f32_e32 v1, v73, v68
	v_sub_f32_e32 v0, v72, v68
	v_sub_f32_e32 v3, v75, v68
	v_sub_f32_e32 v2, v74, v68
	v_pk_mul_f32 v[2:3], v[68:69], v[2:3] op_sel:[1,0]
	v_pk_mul_f32 v[0:1], v[68:69], v[0:1] op_sel:[1,0]
	v_sub_f32_e32 v5, v77, v68
	v_sub_f32_e32 v4, v76, v68
	v_sub_f32_e32 v7, v79, v68
	v_sub_f32_e32 v6, v78, v68
	v_pk_fma_f32 v[0:1], v[112:113], v[0:1], v[116:117]
	v_pk_fma_f32 v[2:3], v[114:115], v[2:3], v[118:119]
	v_pk_mul_f32 v[6:7], v[68:69], v[6:7] op_sel:[1,0]
	v_pk_mul_f32 v[4:5], v[68:69], v[4:5] op_sel:[1,0]
	v_pk_fma_f32 v[6:7], v[98:99], v[6:7], v[102:103]
	v_pk_fma_f32 v[4:5], v[96:97], v[4:5], v[100:101]
	v_cndmask_b32_e32 v3, v191, v3, vcc
	v_cndmask_b32_e32 v2, v191, v2, vcc
	v_cndmask_b32_e32 v1, v191, v1, vcc
	v_cndmask_b32_e32 v0, v191, v0, vcc
	v_cndmask_b32_e32 v7, v191, v7, vcc
	v_cndmask_b32_e32 v6, v191, v6, vcc
	v_cndmask_b32_e32 v5, v191, v5, vcc
	v_cndmask_b32_e32 v4, v191, v4, vcc
	global_store_dwordx4 v[84:85], v[0:3], off offset:512 nt
	global_store_dwordx4 v[84:85], v[4:7], off offset:528 nt
	s_nop 0
	v_sub_f32_e32 v1, v93, v180
	v_sub_f32_e32 v0, v92, v180
	v_sub_f32_e32 v3, v95, v180
	v_sub_f32_e32 v2, v94, v180
	v_pk_mul_f32 v[2:3], v[180:181], v[2:3] op_sel:[1,0]
	v_pk_mul_f32 v[0:1], v[180:181], v[0:1] op_sel:[1,0]
	v_sub_f32_e32 v5, v89, v180
	v_sub_f32_e32 v4, v88, v180
	v_sub_f32_e32 v7, v91, v180
	v_sub_f32_e32 v6, v90, v180
	v_pk_fma_f32 v[0:1], v[112:113], v[0:1], v[116:117]
	v_pk_fma_f32 v[2:3], v[114:115], v[2:3], v[118:119]
	v_pk_mul_f32 v[6:7], v[180:181], v[6:7] op_sel:[1,0]
	v_pk_mul_f32 v[4:5], v[180:181], v[4:5] op_sel:[1,0]
	v_pk_fma_f32 v[6:7], v[98:99], v[6:7], v[102:103]
	v_pk_fma_f32 v[4:5], v[96:97], v[4:5], v[100:101]
	v_cndmask_b32_e32 v3, v191, v3, vcc
	v_cndmask_b32_e32 v2, v191, v2, vcc
	v_cndmask_b32_e32 v1, v191, v1, vcc
	v_cndmask_b32_e32 v0, v191, v0, vcc
	v_cndmask_b32_e32 v7, v191, v7, vcc
	v_cndmask_b32_e32 v6, v191, v6, vcc
	v_cndmask_b32_e32 v5, v191, v5, vcc
	v_cndmask_b32_e32 v4, v191, v4, vcc
	global_store_dwordx4 v[70:71], v[0:3], off offset:512 nt
	global_store_dwordx4 v[70:71], v[4:7], off offset:528 nt
	s_cbranch_scc1 .LBB0_2960
	s_andn2_b64 vcc, exec, s[12:13]
	s_cbranch_vccnz .LBB0_2959
	s_barrier
	s_branch .LBB0_2959
